# K-loops: LDS-DMA refills of each phase issued before the fixed-address ds_read_b128 block instead of after it (requests leave earlier; the loop looked DMA-latency bound); no wait counts changed
# baseline (speedup 1.0000x reference)
; #define PG8_STAGE(bufoff, gbase, voff) do { _Pragma("unroll") for (int _i = 0; _i < 2; ++_i) \
;         __builtin_amdgcn_global_load_lds((const unsigned*)((const char*)(gbase) + (voff)[_i]), (LAS unsigned*)(lds + (bufoff) + ldsw + _i * 8192), 16, 0, 0); } while (0)
; #define PG8_LDA(dst, b, h) do { _Pragma("unroll") for (int m = 0; m < 4; ++m) _Pragma("unroll") for (int k = 0; k < 2; ++k) dst[m][k] = *(const LAS bf16x8*)(lds + PG8_SA(b, h) + aoff + m * 2048 + k * 1024); } while (0)
; #define PG8_LDB(dst, b, h) do { _Pragma("unroll") for (int n = 0; n < 2; ++n) _Pragma("unroll") for (int k = 0; k < 2; ++k) dst[n][k] = *(const LAS bf16x8*)(lds + PG8_SB(b, h) + boff + n * 2048 + k * 1024); } while (0)
; #define PG8_MMA(ai, bj, At, Bt) do { __builtin_amdgcn_s_setprio(1); _Pragma("unroll") for (int m = 0; m < 4; ++m) _Pragma("unroll") for (int n = 0; n < 2; ++n) _Pragma("unroll") for (int k = 0; k < 2; ++k) \
;         acc[ai][bj][m][n] = __builtin_amdgcn_mfma_f32_16x16x32_bf16(Bt[n][k], At[m][k], acc[ai][bj][m][n], 0, 0, 0); __builtin_amdgcn_s_setprio(0); } while (0)
; #define PG8_WAIT_V(n) asm volatile("s_waitcnt vmcnt(" #n ")" ::: "memory")
; #define PG8_WAIT_L(n) asm volatile("s_waitcnt lgkmcnt(" #n ")" ::: "memory")
; #define PG8_BAR __builtin_amdgcn_s_barrier()
; #define PG8_SCHED __builtin_amdgcn_sched_barrier(0)
; template <class Epi>
; __device__ __forceinline__ void gemm_phase(LAS unsigned char* lds, const int tid, const Gemm g, const StaticOrder& S, const Epi& E) {
;     ...
;             const bool last = (t == nt - 2);
;             const char* a1 = cA + (size_t)(t + 1) * kstep;
;             const char* a2 = last ? nA : cA + (size_t)(t + 2) * kstep; const char* b2 = last ? nB : cB + (size_t)(t + 2) * kstep;
;             const char* a3 = a2 + kstep; const char* b3 = b2 + kstep;
;             PG8_LDB(B0, 0, 0); PG8_LDB(B1, 0, 1); PG8_SCHED; PG8_LDA(At, 0, 0); PG8_STAGE(PG8_SA(1, 1), a1 + hstepA, voffA);
;             PG8_WAIT_V(8); PG8_WAIT_L(0); PG8_BAR; PG8_MMA(0, 0, At, B0); PG8_MMA(0, 1, At, B1); PG8_BAR; PG8_SCHED;
;             PG8_LDA(At, 0, 1); PG8_STAGE(PG8_SB(0, 0), b2, voffB); PG8_STAGE(PG8_SB(0, 1), b2 + hstepB, voffB); PG8_STAGE(PG8_SA(0, 0), a2, voffA);
;             PG8_WAIT_V(8); PG8_WAIT_L(0); PG8_BAR; PG8_MMA(1, 0, At, B0); PG8_MMA(1, 1, At, B1); PG8_BAR; PG8_SCHED;
.LBB0_414:
	s_add_u32 s10, s68, 0xfffc0080
	s_addc_u32 s11, s69, -1
	s_add_i32 s17, 0, 0x10000
	s_cmp_eq_u32 s16, 12
	s_cselect_b32 s73, s7, s11
	s_cselect_b32 s72, s67, s10
	s_cselect_b32 s71, s5, s76
	s_cselect_b32 s70, vcc_lo, vcc_hi
	s_add_i32 s0, 0, 0x14000
	v_add_u32_e32 v70, s17, v202
	v_add_u32_e32 v160, s0, v202
	ds_read_b128 v[50:53], v70
	ds_read_b128 v[54:57], v70 offset:1024
	ds_read_b128 v[66:69], v70 offset:2048
	ds_read_b128 v[70:73], v70 offset:3072
	ds_read_b128 v[156:159], v160
	ds_read_b128 v[170:173], v160 offset:1024
	ds_read_b128 v[174:177], v160 offset:2048
	ds_read_b128 v[178:181], v160 offset:3072
	v_lshl_add_u64 v[160:161], s[68:69], 0, v[152:153]
	s_add_i32 m0, s83, 0xc000
	s_nop 0
	global_load_lds_dwordx4 v[160:161], off
	v_lshl_add_u64 v[160:161], s[68:69], 0, v[154:155]
	s_add_i32 m0, s83, 0xe000
	s_nop 0
	global_load_lds_dwordx4 v[160:161], off
	ds_read_b128 v[216:219], v215
	ds_read_b128 v[220:223], v215 offset:1024
	ds_read_b128 v[224:227], v215 offset:2048
	ds_read_b128 v[228:231], v215 offset:3072
	ds_read_b128 v[232:235], v215 offset:4096
	ds_read_b128 v[236:239], v215 offset:5120
	ds_read_b128 v[240:243], v215 offset:6144
	ds_read_b128 v[244:247], v215 offset:7168
	s_waitcnt vmcnt(8)
	s_waitcnt lgkmcnt(0)
	s_barrier
	s_setprio 1
	s_waitcnt lgkmcnt(0)
	v_mfma_f32_16x16x32_bf16 v[142:145], v[50:53], v[216:219], v[142:145]
	v_mfma_f32_16x16x32_bf16 v[138:141], v[66:69], v[216:219], v[138:141]
	v_mfma_f32_16x16x32_bf16 v[126:129], v[50:53], v[224:227], v[126:129]
	v_mfma_f32_16x16x32_bf16 v[122:125], v[66:69], v[224:227], v[122:125]
	v_mfma_f32_16x16x32_bf16 v[110:113], v[50:53], v[232:235], v[110:113]
	v_mfma_f32_16x16x32_bf16 v[106:109], v[66:69], v[232:235], v[106:109]
	v_mfma_f32_16x16x32_bf16 v[94:97], v[50:53], v[240:243], v[94:97]
	v_mfma_f32_16x16x32_bf16 v[90:93], v[66:69], v[240:243], v[90:93]
	v_mfma_f32_16x16x32_bf16 v[142:145], v[54:57], v[220:223], v[142:145]
	v_mfma_f32_16x16x32_bf16 v[138:141], v[70:73], v[220:223], v[138:141]
	v_mfma_f32_16x16x32_bf16 v[126:129], v[54:57], v[228:231], v[126:129]
	v_mfma_f32_16x16x32_bf16 v[122:125], v[70:73], v[228:231], v[122:125]
	v_mfma_f32_16x16x32_bf16 v[110:113], v[54:57], v[236:239], v[110:113]
	v_mfma_f32_16x16x32_bf16 v[106:109], v[70:73], v[236:239], v[106:109]
	v_mfma_f32_16x16x32_bf16 v[94:97], v[54:57], v[244:247], v[94:97]
	v_mfma_f32_16x16x32_bf16 v[90:93], v[70:73], v[244:247], v[90:93]
	s_setprio 0
	s_setprio 1
	v_mfma_f32_16x16x32_bf16 v[134:137], v[156:159], v[216:219], v[134:137]
	v_mfma_f32_16x16x32_bf16 v[130:133], v[174:177], v[216:219], v[130:133]
	v_mfma_f32_16x16x32_bf16 v[118:121], v[156:159], v[224:227], v[118:121]
	v_mfma_f32_16x16x32_bf16 v[114:117], v[174:177], v[224:227], v[114:117]
	v_mfma_f32_16x16x32_bf16 v[102:105], v[156:159], v[232:235], v[102:105]
	v_mfma_f32_16x16x32_bf16 v[98:101], v[174:177], v[232:235], v[98:101]
	v_mfma_f32_16x16x32_bf16 v[86:89], v[156:159], v[240:243], v[86:89]
	v_mfma_f32_16x16x32_bf16 v[82:85], v[174:177], v[240:243], v[82:85]
	v_mfma_f32_16x16x32_bf16 v[134:137], v[170:173], v[220:223], v[134:137]
	v_mfma_f32_16x16x32_bf16 v[130:133], v[178:181], v[220:223], v[130:133]
	v_mfma_f32_16x16x32_bf16 v[118:121], v[170:173], v[228:231], v[118:121]
	v_mfma_f32_16x16x32_bf16 v[114:117], v[178:181], v[228:231], v[114:117]
	v_mfma_f32_16x16x32_bf16 v[102:105], v[170:173], v[236:239], v[102:105]
	v_mfma_f32_16x16x32_bf16 v[98:101], v[178:181], v[236:239], v[98:101]
	v_mfma_f32_16x16x32_bf16 v[86:89], v[170:173], v[244:247], v[86:89]
	v_mfma_f32_16x16x32_bf16 v[82:85], v[178:181], v[244:247], v[82:85]
	s_setprio 0
	s_barrier
	s_add_i32 s1, s17, s82
	v_lshl_add_u64 v[160:161], s[70:71], 0, v[0:1]
	s_mov_b32 m0, s1
	s_nop 0
	global_load_lds_dwordx4 v[160:161], off
	s_add_i32 m0, s1, 0x2000
	s_add_u32 s10, s70, 0x40000
	v_lshl_add_u64 v[182:183], s[70:71], 0, v[146:147]
	s_addc_u32 s11, s71, 0
	s_add_i32 s0, s0, s82
	global_load_lds_dwordx4 v[182:183], off
	v_lshl_add_u64 v[162:163], s[10:11], 0, v[0:1]
	s_mov_b32 m0, s0
	v_lshl_add_u64 v[164:165], s[72:73], 0, v[150:151]
	global_load_lds_dwordx4 v[162:163], off
	v_lshl_add_u64 v[162:163], s[10:11], 0, v[146:147]
	s_add_i32 m0, s0, 0x2000
	s_nop 0
	global_load_lds_dwordx4 v[162:163], off
	v_lshl_add_u64 v[162:163], s[72:73], 0, v[148:149]
	s_mov_b32 m0, s83
	s_nop 0
	global_load_lds_dwordx4 v[162:163], off
	s_mov_b32 m0, s88
	s_nop 0
	global_load_lds_dwordx4 v[164:165], off
	ds_read_b128 v[216:219], v215 offset:16384
	ds_read_b128 v[220:223], v215 offset:17408
	ds_read_b128 v[224:227], v215 offset:18432
	ds_read_b128 v[228:231], v215 offset:19456
	ds_read_b128 v[232:235], v215 offset:20480
	ds_read_b128 v[236:239], v215 offset:21504
	ds_read_b128 v[240:243], v215 offset:22528
	ds_read_b128 v[244:247], v215 offset:23552
	s_waitcnt vmcnt(8)
	s_waitcnt lgkmcnt(0)
	s_barrier
; #define PG8_STAGE(bufoff, gbase, voff) do { _Pragma("unroll") for (int _i = 0; _i < 2; ++_i) \
;         __builtin_amdgcn_global_load_lds((const unsigned*)((const char*)(gbase) + (voff)[_i]), (LAS unsigned*)(lds + (bufoff) + ldsw + _i * 8192), 16, 0, 0); } while (0)
; #define PG8_LDA(dst, b, h) do { _Pragma("unroll") for (int m = 0; m < 4; ++m) _Pragma("unroll") for (int k = 0; k < 2; ++k) dst[m][k] = *(const LAS bf16x8*)(lds + PG8_SA(b, h) + aoff + m * 2048 + k * 1024); } while (0)
; #define PG8_LDB(dst, b, h) do { _Pragma("unroll") for (int n = 0; n < 2; ++n) _Pragma("unroll") for (int k = 0; k < 2; ++k) dst[n][k] = *(const LAS bf16x8*)(lds + PG8_SB(b, h) + boff + n * 2048 + k * 1024); } while (0)
; #define PG8_MMA(ai, bj, At, Bt) do { __builtin_amdgcn_s_setprio(1); _Pragma("unroll") for (int m = 0; m < 4; ++m) _Pragma("unroll") for (int n = 0; n < 2; ++n) _Pragma("unroll") for (int k = 0; k < 2; ++k) \
;         acc[ai][bj][m][n] = __builtin_amdgcn_mfma_f32_16x16x32_bf16(Bt[n][k], At[m][k], acc[ai][bj][m][n], 0, 0, 0); __builtin_amdgcn_s_setprio(0); } while (0)
; #define PG8_WAIT_V(n) asm volatile("s_waitcnt vmcnt(" #n ")" ::: "memory")
; #define PG8_WAIT_L(n) asm volatile("s_waitcnt lgkmcnt(" #n ")" ::: "memory")
; #define PG8_BAR __builtin_amdgcn_s_barrier()
; #define PG8_SCHED __builtin_amdgcn_sched_barrier(0)
; template <class Epi>
; __device__ __forceinline__ void gemm_phase(LAS unsigned char* lds, const int tid, const Gemm g, const StaticOrder& S, const Epi& E) {
;     ...
;             PG8_WAIT_V(8); PG8_WAIT_L(0); PG8_BAR; PG8_MMA(1, 0, At, B0); PG8_MMA(1, 1, At, B1); PG8_BAR; PG8_SCHED;
;             PG8_LDB(B0, 1, 0); PG8_LDB(B1, 1, 1); PG8_SCHED; PG8_LDA(At, 1, 0); PG8_STAGE(PG8_SA(0, 1), a2 + hstepA, voffA);
;             PG8_WAIT_V(8); PG8_WAIT_L(0); PG8_BAR; PG8_MMA(0, 0, At, B0); PG8_MMA(0, 1, At, B1); PG8_BAR; PG8_SCHED;
	s_setprio 1
	s_waitcnt lgkmcnt(0)
	v_mfma_f32_16x16x32_bf16 v[78:81], v[50:53], v[216:219], v[78:81]
	v_mfma_f32_16x16x32_bf16 v[74:77], v[66:69], v[216:219], v[74:77]
	v_mfma_f32_16x16x32_bf16 v[46:49], v[50:53], v[224:227], v[46:49]
	v_mfma_f32_16x16x32_bf16 v[42:45], v[66:69], v[224:227], v[42:45]
	v_mfma_f32_16x16x32_bf16 v[30:33], v[50:53], v[232:235], v[30:33]
	v_mfma_f32_16x16x32_bf16 v[26:29], v[66:69], v[232:235], v[26:29]
	v_mfma_f32_16x16x32_bf16 v[14:17], v[50:53], v[240:243], v[14:17]
	v_mfma_f32_16x16x32_bf16 v[10:13], v[66:69], v[240:243], v[10:13]
	v_mfma_f32_16x16x32_bf16 v[78:81], v[54:57], v[220:223], v[78:81]
	v_mfma_f32_16x16x32_bf16 v[74:77], v[70:73], v[220:223], v[74:77]
	v_mfma_f32_16x16x32_bf16 v[46:49], v[54:57], v[228:231], v[46:49]
	v_mfma_f32_16x16x32_bf16 v[42:45], v[70:73], v[228:231], v[42:45]
	v_mfma_f32_16x16x32_bf16 v[30:33], v[54:57], v[236:239], v[30:33]
	v_mfma_f32_16x16x32_bf16 v[26:29], v[70:73], v[236:239], v[26:29]
	v_mfma_f32_16x16x32_bf16 v[14:17], v[54:57], v[244:247], v[14:17]
	v_mfma_f32_16x16x32_bf16 v[10:13], v[70:73], v[244:247], v[10:13]
	s_setprio 0
	s_setprio 1
	v_mfma_f32_16x16x32_bf16 v[38:41], v[156:159], v[224:227], v[38:41]
	v_mfma_f32_16x16x32_bf16 v[34:37], v[174:177], v[224:227], v[34:37]
	v_mfma_f32_16x16x32_bf16 v[22:25], v[156:159], v[232:235], v[22:25]
	v_mfma_f32_16x16x32_bf16 v[18:21], v[174:177], v[232:235], v[18:21]
	v_mfma_f32_16x16x32_bf16 v[6:9], v[156:159], v[240:243], v[6:9]
	v_mfma_f32_16x16x32_bf16 v[2:5], v[174:177], v[240:243], v[2:5]
	v_mfma_f32_16x16x32_bf16 v[50:53], v[156:159], v[216:219], v[62:65]
	v_mfma_f32_16x16x32_bf16 v[54:57], v[174:177], v[216:219], v[58:61]
	v_mfma_f32_16x16x32_bf16 v[38:41], v[170:173], v[228:231], v[38:41]
	v_mfma_f32_16x16x32_bf16 v[34:37], v[178:181], v[228:231], v[34:37]
	v_mfma_f32_16x16x32_bf16 v[22:25], v[170:173], v[236:239], v[22:25]
	v_mfma_f32_16x16x32_bf16 v[18:21], v[178:181], v[236:239], v[18:21]
	v_mfma_f32_16x16x32_bf16 v[6:9], v[170:173], v[244:247], v[6:9]
	v_mfma_f32_16x16x32_bf16 v[2:5], v[178:181], v[244:247], v[2:5]
	v_mfma_f32_16x16x32_bf16 v[50:53], v[170:173], v[220:223], v[50:53]
	v_mfma_f32_16x16x32_bf16 v[54:57], v[178:181], v[220:223], v[54:57]
	s_setprio 0
	s_barrier
	s_add_i32 s0, 0, 0x18000
	s_add_i32 s1, 0, 0x1c000
	v_add_u32_e32 v70, s0, v202
	v_add_u32_e32 v178, s1, v202
	ds_read_b128 v[58:61], v70
	ds_read_b128 v[62:65], v70 offset:1024
	ds_read_b128 v[66:69], v70 offset:2048
	ds_read_b128 v[70:73], v70 offset:3072
	ds_read_b128 v[156:159], v178
	ds_read_b128 v[170:173], v178 offset:1024
	ds_read_b128 v[174:177], v178 offset:2048
	ds_read_b128 v[178:181], v178 offset:3072
	s_add_u32 s10, s72, 0x40000
	s_addc_u32 s11, s73, 0
	s_mov_b32 m0, s89
	v_lshl_add_u64 v[206:207], s[10:11], 0, v[148:149]
	global_load_lds_dwordx4 v[206:207], off
	v_lshl_add_u64 v[206:207], s[10:11], 0, v[150:151]
	s_mov_b32 m0, s92
	s_nop 0
	global_load_lds_dwordx4 v[206:207], off
	ds_read_b128 v[216:219], v215 offset:32768
	ds_read_b128 v[220:223], v215 offset:33792
	ds_read_b128 v[224:227], v215 offset:34816
	ds_read_b128 v[228:231], v215 offset:35840
	ds_read_b128 v[232:235], v215 offset:36864
	ds_read_b128 v[236:239], v215 offset:37888
	ds_read_b128 v[240:243], v215 offset:38912
	ds_read_b128 v[244:247], v215 offset:39936
	s_waitcnt vmcnt(8)
	s_waitcnt lgkmcnt(0)
	s_barrier
	s_setprio 1
	s_waitcnt lgkmcnt(0)
	v_mfma_f32_16x16x32_bf16 v[142:145], v[58:61], v[216:219], v[142:145]
	v_mfma_f32_16x16x32_bf16 v[138:141], v[66:69], v[216:219], v[138:141]
	v_mfma_f32_16x16x32_bf16 v[126:129], v[58:61], v[224:227], v[126:129]
	v_mfma_f32_16x16x32_bf16 v[122:125], v[66:69], v[224:227], v[122:125]
	v_mfma_f32_16x16x32_bf16 v[110:113], v[58:61], v[232:235], v[110:113]
	v_mfma_f32_16x16x32_bf16 v[106:109], v[66:69], v[232:235], v[106:109]
	v_mfma_f32_16x16x32_bf16 v[94:97], v[58:61], v[240:243], v[94:97]
	v_mfma_f32_16x16x32_bf16 v[90:93], v[66:69], v[240:243], v[90:93]
	v_mfma_f32_16x16x32_bf16 v[142:145], v[62:65], v[220:223], v[142:145]
	v_mfma_f32_16x16x32_bf16 v[138:141], v[70:73], v[220:223], v[138:141]
	v_mfma_f32_16x16x32_bf16 v[126:129], v[62:65], v[228:231], v[126:129]
	v_mfma_f32_16x16x32_bf16 v[122:125], v[70:73], v[228:231], v[122:125]
	v_mfma_f32_16x16x32_bf16 v[110:113], v[62:65], v[236:239], v[110:113]
	v_mfma_f32_16x16x32_bf16 v[106:109], v[70:73], v[236:239], v[106:109]
	v_mfma_f32_16x16x32_bf16 v[94:97], v[62:65], v[244:247], v[94:97]
	v_mfma_f32_16x16x32_bf16 v[90:93], v[70:73], v[244:247], v[90:93]
	s_setprio 0
	s_setprio 1
	v_mfma_f32_16x16x32_bf16 v[134:137], v[156:159], v[216:219], v[134:137]
	v_mfma_f32_16x16x32_bf16 v[130:133], v[174:177], v[216:219], v[130:133]
	v_mfma_f32_16x16x32_bf16 v[118:121], v[156:159], v[224:227], v[118:121]
	v_mfma_f32_16x16x32_bf16 v[114:117], v[174:177], v[224:227], v[114:117]
	v_mfma_f32_16x16x32_bf16 v[102:105], v[156:159], v[232:235], v[102:105]
	v_mfma_f32_16x16x32_bf16 v[98:101], v[174:177], v[232:235], v[98:101]
	v_mfma_f32_16x16x32_bf16 v[86:89], v[156:159], v[240:243], v[86:89]
	v_mfma_f32_16x16x32_bf16 v[82:85], v[174:177], v[240:243], v[82:85]
	v_mfma_f32_16x16x32_bf16 v[134:137], v[170:173], v[220:223], v[134:137]
	v_mfma_f32_16x16x32_bf16 v[130:133], v[178:181], v[220:223], v[130:133]
	v_mfma_f32_16x16x32_bf16 v[118:121], v[170:173], v[228:231], v[118:121]
	v_mfma_f32_16x16x32_bf16 v[114:117], v[178:181], v[228:231], v[114:117]
	v_mfma_f32_16x16x32_bf16 v[102:105], v[170:173], v[236:239], v[102:105]
	v_mfma_f32_16x16x32_bf16 v[98:101], v[178:181], v[236:239], v[98:101]
	v_mfma_f32_16x16x32_bf16 v[86:89], v[170:173], v[244:247], v[86:89]
	v_mfma_f32_16x16x32_bf16 v[82:85], v[178:181], v[244:247], v[82:85]
	s_setprio 0
	s_barrier
; #define PG8_STAGE(bufoff, gbase, voff) do { _Pragma("unroll") for (int _i = 0; _i < 2; ++_i) \
;         __builtin_amdgcn_global_load_lds((const unsigned*)((const char*)(gbase) + (voff)[_i]), (LAS unsigned*)(lds + (bufoff) + ldsw + _i * 8192), 16, 0, 0); } while (0)
; #define PG8_LDA(dst, b, h) do { _Pragma("unroll") for (int m = 0; m < 4; ++m) _Pragma("unroll") for (int k = 0; k < 2; ++k) dst[m][k] = *(const LAS bf16x8*)(lds + PG8_SA(b, h) + aoff + m * 2048 + k * 1024); } while (0)
; #define PG8_MMA(ai, bj, At, Bt) do { __builtin_amdgcn_s_setprio(1); _Pragma("unroll") for (int m = 0; m < 4; ++m) _Pragma("unroll") for (int n = 0; n < 2; ++n) _Pragma("unroll") for (int k = 0; k < 2; ++k) \
;         acc[ai][bj][m][n] = __builtin_amdgcn_mfma_f32_16x16x32_bf16(Bt[n][k], At[m][k], acc[ai][bj][m][n], 0, 0, 0); __builtin_amdgcn_s_setprio(0); } while (0)
; #define PG8_WAIT_V(n) asm volatile("s_waitcnt vmcnt(" #n ")" ::: "memory")
; #define PG8_WAIT_L(n) asm volatile("s_waitcnt lgkmcnt(" #n ")" ::: "memory")
; #define PG8_BAR __builtin_amdgcn_s_barrier()
; #define PG8_SCHED __builtin_amdgcn_sched_barrier(0)
; template <class Epi>
; __device__ __forceinline__ void gemm_phase(LAS unsigned char* lds, const int tid, const Gemm g, const StaticOrder& S, const Epi& E) {
;     ...
;             PG8_LDA(At, 1, 1); PG8_STAGE(PG8_SB(1, 0), b3, voffB); PG8_STAGE(PG8_SB(1, 1), b3 + hstepB, voffB); PG8_STAGE(PG8_SA(1, 0), a3, voffA);
;             PG8_WAIT_V(8); PG8_WAIT_L(0); PG8_BAR; PG8_MMA(1, 0, At, B0); PG8_MMA(1, 1, At, B1); PG8_BAR; PG8_SCHED;
;         }
;         if (wr == 0) PG8_BAR;
	s_add_i32 s0, s0, s82
	v_lshl_add_u64 v[160:161], v[160:161], 0, s[36:37]
	s_mov_b32 m0, s0
	s_nop 0
	global_load_lds_dwordx4 v[160:161], off
	s_add_i32 m0, s0, 0x2000
	s_add_u32 s10, s70, 0x40080
	v_lshl_add_u64 v[160:161], v[182:183], 0, s[36:37]
	s_addc_u32 s11, s71, 0
	s_add_i32 s0, s1, s82
	global_load_lds_dwordx4 v[160:161], off
	v_lshl_add_u64 v[160:161], s[10:11], 0, v[0:1]
	s_mov_b32 m0, s0
	s_nop 0
	global_load_lds_dwordx4 v[160:161], off
	v_lshl_add_u64 v[160:161], s[10:11], 0, v[146:147]
	s_add_i32 m0, s0, 0x2000
	s_nop 0
	global_load_lds_dwordx4 v[160:161], off
	v_lshl_add_u64 v[160:161], v[162:163], 0, s[36:37]
	s_mov_b32 m0, s93
	s_nop 0
	global_load_lds_dwordx4 v[160:161], off
	v_lshl_add_u64 v[160:161], v[164:165], 0, s[36:37]
	s_mov_b32 m0, s74
	s_nop 0
	global_load_lds_dwordx4 v[160:161], off
	ds_read_b128 v[216:219], v215 offset:49152
	ds_read_b128 v[220:223], v215 offset:50176
	ds_read_b128 v[224:227], v215 offset:51200
	ds_read_b128 v[228:231], v215 offset:52224
	ds_read_b128 v[232:235], v215 offset:53248
	ds_read_b128 v[236:239], v215 offset:54272
	ds_read_b128 v[240:243], v215 offset:55296
	ds_read_b128 v[244:247], v215 offset:56320
	s_waitcnt vmcnt(8)
	s_waitcnt lgkmcnt(0)
	s_barrier
	s_setprio 1
	s_waitcnt lgkmcnt(0)
	v_mfma_f32_16x16x32_bf16 v[78:81], v[58:61], v[216:219], v[78:81]
	v_mfma_f32_16x16x32_bf16 v[74:77], v[66:69], v[216:219], v[74:77]
	v_mfma_f32_16x16x32_bf16 v[46:49], v[58:61], v[224:227], v[46:49]
	v_mfma_f32_16x16x32_bf16 v[42:45], v[66:69], v[224:227], v[42:45]
	v_mfma_f32_16x16x32_bf16 v[30:33], v[58:61], v[232:235], v[30:33]
	v_mfma_f32_16x16x32_bf16 v[26:29], v[66:69], v[232:235], v[26:29]
	v_mfma_f32_16x16x32_bf16 v[14:17], v[58:61], v[240:243], v[14:17]
	v_mfma_f32_16x16x32_bf16 v[10:13], v[66:69], v[240:243], v[10:13]
	v_mfma_f32_16x16x32_bf16 v[78:81], v[62:65], v[220:223], v[78:81]
	v_mfma_f32_16x16x32_bf16 v[74:77], v[70:73], v[220:223], v[74:77]
	v_mfma_f32_16x16x32_bf16 v[46:49], v[62:65], v[228:231], v[46:49]
	v_mfma_f32_16x16x32_bf16 v[42:45], v[70:73], v[228:231], v[42:45]
	v_mfma_f32_16x16x32_bf16 v[30:33], v[62:65], v[236:239], v[30:33]
	v_mfma_f32_16x16x32_bf16 v[26:29], v[70:73], v[236:239], v[26:29]
	v_mfma_f32_16x16x32_bf16 v[14:17], v[62:65], v[244:247], v[14:17]
	v_mfma_f32_16x16x32_bf16 v[10:13], v[70:73], v[244:247], v[10:13]
	s_setprio 0
	s_setprio 1
	v_mfma_f32_16x16x32_bf16 v[50:53], v[156:159], v[216:219], v[50:53]
	v_mfma_f32_16x16x32_bf16 v[62:65], v[170:173], v[220:223], v[50:53]
	v_mfma_f32_16x16x32_bf16 v[50:53], v[174:177], v[216:219], v[54:57]
	v_mfma_f32_16x16x32_bf16 v[38:41], v[156:159], v[224:227], v[38:41]
	v_mfma_f32_16x16x32_bf16 v[34:37], v[174:177], v[224:227], v[34:37]
	v_mfma_f32_16x16x32_bf16 v[22:25], v[156:159], v[232:235], v[22:25]
	v_mfma_f32_16x16x32_bf16 v[18:21], v[174:177], v[232:235], v[18:21]
	v_mfma_f32_16x16x32_bf16 v[6:9], v[156:159], v[240:243], v[6:9]
	v_mfma_f32_16x16x32_bf16 v[2:5], v[174:177], v[240:243], v[2:5]
	v_mfma_f32_16x16x32_bf16 v[58:61], v[178:181], v[220:223], v[50:53]
	v_mfma_f32_16x16x32_bf16 v[38:41], v[170:173], v[228:231], v[38:41]
	v_mfma_f32_16x16x32_bf16 v[34:37], v[178:181], v[228:231], v[34:37]
	v_mfma_f32_16x16x32_bf16 v[22:25], v[170:173], v[236:239], v[22:25]
	v_mfma_f32_16x16x32_bf16 v[18:21], v[178:181], v[236:239], v[18:21]
	v_mfma_f32_16x16x32_bf16 v[6:9], v[170:173], v[244:247], v[6:9]
	v_mfma_f32_16x16x32_bf16 v[2:5], v[178:181], v[244:247], v[2:5]
	s_setprio 0
	s_barrier
	s_add_i32 s16, s16, 2
	s_add_u32 s68, s68, 0x100
	s_addc_u32 s69, s69, 0
	s_add_u32 vcc_hi, vcc_hi, 0x100
	s_addc_u32 s76, s76, 0
	s_cmp_gt_u32 s16, 13
	s_cbranch_scc0 .LBB0_414
	s_and_b64 vcc, exec, s[2:3]
	s_cbranch_vccz .LBB0_417
	s_barrier

; #define PG8_STAGE(bufoff, gbase, voff) do { _Pragma("unroll") for (int _i = 0; _i < 2; ++_i) \
;         __builtin_amdgcn_global_load_lds((const unsigned*)((const char*)(gbase) + (voff)[_i]), (LAS unsigned*)(lds + (bufoff) + ldsw + _i * 8192), 16, 0, 0); } while (0)
; #define PG8_LDA(dst, b, h) do { _Pragma("unroll") for (int m = 0; m < 4; ++m) _Pragma("unroll") for (int k = 0; k < 2; ++k) dst[m][k] = *(const LAS bf16x8*)(lds + PG8_SA(b, h) + aoff + m * 2048 + k * 1024); } while (0)
; #define PG8_LDB(dst, b, h) do { _Pragma("unroll") for (int n = 0; n < 2; ++n) _Pragma("unroll") for (int k = 0; k < 2; ++k) dst[n][k] = *(const LAS bf16x8*)(lds + PG8_SB(b, h) + boff + n * 2048 + k * 1024); } while (0)
; #define PG8_MMA(ai, bj, At, Bt) do { __builtin_amdgcn_s_setprio(1); _Pragma("unroll") for (int m = 0; m < 4; ++m) _Pragma("unroll") for (int n = 0; n < 2; ++n) _Pragma("unroll") for (int k = 0; k < 2; ++k) \
;         acc[ai][bj][m][n] = __builtin_amdgcn_mfma_f32_16x16x32_bf16(Bt[n][k], At[m][k], acc[ai][bj][m][n], 0, 0, 0); __builtin_amdgcn_s_setprio(0); } while (0)
; #define PG8_WAIT_V(n) asm volatile("s_waitcnt vmcnt(" #n ")" ::: "memory")
; #define PG8_WAIT_L(n) asm volatile("s_waitcnt lgkmcnt(" #n ")" ::: "memory")
; #define PG8_BAR __builtin_amdgcn_s_barrier()
; #define PG8_SCHED __builtin_amdgcn_sched_barrier(0)
; template <class Epi>
; __device__ __forceinline__ void gemm_phase(LAS unsigned char* lds, const int tid, const Gemm g, const StaticOrder& S, const Epi& E) {
;     ...
;         for (int t = 0; t < nt; t += 2) {
;             const bool last = (t == nt - 2);
;             const char* a1 = cA + (size_t)(t + 1) * kstep;
;             const char* a2 = last ? nA : cA + (size_t)(t + 2) * kstep; const char* b2 = last ? nB : cB + (size_t)(t + 2) * kstep;
;             const char* a3 = a2 + kstep; const char* b3 = b2 + kstep;
;             PG8_LDB(B0, 0, 0); PG8_LDB(B1, 0, 1); PG8_SCHED; PG8_LDA(At, 0, 0); PG8_STAGE(PG8_SA(1, 1), a1 + hstepA, voffA);
;             PG8_WAIT_V(8); PG8_WAIT_L(0); PG8_BAR; PG8_MMA(0, 0, At, B0); PG8_MMA(0, 1, At, B1); PG8_BAR; PG8_SCHED;
;             PG8_LDA(At, 0, 1); PG8_STAGE(PG8_SB(0, 0), b2, voffB); PG8_STAGE(PG8_SB(0, 1), b2 + hstepB, voffB); PG8_STAGE(PG8_SA(0, 0), a2, voffA);
;             PG8_WAIT_V(8); PG8_WAIT_L(0); PG8_BAR; PG8_MMA(1, 0, At, B0); PG8_MMA(1, 1, At, B1); PG8_BAR; PG8_SCHED;
.LBB0_945:
	s_add_u32 s30, s72, 0xfffc0080
	s_addc_u32 s31, s73, -1
	s_add_i32 s76, 0, 0x10000
	s_cmp_eq_u32 vcc_hi, 12
	s_cselect_b32 s75, s9, s31
	s_cselect_b32 s74, s27, s30
	v_add_u32_e32 v0, s76, v178
	s_cselect_b32 s31, s7, vcc_lo
	s_cselect_b32 s30, s28, s65
	s_add_i32 s0, 0, 0x14000
	ds_read_b128 v[18:21], v0
	ds_read_b128 v[22:25], v0 offset:1024
	ds_read_b128 v[26:29], v0 offset:2048
	ds_read_b128 v[30:33], v0 offset:3072
	v_add_u32_e32 v0, s0, v178
	ds_read_b128 v[170:173], v0
	ds_read_b128 v[174:177], v0 offset:1024
	ds_read_b128 v[190:193], v0 offset:2048
	ds_read_b128 v[194:197], v0 offset:3072
	v_lshl_add_u64 v[162:163], s[72:73], 0, v[158:159]
	s_add_i32 m0, s71, 0xc000
	s_nop 0
	global_load_lds_dwordx4 v[162:163], off
	v_lshl_add_u64 v[162:163], s[72:73], 0, v[160:161]
	s_add_i32 m0, s71, 0xe000
	s_nop 0
	global_load_lds_dwordx4 v[162:163], off
	ds_read_b128 v[198:201], v189
	ds_read_b128 v[210:213], v189 offset:1024
	ds_read_b128 v[214:217], v189 offset:2048
	ds_read_b128 v[218:221], v189 offset:3072
	ds_read_b128 v[222:225], v189 offset:4096
	ds_read_b128 v[226:229], v189 offset:5120
	ds_read_b128 v[230:233], v189 offset:6144
	ds_read_b128 v[234:237], v189 offset:7168
	s_waitcnt vmcnt(8)
	s_waitcnt lgkmcnt(0)
	s_barrier
	s_setprio 1
	s_waitcnt lgkmcnt(0)
	v_mfma_f32_16x16x32_bf16 v[142:145], v[18:21], v[198:201], v[142:145]
	v_mfma_f32_16x16x32_bf16 v[138:141], v[26:29], v[198:201], v[138:141]
	v_mfma_f32_16x16x32_bf16 v[126:129], v[18:21], v[214:217], v[126:129]
	v_mfma_f32_16x16x32_bf16 v[122:125], v[26:29], v[214:217], v[122:125]
	v_mfma_f32_16x16x32_bf16 v[110:113], v[18:21], v[222:225], v[110:113]
	v_mfma_f32_16x16x32_bf16 v[106:109], v[26:29], v[222:225], v[106:109]
	v_mfma_f32_16x16x32_bf16 v[94:97], v[18:21], v[230:233], v[94:97]
	v_mfma_f32_16x16x32_bf16 v[90:93], v[26:29], v[230:233], v[90:93]
	v_mfma_f32_16x16x32_bf16 v[142:145], v[22:25], v[210:213], v[142:145]
	v_mfma_f32_16x16x32_bf16 v[138:141], v[30:33], v[210:213], v[138:141]
	v_mfma_f32_16x16x32_bf16 v[126:129], v[22:25], v[218:221], v[126:129]
	v_mfma_f32_16x16x32_bf16 v[122:125], v[30:33], v[218:221], v[122:125]
	v_mfma_f32_16x16x32_bf16 v[110:113], v[22:25], v[226:229], v[110:113]
	v_mfma_f32_16x16x32_bf16 v[106:109], v[30:33], v[226:229], v[106:109]
	v_mfma_f32_16x16x32_bf16 v[94:97], v[22:25], v[234:237], v[94:97]
	v_mfma_f32_16x16x32_bf16 v[90:93], v[30:33], v[234:237], v[90:93]
	s_setprio 0
	s_setprio 1
	v_mfma_f32_16x16x32_bf16 v[134:137], v[170:173], v[198:201], v[134:137]
	v_mfma_f32_16x16x32_bf16 v[130:133], v[190:193], v[198:201], v[130:133]
	v_mfma_f32_16x16x32_bf16 v[118:121], v[170:173], v[214:217], v[118:121]
	v_mfma_f32_16x16x32_bf16 v[114:117], v[190:193], v[214:217], v[114:117]
	v_mfma_f32_16x16x32_bf16 v[102:105], v[170:173], v[222:225], v[102:105]
	v_mfma_f32_16x16x32_bf16 v[98:101], v[190:193], v[222:225], v[98:101]
	v_mfma_f32_16x16x32_bf16 v[86:89], v[170:173], v[230:233], v[86:89]
	v_mfma_f32_16x16x32_bf16 v[82:85], v[190:193], v[230:233], v[82:85]
	v_mfma_f32_16x16x32_bf16 v[134:137], v[174:177], v[210:213], v[134:137]
	v_mfma_f32_16x16x32_bf16 v[130:133], v[194:197], v[210:213], v[130:133]
	v_mfma_f32_16x16x32_bf16 v[118:121], v[174:177], v[218:221], v[118:121]
	v_mfma_f32_16x16x32_bf16 v[114:117], v[194:197], v[218:221], v[114:117]
	v_mfma_f32_16x16x32_bf16 v[102:105], v[174:177], v[226:229], v[102:105]
	v_mfma_f32_16x16x32_bf16 v[98:101], v[194:197], v[226:229], v[98:101]
	v_mfma_f32_16x16x32_bf16 v[86:89], v[174:177], v[234:237], v[86:89]
	v_mfma_f32_16x16x32_bf16 v[82:85], v[194:197], v[234:237], v[82:85]
	s_setprio 0
	s_barrier
	s_add_i32 s1, s76, s93
	v_lshl_add_u64 v[162:163], s[30:31], 0, v[150:151]
	s_mov_b32 m0, s1
	s_nop 0
	global_load_lds_dwordx4 v[162:163], off
	s_add_i32 m0, s1, 0x2000
	s_add_u32 s76, s30, 0x40000
	v_lshl_add_u64 v[164:165], s[30:31], 0, v[154:155]
	s_addc_u32 s77, s31, 0
	s_add_i32 s0, s0, s93
	global_load_lds_dwordx4 v[164:165], off
	v_lshl_add_u64 v[202:203], s[76:77], 0, v[150:151]
	s_mov_b32 m0, s0
	v_lshl_add_u64 v[206:207], s[74:75], 0, v[152:153]
	global_load_lds_dwordx4 v[202:203], off
	v_lshl_add_u64 v[202:203], s[76:77], 0, v[154:155]
	s_add_i32 m0, s0, 0x2000
	s_nop 0
	global_load_lds_dwordx4 v[202:203], off
	v_lshl_add_u64 v[202:203], s[74:75], 0, v[148:149]
	s_mov_b32 m0, s71
	s_nop 0
	global_load_lds_dwordx4 v[202:203], off
	s_mov_b32 m0, s88
	s_nop 0
	global_load_lds_dwordx4 v[206:207], off
	ds_read_b128 v[198:201], v189 offset:16384
	ds_read_b128 v[210:213], v189 offset:17408
	ds_read_b128 v[214:217], v189 offset:18432
	ds_read_b128 v[218:221], v189 offset:19456
	ds_read_b128 v[222:225], v189 offset:20480
	ds_read_b128 v[226:229], v189 offset:21504
	ds_read_b128 v[230:233], v189 offset:22528
	ds_read_b128 v[234:237], v189 offset:23552
	s_waitcnt vmcnt(8)
	s_waitcnt lgkmcnt(0)
	s_barrier
; #define PG8_STAGE(bufoff, gbase, voff) do { _Pragma("unroll") for (int _i = 0; _i < 2; ++_i) \
;         __builtin_amdgcn_global_load_lds((const unsigned*)((const char*)(gbase) + (voff)[_i]), (LAS unsigned*)(lds + (bufoff) + ldsw + _i * 8192), 16, 0, 0); } while (0)
; #define PG8_LDA(dst, b, h) do { _Pragma("unroll") for (int m = 0; m < 4; ++m) _Pragma("unroll") for (int k = 0; k < 2; ++k) dst[m][k] = *(const LAS bf16x8*)(lds + PG8_SA(b, h) + aoff + m * 2048 + k * 1024); } while (0)
; #define PG8_LDB(dst, b, h) do { _Pragma("unroll") for (int n = 0; n < 2; ++n) _Pragma("unroll") for (int k = 0; k < 2; ++k) dst[n][k] = *(const LAS bf16x8*)(lds + PG8_SB(b, h) + boff + n * 2048 + k * 1024); } while (0)
; #define PG8_MMA(ai, bj, At, Bt) do { __builtin_amdgcn_s_setprio(1); _Pragma("unroll") for (int m = 0; m < 4; ++m) _Pragma("unroll") for (int n = 0; n < 2; ++n) _Pragma("unroll") for (int k = 0; k < 2; ++k) \
;         acc[ai][bj][m][n] = __builtin_amdgcn_mfma_f32_16x16x32_bf16(Bt[n][k], At[m][k], acc[ai][bj][m][n], 0, 0, 0); __builtin_amdgcn_s_setprio(0); } while (0)
; #define PG8_WAIT_V(n) asm volatile("s_waitcnt vmcnt(" #n ")" ::: "memory")
; #define PG8_WAIT_L(n) asm volatile("s_waitcnt lgkmcnt(" #n ")" ::: "memory")
; #define PG8_BAR __builtin_amdgcn_s_barrier()
; #define PG8_SCHED __builtin_amdgcn_sched_barrier(0)
; template <class Epi>
; __device__ __forceinline__ void gemm_phase(LAS unsigned char* lds, const int tid, const Gemm g, const StaticOrder& S, const Epi& E) {
;     ...
;             PG8_WAIT_V(8); PG8_WAIT_L(0); PG8_BAR; PG8_MMA(1, 0, At, B0); PG8_MMA(1, 1, At, B1); PG8_BAR; PG8_SCHED;
;             PG8_LDB(B0, 1, 0); PG8_LDB(B1, 1, 1); PG8_SCHED; PG8_LDA(At, 1, 0); PG8_STAGE(PG8_SA(0, 1), a2 + hstepA, voffA);
;             PG8_WAIT_V(8); PG8_WAIT_L(0); PG8_BAR; PG8_MMA(0, 0, At, B0); PG8_MMA(0, 1, At, B1); PG8_BAR; PG8_SCHED;
;             PG8_LDA(At, 1, 1); PG8_STAGE(PG8_SB(1, 0), b3, voffB); PG8_STAGE(PG8_SB(1, 1), b3 + hstepB, voffB); PG8_STAGE(PG8_SA(1, 0), a3, voffA);
;             PG8_WAIT_V(8); PG8_WAIT_L(0); PG8_BAR; PG8_MMA(1, 0, At, B0); PG8_MMA(1, 1, At, B1); PG8_BAR; PG8_SCHED;
	s_setprio 1
	s_waitcnt lgkmcnt(0)
	v_mfma_f32_16x16x32_bf16 v[78:81], v[18:21], v[198:201], v[78:81]
	v_mfma_f32_16x16x32_bf16 v[74:77], v[26:29], v[198:201], v[74:77]
	v_mfma_f32_16x16x32_bf16 v[62:65], v[18:21], v[214:217], v[62:65]
	v_mfma_f32_16x16x32_bf16 v[58:61], v[26:29], v[214:217], v[58:61]
	v_mfma_f32_16x16x32_bf16 v[46:49], v[18:21], v[222:225], v[46:49]
	v_mfma_f32_16x16x32_bf16 v[42:45], v[26:29], v[222:225], v[42:45]
	v_mfma_f32_16x16x32_bf16 v[14:17], v[18:21], v[230:233], v[14:17]
	v_mfma_f32_16x16x32_bf16 v[10:13], v[26:29], v[230:233], v[10:13]
	v_mfma_f32_16x16x32_bf16 v[78:81], v[22:25], v[210:213], v[78:81]
	v_mfma_f32_16x16x32_bf16 v[74:77], v[30:33], v[210:213], v[74:77]
	v_mfma_f32_16x16x32_bf16 v[62:65], v[22:25], v[218:221], v[62:65]
	v_mfma_f32_16x16x32_bf16 v[58:61], v[30:33], v[218:221], v[58:61]
	v_mfma_f32_16x16x32_bf16 v[46:49], v[22:25], v[226:229], v[46:49]
	v_mfma_f32_16x16x32_bf16 v[42:45], v[30:33], v[226:229], v[42:45]
	v_mfma_f32_16x16x32_bf16 v[14:17], v[22:25], v[234:237], v[14:17]
	v_mfma_f32_16x16x32_bf16 v[10:13], v[30:33], v[234:237], v[10:13]
	s_setprio 0
	s_setprio 1
	v_mfma_f32_16x16x32_bf16 v[38:41], v[170:173], v[222:225], v[38:41]
	v_mfma_f32_16x16x32_bf16 v[34:37], v[190:193], v[222:225], v[34:37]
	v_mfma_f32_16x16x32_bf16 v[6:9], v[170:173], v[230:233], v[6:9]
	v_mfma_f32_16x16x32_bf16 v[2:5], v[190:193], v[230:233], v[2:5]
	v_mfma_f32_16x16x32_bf16 v[18:21], v[170:173], v[198:201], v[70:73]
	v_mfma_f32_16x16x32_bf16 v[22:25], v[190:193], v[198:201], v[66:69]
	v_mfma_f32_16x16x32_bf16 v[26:29], v[170:173], v[214:217], v[54:57]
	v_mfma_f32_16x16x32_bf16 v[30:33], v[190:193], v[214:217], v[50:53]
	v_mfma_f32_16x16x32_bf16 v[38:41], v[174:177], v[226:229], v[38:41]
	v_mfma_f32_16x16x32_bf16 v[34:37], v[194:197], v[226:229], v[34:37]
	v_mfma_f32_16x16x32_bf16 v[6:9], v[174:177], v[234:237], v[6:9]
	v_mfma_f32_16x16x32_bf16 v[2:5], v[194:197], v[234:237], v[2:5]
	v_mfma_f32_16x16x32_bf16 v[18:21], v[174:177], v[210:213], v[18:21]
	v_mfma_f32_16x16x32_bf16 v[22:25], v[194:197], v[210:213], v[22:25]
	v_mfma_f32_16x16x32_bf16 v[26:29], v[174:177], v[218:221], v[26:29]
	v_mfma_f32_16x16x32_bf16 v[30:33], v[194:197], v[218:221], v[30:33]
	s_setprio 0
	s_barrier
	s_add_i32 s0, 0, 0x18000
	v_add_u32_e32 v0, s0, v178
	s_add_i32 s1, 0, 0x1c000
	ds_read_b128 v[50:53], v0
	ds_read_b128 v[54:57], v0 offset:1024
	ds_read_b128 v[66:69], v0 offset:2048
	ds_read_b128 v[70:73], v0 offset:3072
	v_add_u32_e32 v0, s1, v178
	ds_read_b128 v[170:173], v0
	ds_read_b128 v[174:177], v0 offset:1024
	ds_read_b128 v[190:193], v0 offset:2048
	ds_read_b128 v[194:197], v0 offset:3072
	s_add_u32 s74, s74, 0x40000
	s_addc_u32 s75, s75, 0
	s_mov_b32 m0, s83
	v_lshl_add_u64 v[238:239], s[74:75], 0, v[148:149]
	global_load_lds_dwordx4 v[238:239], off
	v_lshl_add_u64 v[238:239], s[74:75], 0, v[152:153]
	s_mov_b32 m0, s16
	s_nop 0
	global_load_lds_dwordx4 v[238:239], off
	ds_read_b128 v[198:201], v189 offset:32768
	ds_read_b128 v[210:213], v189 offset:33792
	ds_read_b128 v[214:217], v189 offset:34816
	ds_read_b128 v[218:221], v189 offset:35840
	ds_read_b128 v[222:225], v189 offset:36864
	ds_read_b128 v[226:229], v189 offset:37888
	ds_read_b128 v[230:233], v189 offset:38912
	ds_read_b128 v[234:237], v189 offset:39936
	s_waitcnt vmcnt(8)
	s_waitcnt lgkmcnt(0)
	s_barrier
	s_setprio 1
	s_waitcnt lgkmcnt(0)
	v_mfma_f32_16x16x32_bf16 v[142:145], v[50:53], v[198:201], v[142:145]
	v_mfma_f32_16x16x32_bf16 v[138:141], v[66:69], v[198:201], v[138:141]
	v_mfma_f32_16x16x32_bf16 v[126:129], v[50:53], v[214:217], v[126:129]
	v_mfma_f32_16x16x32_bf16 v[122:125], v[66:69], v[214:217], v[122:125]
	v_mfma_f32_16x16x32_bf16 v[110:113], v[50:53], v[222:225], v[110:113]
	v_mfma_f32_16x16x32_bf16 v[106:109], v[66:69], v[222:225], v[106:109]
	v_mfma_f32_16x16x32_bf16 v[94:97], v[50:53], v[230:233], v[94:97]
	v_mfma_f32_16x16x32_bf16 v[90:93], v[66:69], v[230:233], v[90:93]
	v_mfma_f32_16x16x32_bf16 v[142:145], v[54:57], v[210:213], v[142:145]
	v_mfma_f32_16x16x32_bf16 v[138:141], v[70:73], v[210:213], v[138:141]
	v_mfma_f32_16x16x32_bf16 v[126:129], v[54:57], v[218:221], v[126:129]
	v_mfma_f32_16x16x32_bf16 v[122:125], v[70:73], v[218:221], v[122:125]
	v_mfma_f32_16x16x32_bf16 v[110:113], v[54:57], v[226:229], v[110:113]
	v_mfma_f32_16x16x32_bf16 v[106:109], v[70:73], v[226:229], v[106:109]
	v_mfma_f32_16x16x32_bf16 v[94:97], v[54:57], v[234:237], v[94:97]
	v_mfma_f32_16x16x32_bf16 v[90:93], v[70:73], v[234:237], v[90:93]
	s_setprio 0
	s_setprio 1
	v_mfma_f32_16x16x32_bf16 v[134:137], v[170:173], v[198:201], v[134:137]
	v_mfma_f32_16x16x32_bf16 v[130:133], v[190:193], v[198:201], v[130:133]
	v_mfma_f32_16x16x32_bf16 v[118:121], v[170:173], v[214:217], v[118:121]
	v_mfma_f32_16x16x32_bf16 v[114:117], v[190:193], v[214:217], v[114:117]
	v_mfma_f32_16x16x32_bf16 v[102:105], v[170:173], v[222:225], v[102:105]
	v_mfma_f32_16x16x32_bf16 v[98:101], v[190:193], v[222:225], v[98:101]
	v_mfma_f32_16x16x32_bf16 v[86:89], v[170:173], v[230:233], v[86:89]
	v_mfma_f32_16x16x32_bf16 v[82:85], v[190:193], v[230:233], v[82:85]
	v_mfma_f32_16x16x32_bf16 v[134:137], v[174:177], v[210:213], v[134:137]
	v_mfma_f32_16x16x32_bf16 v[130:133], v[194:197], v[210:213], v[130:133]
	v_mfma_f32_16x16x32_bf16 v[118:121], v[174:177], v[218:221], v[118:121]
	v_mfma_f32_16x16x32_bf16 v[114:117], v[194:197], v[218:221], v[114:117]
	v_mfma_f32_16x16x32_bf16 v[102:105], v[174:177], v[226:229], v[102:105]
	v_mfma_f32_16x16x32_bf16 v[98:101], v[194:197], v[226:229], v[98:101]
	v_mfma_f32_16x16x32_bf16 v[86:89], v[174:177], v[234:237], v[86:89]
	v_mfma_f32_16x16x32_bf16 v[82:85], v[194:197], v[234:237], v[82:85]
	s_setprio 0
	s_barrier
; #define PG8_STAGE(bufoff, gbase, voff) do { _Pragma("unroll") for (int _i = 0; _i < 2; ++_i) \
;         __builtin_amdgcn_global_load_lds((const unsigned*)((const char*)(gbase) + (voff)[_i]), (LAS unsigned*)(lds + (bufoff) + ldsw + _i * 8192), 16, 0, 0); } while (0)
; #define PG8_LDA(dst, b, h) do { _Pragma("unroll") for (int m = 0; m < 4; ++m) _Pragma("unroll") for (int k = 0; k < 2; ++k) dst[m][k] = *(const LAS bf16x8*)(lds + PG8_SA(b, h) + aoff + m * 2048 + k * 1024); } while (0)
; #define PG8_MMA(ai, bj, At, Bt) do { __builtin_amdgcn_s_setprio(1); _Pragma("unroll") for (int m = 0; m < 4; ++m) _Pragma("unroll") for (int n = 0; n < 2; ++n) _Pragma("unroll") for (int k = 0; k < 2; ++k) \
;         acc[ai][bj][m][n] = __builtin_amdgcn_mfma_f32_16x16x32_bf16(Bt[n][k], At[m][k], acc[ai][bj][m][n], 0, 0, 0); __builtin_amdgcn_s_setprio(0); } while (0)
; #define PG8_WAIT_V(n) asm volatile("s_waitcnt vmcnt(" #n ")" ::: "memory")
; #define PG8_WAIT_L(n) asm volatile("s_waitcnt lgkmcnt(" #n ")" ::: "memory")
; #define PG8_BAR __builtin_amdgcn_s_barrier()
; #define PG8_SCHED __builtin_amdgcn_sched_barrier(0)
; template <class Epi>
; __device__ __forceinline__ void gemm_phase(LAS unsigned char* lds, const int tid, const Gemm g, const StaticOrder& S, const Epi& E) {
;     ...
;             PG8_LDA(At, 1, 1); PG8_STAGE(PG8_SB(1, 0), b3, voffB); PG8_STAGE(PG8_SB(1, 1), b3 + hstepB, voffB); PG8_STAGE(PG8_SA(1, 0), a3, voffA);
;             PG8_WAIT_V(8); PG8_WAIT_L(0); PG8_BAR; PG8_MMA(1, 0, At, B0); PG8_MMA(1, 1, At, B1); PG8_BAR; PG8_SCHED;
;         }
;         if (wr == 0) PG8_BAR;
	s_add_i32 s0, s0, s93
	v_lshl_add_u64 v[162:163], v[162:163], 0, s[36:37]
	s_mov_b32 m0, s0
	s_nop 0
	global_load_lds_dwordx4 v[162:163], off
	s_add_i32 m0, s0, 0x2000
	s_add_u32 s30, s30, 0x40080
	v_lshl_add_u64 v[162:163], v[164:165], 0, s[36:37]
	s_addc_u32 s31, s31, 0
	s_add_i32 s0, s1, s93
	global_load_lds_dwordx4 v[162:163], off
	v_lshl_add_u64 v[162:163], s[30:31], 0, v[150:151]
	s_mov_b32 m0, s0
	s_nop 0
	global_load_lds_dwordx4 v[162:163], off
	v_lshl_add_u64 v[162:163], s[30:31], 0, v[154:155]
	s_add_i32 m0, s0, 0x2000
	s_nop 0
	global_load_lds_dwordx4 v[162:163], off
	v_lshl_add_u64 v[162:163], v[202:203], 0, s[36:37]
	s_mov_b32 m0, s92
	s_nop 0
	global_load_lds_dwordx4 v[162:163], off
	v_lshl_add_u64 v[162:163], v[206:207], 0, s[36:37]
	s_mov_b32 m0, s89
	s_nop 0
	global_load_lds_dwordx4 v[162:163], off
	ds_read_b128 v[198:201], v189 offset:49152
	ds_read_b128 v[210:213], v189 offset:50176
	ds_read_b128 v[214:217], v189 offset:51200
	ds_read_b128 v[218:221], v189 offset:52224
	ds_read_b128 v[222:225], v189 offset:53248
	ds_read_b128 v[226:229], v189 offset:54272
	ds_read_b128 v[230:233], v189 offset:55296
	ds_read_b128 v[234:237], v189 offset:56320
	s_waitcnt vmcnt(8)
	s_waitcnt lgkmcnt(0)
	s_barrier
	s_setprio 1
	s_waitcnt lgkmcnt(0)
	v_mfma_f32_16x16x32_bf16 v[78:81], v[50:53], v[198:201], v[78:81]
	v_mfma_f32_16x16x32_bf16 v[74:77], v[66:69], v[198:201], v[74:77]
	v_mfma_f32_16x16x32_bf16 v[62:65], v[50:53], v[214:217], v[62:65]
	v_mfma_f32_16x16x32_bf16 v[58:61], v[66:69], v[214:217], v[58:61]
	v_mfma_f32_16x16x32_bf16 v[46:49], v[50:53], v[222:225], v[46:49]
	v_mfma_f32_16x16x32_bf16 v[42:45], v[66:69], v[222:225], v[42:45]
	v_mfma_f32_16x16x32_bf16 v[14:17], v[50:53], v[230:233], v[14:17]
	v_mfma_f32_16x16x32_bf16 v[10:13], v[66:69], v[230:233], v[10:13]
	v_mfma_f32_16x16x32_bf16 v[78:81], v[54:57], v[210:213], v[78:81]
	v_mfma_f32_16x16x32_bf16 v[74:77], v[70:73], v[210:213], v[74:77]
	v_mfma_f32_16x16x32_bf16 v[62:65], v[54:57], v[218:221], v[62:65]
	v_mfma_f32_16x16x32_bf16 v[58:61], v[70:73], v[218:221], v[58:61]
	v_mfma_f32_16x16x32_bf16 v[46:49], v[54:57], v[226:229], v[46:49]
	v_mfma_f32_16x16x32_bf16 v[42:45], v[70:73], v[226:229], v[42:45]
	v_mfma_f32_16x16x32_bf16 v[14:17], v[54:57], v[234:237], v[14:17]
	v_mfma_f32_16x16x32_bf16 v[10:13], v[70:73], v[234:237], v[10:13]
	s_setprio 0
	s_setprio 1
	v_mfma_f32_16x16x32_bf16 v[18:21], v[170:173], v[198:201], v[18:21]
	v_mfma_f32_16x16x32_bf16 v[70:73], v[174:177], v[210:213], v[18:21]
	v_mfma_f32_16x16x32_bf16 v[18:21], v[190:193], v[198:201], v[22:25]
	v_mfma_f32_16x16x32_bf16 v[66:69], v[194:197], v[210:213], v[18:21]
	v_mfma_f32_16x16x32_bf16 v[18:21], v[170:173], v[214:217], v[26:29]
	v_mfma_f32_16x16x32_bf16 v[54:57], v[174:177], v[218:221], v[18:21]
	v_mfma_f32_16x16x32_bf16 v[18:21], v[190:193], v[214:217], v[30:33]
	v_mfma_f32_16x16x32_bf16 v[50:53], v[194:197], v[218:221], v[18:21]
	v_mfma_f32_16x16x32_bf16 v[18:21], v[170:173], v[222:225], v[38:41]
	v_mfma_f32_16x16x32_bf16 v[38:41], v[174:177], v[226:229], v[18:21]
	v_mfma_f32_16x16x32_bf16 v[18:21], v[190:193], v[222:225], v[34:37]
	v_mfma_f32_16x16x32_bf16 v[6:9], v[170:173], v[230:233], v[6:9]
	v_mfma_f32_16x16x32_bf16 v[2:5], v[190:193], v[230:233], v[2:5]
	v_mfma_f32_16x16x32_bf16 v[34:37], v[194:197], v[226:229], v[18:21]
	v_mfma_f32_16x16x32_bf16 v[6:9], v[174:177], v[234:237], v[6:9]
	v_mfma_f32_16x16x32_bf16 v[2:5], v[194:197], v[234:237], v[2:5]
	s_setprio 0
	s_barrier
	s_add_i32 vcc_hi, vcc_hi, 2
	s_add_u32 s72, s72, 0x100
	s_addc_u32 s73, s73, 0
	s_add_u32 s65, s65, 0x100
	s_addc_u32 vcc_lo, vcc_lo, 0
	s_cmp_gt_u32 vcc_hi, 13
	s_cbranch_scc0 .LBB0_945
	s_and_b64 vcc, exec, s[4:5]
	s_cbranch_vccz .LBB0_948
	s_barrier

; #define PG8_STAGE(bufoff, gbase, voff) do { _Pragma("unroll") for (int _i = 0; _i < 2; ++_i) \
;         __builtin_amdgcn_global_load_lds((const unsigned*)((const char*)(gbase) + (voff)[_i]), (LAS unsigned*)(lds + (bufoff) + ldsw + _i * 8192), 16, 0, 0); } while (0)
; #define PG8_LDA(dst, b, h) do { _Pragma("unroll") for (int m = 0; m < 4; ++m) _Pragma("unroll") for (int k = 0; k < 2; ++k) dst[m][k] = *(const LAS bf16x8*)(lds + PG8_SA(b, h) + aoff + m * 2048 + k * 1024); } while (0)
; #define PG8_LDB(dst, b, h) do { _Pragma("unroll") for (int n = 0; n < 2; ++n) _Pragma("unroll") for (int k = 0; k < 2; ++k) dst[n][k] = *(const LAS bf16x8*)(lds + PG8_SB(b, h) + boff + n * 2048 + k * 1024); } while (0)
; #define PG8_MMA(ai, bj, At, Bt) do { __builtin_amdgcn_s_setprio(1); _Pragma("unroll") for (int m = 0; m < 4; ++m) _Pragma("unroll") for (int n = 0; n < 2; ++n) _Pragma("unroll") for (int k = 0; k < 2; ++k) \
;         acc[ai][bj][m][n] = __builtin_amdgcn_mfma_f32_16x16x32_bf16(Bt[n][k], At[m][k], acc[ai][bj][m][n], 0, 0, 0); __builtin_amdgcn_s_setprio(0); } while (0)
; #define PG8_WAIT_V(n) asm volatile("s_waitcnt vmcnt(" #n ")" ::: "memory")
; #define PG8_WAIT_L(n) asm volatile("s_waitcnt lgkmcnt(" #n ")" ::: "memory")
; #define PG8_BAR __builtin_amdgcn_s_barrier()
; #define PG8_SCHED __builtin_amdgcn_sched_barrier(0)
; template <class Epi>
; __device__ __forceinline__ void gemm_phase(LAS unsigned char* lds, const int tid, const Gemm g, const StaticOrder& S, const Epi& E) {
;     ...
;         for (int t = 0; t < nt; t += 2) {
;             const bool last = (t == nt - 2);
;             const char* a1 = cA + (size_t)(t + 1) * kstep;
;             const char* a2 = last ? nA : cA + (size_t)(t + 2) * kstep; const char* b2 = last ? nB : cB + (size_t)(t + 2) * kstep;
;             const char* a3 = a2 + kstep; const char* b3 = b2 + kstep;
;             PG8_LDB(B0, 0, 0); PG8_LDB(B1, 0, 1); PG8_SCHED; PG8_LDA(At, 0, 0); PG8_STAGE(PG8_SA(1, 1), a1 + hstepA, voffA);
;             PG8_WAIT_V(8); PG8_WAIT_L(0); PG8_BAR; PG8_MMA(0, 0, At, B0); PG8_MMA(0, 1, At, B1); PG8_BAR; PG8_SCHED;
;             PG8_LDA(At, 0, 1); PG8_STAGE(PG8_SB(0, 0), b2, voffB); PG8_STAGE(PG8_SB(0, 1), b2 + hstepB, voffB); PG8_STAGE(PG8_SA(0, 0), a2, voffA);
;             PG8_WAIT_V(8); PG8_WAIT_L(0); PG8_BAR; PG8_MMA(1, 0, At, B0); PG8_MMA(1, 1, At, B1); PG8_BAR; PG8_SCHED;
.LBB0_1284:
	s_add_u32 s2, s66, 0xfff80080
	s_addc_u32 s3, s67, -1
	s_add_i32 vcc_hi, 0, 0x10000
	s_cmp_eq_u32 vcc_lo, 12
	s_cselect_b32 s69, s11, s3
	s_cselect_b32 s68, s88, s2
	v_add_u32_e32 v144, vcc_hi, v171
	s_cselect_b32 s31, s9, s93
	s_cselect_b32 s30, s89, s92
	s_add_i32 s0, 0, 0x14000
	ds_read_b128 v[140:143], v144
	ds_read_b128 v[176:179], v144 offset:1024
	ds_read_b128 v[180:183], v144 offset:2048
	ds_read_b128 v[184:187], v144 offset:3072
	v_add_u32_e32 v144, s0, v171
	ds_read_b128 v[188:191], v144
	ds_read_b128 v[192:195], v144 offset:1024
	ds_read_b128 v[196:199], v144 offset:2048
	ds_read_b128 v[200:203], v144 offset:3072
	v_lshl_add_u64 v[144:145], s[66:67], 0, v[136:137]
	s_add_i32 m0, s71, 0xc000
	s_nop 0
	global_load_lds_dwordx4 v[144:145], off
	v_lshl_add_u64 v[144:145], s[66:67], 0, v[138:139]
	s_add_i32 m0, s71, 0xe000
	s_nop 0
	global_load_lds_dwordx4 v[144:145], off
	ds_read_b128 v[210:213], v174
	ds_read_b128 v[214:217], v174 offset:1024
	ds_read_b128 v[218:221], v174 offset:2048
	ds_read_b128 v[222:225], v174 offset:3072
	ds_read_b128 v[226:229], v174 offset:4096
	ds_read_b128 v[230:233], v174 offset:5120
	ds_read_b128 v[234:237], v174 offset:6144
	ds_read_b128 v[238:241], v174 offset:7168
	s_waitcnt vmcnt(8)
	s_waitcnt lgkmcnt(0)
	s_barrier
	s_setprio 1
	s_waitcnt lgkmcnt(0)
	v_mfma_f32_16x16x32_bf16 v[126:129], v[140:143], v[210:213], v[126:129]
	v_mfma_f32_16x16x32_bf16 v[122:125], v[180:183], v[210:213], v[122:125]
	v_mfma_f32_16x16x32_bf16 v[118:121], v[140:143], v[218:221], v[118:121]
	v_mfma_f32_16x16x32_bf16 v[110:113], v[180:183], v[218:221], v[110:113]
	v_mfma_f32_16x16x32_bf16 v[94:97], v[140:143], v[226:229], v[94:97]
	v_mfma_f32_16x16x32_bf16 v[90:93], v[180:183], v[226:229], v[90:93]
	v_mfma_f32_16x16x32_bf16 v[86:89], v[140:143], v[234:237], v[86:89]
	v_mfma_f32_16x16x32_bf16 v[78:81], v[180:183], v[234:237], v[78:81]
	v_mfma_f32_16x16x32_bf16 v[126:129], v[176:179], v[214:217], v[126:129]
	v_mfma_f32_16x16x32_bf16 v[122:125], v[184:187], v[214:217], v[122:125]
	v_mfma_f32_16x16x32_bf16 v[118:121], v[176:179], v[222:225], v[118:121]
	v_mfma_f32_16x16x32_bf16 v[110:113], v[184:187], v[222:225], v[110:113]
	v_mfma_f32_16x16x32_bf16 v[94:97], v[176:179], v[230:233], v[94:97]
	v_mfma_f32_16x16x32_bf16 v[90:93], v[184:187], v[230:233], v[90:93]
	v_mfma_f32_16x16x32_bf16 v[86:89], v[176:179], v[238:241], v[86:89]
	v_mfma_f32_16x16x32_bf16 v[78:81], v[184:187], v[238:241], v[78:81]
	s_setprio 0
	s_setprio 1
	v_mfma_f32_16x16x32_bf16 v[114:117], v[188:191], v[210:213], v[114:117]
	v_mfma_f32_16x16x32_bf16 v[106:109], v[196:199], v[210:213], v[106:109]
	v_mfma_f32_16x16x32_bf16 v[102:105], v[188:191], v[218:221], v[102:105]
	v_mfma_f32_16x16x32_bf16 v[98:101], v[196:199], v[218:221], v[98:101]
	v_mfma_f32_16x16x32_bf16 v[82:85], v[188:191], v[226:229], v[82:85]
	v_mfma_f32_16x16x32_bf16 v[74:77], v[196:199], v[226:229], v[74:77]
	v_mfma_f32_16x16x32_bf16 v[70:73], v[188:191], v[234:237], v[70:73]
	v_mfma_f32_16x16x32_bf16 v[66:69], v[196:199], v[234:237], v[66:69]
	v_mfma_f32_16x16x32_bf16 v[114:117], v[192:195], v[214:217], v[114:117]
	v_mfma_f32_16x16x32_bf16 v[106:109], v[200:203], v[214:217], v[106:109]
	v_mfma_f32_16x16x32_bf16 v[102:105], v[192:195], v[222:225], v[102:105]
	v_mfma_f32_16x16x32_bf16 v[98:101], v[200:203], v[222:225], v[98:101]
	v_mfma_f32_16x16x32_bf16 v[82:85], v[192:195], v[230:233], v[82:85]
	v_mfma_f32_16x16x32_bf16 v[74:77], v[200:203], v[230:233], v[74:77]
	v_mfma_f32_16x16x32_bf16 v[70:73], v[192:195], v[238:241], v[70:73]
	v_mfma_f32_16x16x32_bf16 v[66:69], v[200:203], v[238:241], v[66:69]
	s_setprio 0
	s_barrier
	s_add_i32 s1, vcc_hi, s28
	v_lshl_add_u64 v[144:145], s[30:31], 0, v[0:1]
	s_mov_b32 m0, s1
	s_nop 0
	global_load_lds_dwordx4 v[144:145], off
	s_add_i32 m0, s1, 0x2000
	s_add_u32 s2, s30, 0x40000
	v_lshl_add_u64 v[162:163], s[30:31], 0, v[130:131]
	s_addc_u32 s3, s31, 0
	s_add_i32 s0, s0, s28
	global_load_lds_dwordx4 v[162:163], off
	v_lshl_add_u64 v[164:165], s[2:3], 0, v[0:1]
	s_mov_b32 m0, s0
	v_lshl_add_u64 v[206:207], s[68:69], 0, v[132:133]
	global_load_lds_dwordx4 v[164:165], off
	v_lshl_add_u64 v[164:165], s[2:3], 0, v[130:131]
	s_add_i32 m0, s0, 0x2000
	s_nop 0
	global_load_lds_dwordx4 v[164:165], off
	v_lshl_add_u64 v[164:165], s[68:69], 0, v[134:135]
	s_mov_b32 m0, s71
	s_nop 0
	global_load_lds_dwordx4 v[164:165], off
	s_mov_b32 m0, s72
	s_nop 0
	global_load_lds_dwordx4 v[206:207], off
	ds_read_b128 v[210:213], v174 offset:16384
	ds_read_b128 v[214:217], v174 offset:17408
	ds_read_b128 v[218:221], v174 offset:18432
	ds_read_b128 v[222:225], v174 offset:19456
	ds_read_b128 v[226:229], v174 offset:20480
	ds_read_b128 v[230:233], v174 offset:21504
	ds_read_b128 v[234:237], v174 offset:22528
	ds_read_b128 v[238:241], v174 offset:23552
	s_waitcnt vmcnt(8)
	s_waitcnt lgkmcnt(0)
	s_barrier
; #define PG8_STAGE(bufoff, gbase, voff) do { _Pragma("unroll") for (int _i = 0; _i < 2; ++_i) \
;         __builtin_amdgcn_global_load_lds((const unsigned*)((const char*)(gbase) + (voff)[_i]), (LAS unsigned*)(lds + (bufoff) + ldsw + _i * 8192), 16, 0, 0); } while (0)
; #define PG8_LDA(dst, b, h) do { _Pragma("unroll") for (int m = 0; m < 4; ++m) _Pragma("unroll") for (int k = 0; k < 2; ++k) dst[m][k] = *(const LAS bf16x8*)(lds + PG8_SA(b, h) + aoff + m * 2048 + k * 1024); } while (0)
; #define PG8_LDB(dst, b, h) do { _Pragma("unroll") for (int n = 0; n < 2; ++n) _Pragma("unroll") for (int k = 0; k < 2; ++k) dst[n][k] = *(const LAS bf16x8*)(lds + PG8_SB(b, h) + boff + n * 2048 + k * 1024); } while (0)
; #define PG8_MMA(ai, bj, At, Bt) do { __builtin_amdgcn_s_setprio(1); _Pragma("unroll") for (int m = 0; m < 4; ++m) _Pragma("unroll") for (int n = 0; n < 2; ++n) _Pragma("unroll") for (int k = 0; k < 2; ++k) \
;         acc[ai][bj][m][n] = __builtin_amdgcn_mfma_f32_16x16x32_bf16(Bt[n][k], At[m][k], acc[ai][bj][m][n], 0, 0, 0); __builtin_amdgcn_s_setprio(0); } while (0)
; #define PG8_WAIT_V(n) asm volatile("s_waitcnt vmcnt(" #n ")" ::: "memory")
; #define PG8_WAIT_L(n) asm volatile("s_waitcnt lgkmcnt(" #n ")" ::: "memory")
; #define PG8_BAR __builtin_amdgcn_s_barrier()
; #define PG8_SCHED __builtin_amdgcn_sched_barrier(0)
; template <class Epi>
; __device__ __forceinline__ void gemm_phase(LAS unsigned char* lds, const int tid, const Gemm g, const StaticOrder& S, const Epi& E) {
;     ...
;             PG8_WAIT_V(8); PG8_WAIT_L(0); PG8_BAR; PG8_MMA(1, 0, At, B0); PG8_MMA(1, 1, At, B1); PG8_BAR; PG8_SCHED;
;             PG8_LDB(B0, 1, 0); PG8_LDB(B1, 1, 1); PG8_SCHED; PG8_LDA(At, 1, 0); PG8_STAGE(PG8_SA(0, 1), a2 + hstepA, voffA);
;             PG8_WAIT_V(8); PG8_WAIT_L(0); PG8_BAR; PG8_MMA(0, 0, At, B0); PG8_MMA(0, 1, At, B1); PG8_BAR; PG8_SCHED;
;             PG8_LDA(At, 1, 1); PG8_STAGE(PG8_SB(1, 0), b3, voffB); PG8_STAGE(PG8_SB(1, 1), b3 + hstepB, voffB); PG8_STAGE(PG8_SA(1, 0), a3, voffA);
;             PG8_WAIT_V(8); PG8_WAIT_L(0); PG8_BAR; PG8_MMA(1, 0, At, B0); PG8_MMA(1, 1, At, B1); PG8_BAR; PG8_SCHED;
	s_setprio 1
	s_waitcnt lgkmcnt(0)
	v_mfma_f32_16x16x32_bf16 v[62:65], v[140:143], v[210:213], v[62:65]
	v_mfma_f32_16x16x32_bf16 v[58:61], v[180:183], v[210:213], v[58:61]
	v_mfma_f32_16x16x32_bf16 v[54:57], v[140:143], v[218:221], v[54:57]
	v_mfma_f32_16x16x32_bf16 v[46:49], v[180:183], v[218:221], v[46:49]
	v_mfma_f32_16x16x32_bf16 v[30:33], v[140:143], v[226:229], v[30:33]
	v_mfma_f32_16x16x32_bf16 v[26:29], v[180:183], v[226:229], v[26:29]
	v_mfma_f32_16x16x32_bf16 v[22:25], v[140:143], v[234:237], v[22:25]
	v_mfma_f32_16x16x32_bf16 v[14:17], v[180:183], v[234:237], v[14:17]
	v_mfma_f32_16x16x32_bf16 v[62:65], v[176:179], v[214:217], v[62:65]
	v_mfma_f32_16x16x32_bf16 v[58:61], v[184:187], v[214:217], v[58:61]
	v_mfma_f32_16x16x32_bf16 v[54:57], v[176:179], v[222:225], v[54:57]
	v_mfma_f32_16x16x32_bf16 v[46:49], v[184:187], v[222:225], v[46:49]
	v_mfma_f32_16x16x32_bf16 v[30:33], v[176:179], v[230:233], v[30:33]
	v_mfma_f32_16x16x32_bf16 v[26:29], v[184:187], v[230:233], v[26:29]
	v_mfma_f32_16x16x32_bf16 v[22:25], v[176:179], v[238:241], v[22:25]
	v_mfma_f32_16x16x32_bf16 v[14:17], v[184:187], v[238:241], v[14:17]
	s_setprio 0
	s_setprio 1
	v_mfma_f32_16x16x32_bf16 v[50:53], v[188:191], v[210:213], v[50:53]
	v_mfma_f32_16x16x32_bf16 v[42:45], v[196:199], v[210:213], v[42:45]
	v_mfma_f32_16x16x32_bf16 v[38:41], v[188:191], v[218:221], v[38:41]
	v_mfma_f32_16x16x32_bf16 v[34:37], v[196:199], v[218:221], v[34:37]
	v_mfma_f32_16x16x32_bf16 v[18:21], v[188:191], v[226:229], v[18:21]
	v_mfma_f32_16x16x32_bf16 v[10:13], v[196:199], v[226:229], v[10:13]
	v_mfma_f32_16x16x32_bf16 v[6:9], v[188:191], v[234:237], v[6:9]
	v_mfma_f32_16x16x32_bf16 v[2:5], v[196:199], v[234:237], v[2:5]
	v_mfma_f32_16x16x32_bf16 v[50:53], v[192:195], v[214:217], v[50:53]
	v_mfma_f32_16x16x32_bf16 v[42:45], v[200:203], v[214:217], v[42:45]
	v_mfma_f32_16x16x32_bf16 v[38:41], v[192:195], v[222:225], v[38:41]
	v_mfma_f32_16x16x32_bf16 v[34:37], v[200:203], v[222:225], v[34:37]
	v_mfma_f32_16x16x32_bf16 v[18:21], v[192:195], v[230:233], v[18:21]
	v_mfma_f32_16x16x32_bf16 v[10:13], v[200:203], v[230:233], v[10:13]
	v_mfma_f32_16x16x32_bf16 v[6:9], v[192:195], v[238:241], v[6:9]
	v_mfma_f32_16x16x32_bf16 v[2:5], v[200:203], v[238:241], v[2:5]
	s_setprio 0
	s_barrier
	s_add_i32 s0, 0, 0x18000
	v_add_u32_e32 v175, s0, v171
	s_add_i32 s1, 0, 0x1c000
	ds_read_b128 v[140:143], v175
	ds_read_b128 v[176:179], v175 offset:1024
	ds_read_b128 v[180:183], v175 offset:2048
	ds_read_b128 v[184:187], v175 offset:3072
	v_add_u32_e32 v175, s1, v171
	ds_read_b128 v[188:191], v175
	ds_read_b128 v[192:195], v175 offset:1024
	ds_read_b128 v[196:199], v175 offset:2048
	ds_read_b128 v[200:203], v175 offset:3072
	s_add_u32 s2, s68, 0x80000
	s_addc_u32 s3, s69, 0
	s_mov_b32 m0, s73
	v_lshl_add_u64 v[242:243], s[2:3], 0, v[134:135]
	global_load_lds_dwordx4 v[242:243], off
	v_lshl_add_u64 v[242:243], s[2:3], 0, v[132:133]
	s_mov_b32 m0, s74
	s_nop 0
	global_load_lds_dwordx4 v[242:243], off
	ds_read_b128 v[210:213], v174 offset:32768
	ds_read_b128 v[214:217], v174 offset:33792
	ds_read_b128 v[218:221], v174 offset:34816
	ds_read_b128 v[222:225], v174 offset:35840
	ds_read_b128 v[226:229], v174 offset:36864
	ds_read_b128 v[230:233], v174 offset:37888
	ds_read_b128 v[234:237], v174 offset:38912
	ds_read_b128 v[238:241], v174 offset:39936
	s_waitcnt vmcnt(8)
	s_waitcnt lgkmcnt(0)
	s_barrier
	s_setprio 1
	s_waitcnt lgkmcnt(0)
	v_mfma_f32_16x16x32_bf16 v[126:129], v[140:143], v[210:213], v[126:129]
	v_mfma_f32_16x16x32_bf16 v[122:125], v[180:183], v[210:213], v[122:125]
	v_mfma_f32_16x16x32_bf16 v[118:121], v[140:143], v[218:221], v[118:121]
	v_mfma_f32_16x16x32_bf16 v[110:113], v[180:183], v[218:221], v[110:113]
	v_mfma_f32_16x16x32_bf16 v[94:97], v[140:143], v[226:229], v[94:97]
	v_mfma_f32_16x16x32_bf16 v[90:93], v[180:183], v[226:229], v[90:93]
	v_mfma_f32_16x16x32_bf16 v[86:89], v[140:143], v[234:237], v[86:89]
	v_mfma_f32_16x16x32_bf16 v[78:81], v[180:183], v[234:237], v[78:81]
	v_mfma_f32_16x16x32_bf16 v[126:129], v[176:179], v[214:217], v[126:129]
	v_mfma_f32_16x16x32_bf16 v[122:125], v[184:187], v[214:217], v[122:125]
	v_mfma_f32_16x16x32_bf16 v[118:121], v[176:179], v[222:225], v[118:121]
	v_mfma_f32_16x16x32_bf16 v[110:113], v[184:187], v[222:225], v[110:113]
	v_mfma_f32_16x16x32_bf16 v[94:97], v[176:179], v[230:233], v[94:97]
	v_mfma_f32_16x16x32_bf16 v[90:93], v[184:187], v[230:233], v[90:93]
	v_mfma_f32_16x16x32_bf16 v[86:89], v[176:179], v[238:241], v[86:89]
	v_mfma_f32_16x16x32_bf16 v[78:81], v[184:187], v[238:241], v[78:81]
	s_setprio 0
	s_setprio 1
	v_mfma_f32_16x16x32_bf16 v[114:117], v[188:191], v[210:213], v[114:117]
	v_mfma_f32_16x16x32_bf16 v[106:109], v[196:199], v[210:213], v[106:109]
	v_mfma_f32_16x16x32_bf16 v[102:105], v[188:191], v[218:221], v[102:105]
	v_mfma_f32_16x16x32_bf16 v[98:101], v[196:199], v[218:221], v[98:101]
	v_mfma_f32_16x16x32_bf16 v[82:85], v[188:191], v[226:229], v[82:85]
	v_mfma_f32_16x16x32_bf16 v[74:77], v[196:199], v[226:229], v[74:77]
	v_mfma_f32_16x16x32_bf16 v[70:73], v[188:191], v[234:237], v[70:73]
	v_mfma_f32_16x16x32_bf16 v[66:69], v[196:199], v[234:237], v[66:69]
	v_mfma_f32_16x16x32_bf16 v[114:117], v[192:195], v[214:217], v[114:117]
	v_mfma_f32_16x16x32_bf16 v[106:109], v[200:203], v[214:217], v[106:109]
	v_mfma_f32_16x16x32_bf16 v[102:105], v[192:195], v[222:225], v[102:105]
	v_mfma_f32_16x16x32_bf16 v[98:101], v[200:203], v[222:225], v[98:101]
	v_mfma_f32_16x16x32_bf16 v[82:85], v[192:195], v[230:233], v[82:85]
	v_mfma_f32_16x16x32_bf16 v[74:77], v[200:203], v[230:233], v[74:77]
	v_mfma_f32_16x16x32_bf16 v[70:73], v[192:195], v[238:241], v[70:73]
	v_mfma_f32_16x16x32_bf16 v[66:69], v[200:203], v[238:241], v[66:69]
	s_setprio 0
	s_barrier
; #define PG8_STAGE(bufoff, gbase, voff) do { _Pragma("unroll") for (int _i = 0; _i < 2; ++_i) \
;         __builtin_amdgcn_global_load_lds((const unsigned*)((const char*)(gbase) + (voff)[_i]), (LAS unsigned*)(lds + (bufoff) + ldsw + _i * 8192), 16, 0, 0); } while (0)
; #define PG8_LDA(dst, b, h) do { _Pragma("unroll") for (int m = 0; m < 4; ++m) _Pragma("unroll") for (int k = 0; k < 2; ++k) dst[m][k] = *(const LAS bf16x8*)(lds + PG8_SA(b, h) + aoff + m * 2048 + k * 1024); } while (0)
; #define PG8_MMA(ai, bj, At, Bt) do { __builtin_amdgcn_s_setprio(1); _Pragma("unroll") for (int m = 0; m < 4; ++m) _Pragma("unroll") for (int n = 0; n < 2; ++n) _Pragma("unroll") for (int k = 0; k < 2; ++k) \
;         acc[ai][bj][m][n] = __builtin_amdgcn_mfma_f32_16x16x32_bf16(Bt[n][k], At[m][k], acc[ai][bj][m][n], 0, 0, 0); __builtin_amdgcn_s_setprio(0); } while (0)
; #define PG8_WAIT_V(n) asm volatile("s_waitcnt vmcnt(" #n ")" ::: "memory")
; #define PG8_WAIT_L(n) asm volatile("s_waitcnt lgkmcnt(" #n ")" ::: "memory")
; #define PG8_BAR __builtin_amdgcn_s_barrier()
; #define PG8_SCHED __builtin_amdgcn_sched_barrier(0)
; template <class Epi>
; __device__ __forceinline__ void gemm_phase(LAS unsigned char* lds, const int tid, const Gemm g, const StaticOrder& S, const Epi& E) {
;     ...
;             PG8_LDA(At, 1, 1); PG8_STAGE(PG8_SB(1, 0), b3, voffB); PG8_STAGE(PG8_SB(1, 1), b3 + hstepB, voffB); PG8_STAGE(PG8_SA(1, 0), a3, voffA);
;             PG8_WAIT_V(8); PG8_WAIT_L(0); PG8_BAR; PG8_MMA(1, 0, At, B0); PG8_MMA(1, 1, At, B1); PG8_BAR; PG8_SCHED;
;         }
;         if (wr == 0) PG8_BAR;
	s_add_i32 s0, s0, s28
	v_lshl_add_u64 v[144:145], v[144:145], 0, s[36:37]
	s_mov_b32 m0, s0
	s_nop 0
	global_load_lds_dwordx4 v[144:145], off
	s_add_i32 m0, s0, 0x2000
	s_add_u32 s2, s30, 0x40080
	v_lshl_add_u64 v[144:145], v[162:163], 0, s[36:37]
	s_addc_u32 s3, s31, 0
	s_add_i32 s0, s1, s28
	global_load_lds_dwordx4 v[144:145], off
	v_lshl_add_u64 v[144:145], s[2:3], 0, v[0:1]
	s_mov_b32 m0, s0
	s_nop 0
	global_load_lds_dwordx4 v[144:145], off
	v_lshl_add_u64 v[144:145], s[2:3], 0, v[130:131]
	s_add_i32 m0, s0, 0x2000
	s_nop 0
	global_load_lds_dwordx4 v[144:145], off
	v_lshl_add_u64 v[144:145], v[164:165], 0, s[36:37]
	s_mov_b32 m0, s75
	s_nop 0
	global_load_lds_dwordx4 v[144:145], off
	v_lshl_add_u64 v[144:145], v[206:207], 0, s[36:37]
	s_mov_b32 m0, s76
	s_nop 0
	global_load_lds_dwordx4 v[144:145], off
	ds_read_b128 v[210:213], v174 offset:49152
	ds_read_b128 v[214:217], v174 offset:50176
	ds_read_b128 v[218:221], v174 offset:51200
	ds_read_b128 v[222:225], v174 offset:52224
	ds_read_b128 v[226:229], v174 offset:53248
	ds_read_b128 v[230:233], v174 offset:54272
	ds_read_b128 v[234:237], v174 offset:55296
	ds_read_b128 v[238:241], v174 offset:56320
	s_waitcnt vmcnt(8)
	s_waitcnt lgkmcnt(0)
	s_barrier
	s_setprio 1
	s_waitcnt lgkmcnt(0)
	v_mfma_f32_16x16x32_bf16 v[62:65], v[140:143], v[210:213], v[62:65]
	v_mfma_f32_16x16x32_bf16 v[58:61], v[180:183], v[210:213], v[58:61]
	v_mfma_f32_16x16x32_bf16 v[54:57], v[140:143], v[218:221], v[54:57]
	v_mfma_f32_16x16x32_bf16 v[46:49], v[180:183], v[218:221], v[46:49]
	v_mfma_f32_16x16x32_bf16 v[30:33], v[140:143], v[226:229], v[30:33]
	v_mfma_f32_16x16x32_bf16 v[26:29], v[180:183], v[226:229], v[26:29]
	v_mfma_f32_16x16x32_bf16 v[22:25], v[140:143], v[234:237], v[22:25]
	v_mfma_f32_16x16x32_bf16 v[14:17], v[180:183], v[234:237], v[14:17]
	v_mfma_f32_16x16x32_bf16 v[62:65], v[176:179], v[214:217], v[62:65]
	v_mfma_f32_16x16x32_bf16 v[58:61], v[184:187], v[214:217], v[58:61]
	v_mfma_f32_16x16x32_bf16 v[54:57], v[176:179], v[222:225], v[54:57]
	v_mfma_f32_16x16x32_bf16 v[46:49], v[184:187], v[222:225], v[46:49]
	v_mfma_f32_16x16x32_bf16 v[30:33], v[176:179], v[230:233], v[30:33]
	v_mfma_f32_16x16x32_bf16 v[26:29], v[184:187], v[230:233], v[26:29]
	v_mfma_f32_16x16x32_bf16 v[22:25], v[176:179], v[238:241], v[22:25]
	v_mfma_f32_16x16x32_bf16 v[14:17], v[184:187], v[238:241], v[14:17]
	s_setprio 0
	s_setprio 1
	v_mfma_f32_16x16x32_bf16 v[50:53], v[188:191], v[210:213], v[50:53]
	v_mfma_f32_16x16x32_bf16 v[42:45], v[196:199], v[210:213], v[42:45]
	v_mfma_f32_16x16x32_bf16 v[38:41], v[188:191], v[218:221], v[38:41]
	v_mfma_f32_16x16x32_bf16 v[34:37], v[196:199], v[218:221], v[34:37]
	v_mfma_f32_16x16x32_bf16 v[18:21], v[188:191], v[226:229], v[18:21]
	v_mfma_f32_16x16x32_bf16 v[10:13], v[196:199], v[226:229], v[10:13]
	v_mfma_f32_16x16x32_bf16 v[6:9], v[188:191], v[234:237], v[6:9]
	v_mfma_f32_16x16x32_bf16 v[2:5], v[196:199], v[234:237], v[2:5]
	v_mfma_f32_16x16x32_bf16 v[50:53], v[192:195], v[214:217], v[50:53]
	v_mfma_f32_16x16x32_bf16 v[42:45], v[200:203], v[214:217], v[42:45]
	v_mfma_f32_16x16x32_bf16 v[38:41], v[192:195], v[222:225], v[38:41]
	v_mfma_f32_16x16x32_bf16 v[34:37], v[200:203], v[222:225], v[34:37]
	v_mfma_f32_16x16x32_bf16 v[18:21], v[192:195], v[230:233], v[18:21]
	v_mfma_f32_16x16x32_bf16 v[10:13], v[200:203], v[230:233], v[10:13]
	v_mfma_f32_16x16x32_bf16 v[6:9], v[192:195], v[238:241], v[6:9]
	v_mfma_f32_16x16x32_bf16 v[2:5], v[200:203], v[238:241], v[2:5]
	s_setprio 0
	s_barrier
	s_add_i32 vcc_lo, vcc_lo, 2
	s_add_u32 s66, s66, 0x100
	s_addc_u32 s67, s67, 0
	s_add_u32 s92, s92, 0x100
	s_addc_u32 s93, s93, 0
	s_cmp_gt_u32 vcc_lo, 13
	s_cbranch_scc0 .LBB0_1284
	s_and_b64 vcc, exec, s[6:7]
	s_mov_b32 s92, 0x2c000
	s_mov_b32 s93, 0x2e000
	s_cbranch_vccz .LBB0_1287
	s_barrier

; #define PG8_STAGE(bufoff, gbase, voff) do { _Pragma("unroll") for (int _i = 0; _i < 2; ++_i) \
;         __builtin_amdgcn_global_load_lds((const unsigned*)((const char*)(gbase) + (voff)[_i]), (LAS unsigned*)(lds + (bufoff) + ldsw + _i * 8192), 16, 0, 0); } while (0)
; #define PG8_LDA(dst, b, h) do { _Pragma("unroll") for (int m = 0; m < 4; ++m) _Pragma("unroll") for (int k = 0; k < 2; ++k) dst[m][k] = *(const LAS bf16x8*)(lds + PG8_SA(b, h) + aoff + m * 2048 + k * 1024); } while (0)
; #define PG8_LDB(dst, b, h) do { _Pragma("unroll") for (int n = 0; n < 2; ++n) _Pragma("unroll") for (int k = 0; k < 2; ++k) dst[n][k] = *(const LAS bf16x8*)(lds + PG8_SB(b, h) + boff + n * 2048 + k * 1024); } while (0)
; #define PG8_MMA(ai, bj, At, Bt) do { __builtin_amdgcn_s_setprio(1); _Pragma("unroll") for (int m = 0; m < 4; ++m) _Pragma("unroll") for (int n = 0; n < 2; ++n) _Pragma("unroll") for (int k = 0; k < 2; ++k) \
;         acc[ai][bj][m][n] = __builtin_amdgcn_mfma_f32_16x16x32_bf16(Bt[n][k], At[m][k], acc[ai][bj][m][n], 0, 0, 0); __builtin_amdgcn_s_setprio(0); } while (0)
; #define PG8_WAIT_V(n) asm volatile("s_waitcnt vmcnt(" #n ")" ::: "memory")
; #define PG8_WAIT_L(n) asm volatile("s_waitcnt lgkmcnt(" #n ")" ::: "memory")
; #define PG8_BAR __builtin_amdgcn_s_barrier()
; #define PG8_SCHED __builtin_amdgcn_sched_barrier(0)
; template <class Epi>
; __device__ __forceinline__ void gemm_phase(LAS unsigned char* lds, const int tid, const Gemm g, const StaticOrder& S, const Epi& E) {
;     ...
;         for (int t = 0; t < nt; t += 2) {
;             const bool last = (t == nt - 2);
;             const char* a1 = cA + (size_t)(t + 1) * kstep;
;             const char* a2 = last ? nA : cA + (size_t)(t + 2) * kstep; const char* b2 = last ? nB : cB + (size_t)(t + 2) * kstep;
;             const char* a3 = a2 + kstep; const char* b3 = b2 + kstep;
;             PG8_LDB(B0, 0, 0); PG8_LDB(B1, 0, 1); PG8_SCHED; PG8_LDA(At, 0, 0); PG8_STAGE(PG8_SA(1, 1), a1 + hstepA, voffA);
;             PG8_WAIT_V(8); PG8_WAIT_L(0); PG8_BAR; PG8_MMA(0, 0, At, B0); PG8_MMA(0, 1, At, B1); PG8_BAR; PG8_SCHED;
;             PG8_LDA(At, 0, 1); PG8_STAGE(PG8_SB(0, 0), b2, voffB); PG8_STAGE(PG8_SB(0, 1), b2 + hstepB, voffB); PG8_STAGE(PG8_SA(0, 0), a2, voffA);
;             PG8_WAIT_V(8); PG8_WAIT_L(0); PG8_BAR; PG8_MMA(1, 0, At, B0); PG8_MMA(1, 1, At, B1); PG8_BAR; PG8_SCHED;
.LBB0_1333:
	s_add_u32 s0, s66, 0xfff80080
	s_addc_u32 s1, s67, -1
	s_add_i32 s2, 0, 0x10000
	s_cmp_eq_u32 vcc_lo, 12
	s_cselect_b32 s69, s11, s1
	s_cselect_b32 s68, s88, s0
	s_cselect_b32 s31, s9, s93
	s_cselect_b32 s30, s89, s92
	s_add_i32 s0, 0, 0x14000
	v_add_u32_e32 v142, s2, v189
	v_add_u32_e32 v162, s0, v189
	ds_read_b128 v[130:133], v142
	ds_read_b128 v[134:137], v142 offset:1024
	ds_read_b128 v[138:141], v142 offset:2048
	ds_read_b128 v[142:145], v142 offset:3072
	ds_read_b128 v[158:161], v162
	ds_read_b128 v[192:195], v162 offset:1024
	ds_read_b128 v[196:199], v162 offset:2048
	ds_read_b128 v[200:203], v162 offset:3072
	v_lshl_add_u64 v[162:163], s[66:67], 0, v[154:155]
	s_add_i32 m0, s71, 0xc000
	s_nop 0
	global_load_lds_dwordx4 v[162:163], off
	v_lshl_add_u64 v[162:163], s[66:67], 0, v[156:157]
	s_add_i32 m0, s71, 0xe000
	s_nop 0
	global_load_lds_dwordx4 v[162:163], off
	ds_read_b128 v[210:213], v191
	ds_read_b128 v[214:217], v191 offset:1024
	ds_read_b128 v[218:221], v191 offset:2048
	ds_read_b128 v[222:225], v191 offset:3072
	ds_read_b128 v[226:229], v191 offset:4096
	ds_read_b128 v[230:233], v191 offset:5120
	ds_read_b128 v[234:237], v191 offset:6144
	ds_read_b128 v[238:241], v191 offset:7168
	s_waitcnt vmcnt(8)
	s_waitcnt lgkmcnt(0)
	s_barrier
	s_setprio 1
	s_waitcnt lgkmcnt(0)
	v_mfma_f32_16x16x32_bf16 v[126:129], v[130:133], v[210:213], v[126:129]
	v_mfma_f32_16x16x32_bf16 v[122:125], v[138:141], v[210:213], v[122:125]
	v_mfma_f32_16x16x32_bf16 v[110:113], v[130:133], v[218:221], v[110:113]
	v_mfma_f32_16x16x32_bf16 v[106:109], v[138:141], v[218:221], v[106:109]
	v_mfma_f32_16x16x32_bf16 v[94:97], v[130:133], v[226:229], v[94:97]
	v_mfma_f32_16x16x32_bf16 v[90:93], v[138:141], v[226:229], v[90:93]
	v_mfma_f32_16x16x32_bf16 v[78:81], v[130:133], v[234:237], v[78:81]
	v_mfma_f32_16x16x32_bf16 v[74:77], v[138:141], v[234:237], v[74:77]
	v_mfma_f32_16x16x32_bf16 v[126:129], v[134:137], v[214:217], v[126:129]
	v_mfma_f32_16x16x32_bf16 v[122:125], v[142:145], v[214:217], v[122:125]
	v_mfma_f32_16x16x32_bf16 v[110:113], v[134:137], v[222:225], v[110:113]
	v_mfma_f32_16x16x32_bf16 v[106:109], v[142:145], v[222:225], v[106:109]
	v_mfma_f32_16x16x32_bf16 v[94:97], v[134:137], v[230:233], v[94:97]
	v_mfma_f32_16x16x32_bf16 v[90:93], v[142:145], v[230:233], v[90:93]
	v_mfma_f32_16x16x32_bf16 v[78:81], v[134:137], v[238:241], v[78:81]
	v_mfma_f32_16x16x32_bf16 v[74:77], v[142:145], v[238:241], v[74:77]
	s_setprio 0
	s_setprio 1
	v_mfma_f32_16x16x32_bf16 v[118:121], v[158:161], v[210:213], v[118:121]
	v_mfma_f32_16x16x32_bf16 v[114:117], v[196:199], v[210:213], v[114:117]
	v_mfma_f32_16x16x32_bf16 v[102:105], v[158:161], v[218:221], v[102:105]
	v_mfma_f32_16x16x32_bf16 v[98:101], v[196:199], v[218:221], v[98:101]
	v_mfma_f32_16x16x32_bf16 v[86:89], v[158:161], v[226:229], v[86:89]
	v_mfma_f32_16x16x32_bf16 v[82:85], v[196:199], v[226:229], v[82:85]
	v_mfma_f32_16x16x32_bf16 v[70:73], v[158:161], v[234:237], v[70:73]
	v_mfma_f32_16x16x32_bf16 v[66:69], v[196:199], v[234:237], v[66:69]
	v_mfma_f32_16x16x32_bf16 v[118:121], v[192:195], v[214:217], v[118:121]
	v_mfma_f32_16x16x32_bf16 v[114:117], v[200:203], v[214:217], v[114:117]
	v_mfma_f32_16x16x32_bf16 v[102:105], v[192:195], v[222:225], v[102:105]
	v_mfma_f32_16x16x32_bf16 v[98:101], v[200:203], v[222:225], v[98:101]
	v_mfma_f32_16x16x32_bf16 v[86:89], v[192:195], v[230:233], v[86:89]
	v_mfma_f32_16x16x32_bf16 v[82:85], v[200:203], v[230:233], v[82:85]
	v_mfma_f32_16x16x32_bf16 v[70:73], v[192:195], v[238:241], v[70:73]
	v_mfma_f32_16x16x32_bf16 v[66:69], v[200:203], v[238:241], v[66:69]
	s_setprio 0
	s_barrier
	s_add_i32 s1, s2, s28
	v_lshl_add_u64 v[162:163], s[30:31], 0, v[0:1]
	s_mov_b32 m0, s1
	s_nop 0
	global_load_lds_dwordx4 v[162:163], off
	s_add_i32 m0, s1, 0x2000
	s_add_u32 s2, s30, 0x40000
	v_lshl_add_u64 v[164:165], s[30:31], 0, v[148:149]
	s_addc_u32 s3, s31, 0
	s_add_i32 s0, s0, s28
	global_load_lds_dwordx4 v[164:165], off
	v_lshl_add_u64 v[170:171], s[2:3], 0, v[0:1]
	s_mov_b32 m0, s0
	v_lshl_add_u64 v[206:207], s[68:69], 0, v[150:151]
	global_load_lds_dwordx4 v[170:171], off
	v_lshl_add_u64 v[170:171], s[2:3], 0, v[148:149]
	s_add_i32 m0, s0, 0x2000
	s_nop 0
	global_load_lds_dwordx4 v[170:171], off
	v_lshl_add_u64 v[170:171], s[68:69], 0, v[152:153]
	s_mov_b32 m0, s71
	s_nop 0
	global_load_lds_dwordx4 v[170:171], off
	s_mov_b32 m0, s72
	s_nop 0
	global_load_lds_dwordx4 v[206:207], off
	ds_read_b128 v[210:213], v191 offset:16384
	ds_read_b128 v[214:217], v191 offset:17408
	ds_read_b128 v[218:221], v191 offset:18432
	ds_read_b128 v[222:225], v191 offset:19456
	ds_read_b128 v[226:229], v191 offset:20480
	ds_read_b128 v[230:233], v191 offset:21504
	ds_read_b128 v[234:237], v191 offset:22528
	ds_read_b128 v[238:241], v191 offset:23552
	s_waitcnt vmcnt(8)
	s_waitcnt lgkmcnt(0)
	s_barrier
; #define PG8_STAGE(bufoff, gbase, voff) do { _Pragma("unroll") for (int _i = 0; _i < 2; ++_i) \
;         __builtin_amdgcn_global_load_lds((const unsigned*)((const char*)(gbase) + (voff)[_i]), (LAS unsigned*)(lds + (bufoff) + ldsw + _i * 8192), 16, 0, 0); } while (0)
; #define PG8_LDA(dst, b, h) do { _Pragma("unroll") for (int m = 0; m < 4; ++m) _Pragma("unroll") for (int k = 0; k < 2; ++k) dst[m][k] = *(const LAS bf16x8*)(lds + PG8_SA(b, h) + aoff + m * 2048 + k * 1024); } while (0)
; #define PG8_LDB(dst, b, h) do { _Pragma("unroll") for (int n = 0; n < 2; ++n) _Pragma("unroll") for (int k = 0; k < 2; ++k) dst[n][k] = *(const LAS bf16x8*)(lds + PG8_SB(b, h) + boff + n * 2048 + k * 1024); } while (0)
; #define PG8_MMA(ai, bj, At, Bt) do { __builtin_amdgcn_s_setprio(1); _Pragma("unroll") for (int m = 0; m < 4; ++m) _Pragma("unroll") for (int n = 0; n < 2; ++n) _Pragma("unroll") for (int k = 0; k < 2; ++k) \
;         acc[ai][bj][m][n] = __builtin_amdgcn_mfma_f32_16x16x32_bf16(Bt[n][k], At[m][k], acc[ai][bj][m][n], 0, 0, 0); __builtin_amdgcn_s_setprio(0); } while (0)
; #define PG8_WAIT_V(n) asm volatile("s_waitcnt vmcnt(" #n ")" ::: "memory")
; #define PG8_WAIT_L(n) asm volatile("s_waitcnt lgkmcnt(" #n ")" ::: "memory")
; #define PG8_BAR __builtin_amdgcn_s_barrier()
; #define PG8_SCHED __builtin_amdgcn_sched_barrier(0)
; template <class Epi>
; __device__ __forceinline__ void gemm_phase(LAS unsigned char* lds, const int tid, const Gemm g, const StaticOrder& S, const Epi& E) {
;     ...
;             PG8_WAIT_V(8); PG8_WAIT_L(0); PG8_BAR; PG8_MMA(1, 0, At, B0); PG8_MMA(1, 1, At, B1); PG8_BAR; PG8_SCHED;
;             PG8_LDB(B0, 1, 0); PG8_LDB(B1, 1, 1); PG8_SCHED; PG8_LDA(At, 1, 0); PG8_STAGE(PG8_SA(0, 1), a2 + hstepA, voffA);
;             PG8_WAIT_V(8); PG8_WAIT_L(0); PG8_BAR; PG8_MMA(0, 0, At, B0); PG8_MMA(0, 1, At, B1); PG8_BAR; PG8_SCHED;
;             PG8_LDA(At, 1, 1); PG8_STAGE(PG8_SB(1, 0), b3, voffB); PG8_STAGE(PG8_SB(1, 1), b3 + hstepB, voffB); PG8_STAGE(PG8_SA(1, 0), a3, voffA);
;             PG8_WAIT_V(8); PG8_WAIT_L(0); PG8_BAR; PG8_MMA(1, 0, At, B0); PG8_MMA(1, 1, At, B1); PG8_BAR; PG8_SCHED;
	s_setprio 1
	s_waitcnt lgkmcnt(0)
	v_mfma_f32_16x16x32_bf16 v[62:65], v[130:133], v[210:213], v[62:65]
	v_mfma_f32_16x16x32_bf16 v[58:61], v[138:141], v[210:213], v[58:61]
	v_mfma_f32_16x16x32_bf16 v[46:49], v[130:133], v[218:221], v[46:49]
	v_mfma_f32_16x16x32_bf16 v[42:45], v[138:141], v[218:221], v[42:45]
	v_mfma_f32_16x16x32_bf16 v[30:33], v[130:133], v[226:229], v[30:33]
	v_mfma_f32_16x16x32_bf16 v[26:29], v[138:141], v[226:229], v[26:29]
	v_mfma_f32_16x16x32_bf16 v[14:17], v[130:133], v[234:237], v[14:17]
	v_mfma_f32_16x16x32_bf16 v[10:13], v[138:141], v[234:237], v[10:13]
	v_mfma_f32_16x16x32_bf16 v[62:65], v[134:137], v[214:217], v[62:65]
	v_mfma_f32_16x16x32_bf16 v[58:61], v[142:145], v[214:217], v[58:61]
	v_mfma_f32_16x16x32_bf16 v[46:49], v[134:137], v[222:225], v[46:49]
	v_mfma_f32_16x16x32_bf16 v[42:45], v[142:145], v[222:225], v[42:45]
	v_mfma_f32_16x16x32_bf16 v[30:33], v[134:137], v[230:233], v[30:33]
	v_mfma_f32_16x16x32_bf16 v[26:29], v[142:145], v[230:233], v[26:29]
	v_mfma_f32_16x16x32_bf16 v[14:17], v[134:137], v[238:241], v[14:17]
	v_mfma_f32_16x16x32_bf16 v[10:13], v[142:145], v[238:241], v[10:13]
	s_setprio 0
	s_setprio 1
	v_mfma_f32_16x16x32_bf16 v[54:57], v[158:161], v[210:213], v[54:57]
	v_mfma_f32_16x16x32_bf16 v[50:53], v[196:199], v[210:213], v[50:53]
	v_mfma_f32_16x16x32_bf16 v[38:41], v[158:161], v[218:221], v[38:41]
	v_mfma_f32_16x16x32_bf16 v[34:37], v[196:199], v[218:221], v[34:37]
	v_mfma_f32_16x16x32_bf16 v[22:25], v[158:161], v[226:229], v[22:25]
	v_mfma_f32_16x16x32_bf16 v[18:21], v[196:199], v[226:229], v[18:21]
	v_mfma_f32_16x16x32_bf16 v[6:9], v[158:161], v[234:237], v[6:9]
	v_mfma_f32_16x16x32_bf16 v[2:5], v[196:199], v[234:237], v[2:5]
	v_mfma_f32_16x16x32_bf16 v[54:57], v[192:195], v[214:217], v[54:57]
	v_mfma_f32_16x16x32_bf16 v[50:53], v[200:203], v[214:217], v[50:53]
	v_mfma_f32_16x16x32_bf16 v[38:41], v[192:195], v[222:225], v[38:41]
	v_mfma_f32_16x16x32_bf16 v[34:37], v[200:203], v[222:225], v[34:37]
	v_mfma_f32_16x16x32_bf16 v[22:25], v[192:195], v[230:233], v[22:25]
	v_mfma_f32_16x16x32_bf16 v[18:21], v[200:203], v[230:233], v[18:21]
	v_mfma_f32_16x16x32_bf16 v[6:9], v[192:195], v[238:241], v[6:9]
	v_mfma_f32_16x16x32_bf16 v[2:5], v[200:203], v[238:241], v[2:5]
	s_setprio 0
	s_barrier
	s_add_i32 s0, 0, 0x18000
	s_add_i32 s1, 0, 0x1c000
	v_add_u32_e32 v142, s0, v189
	v_add_u32_e32 v200, s1, v189
	ds_read_b128 v[130:133], v142
	ds_read_b128 v[134:137], v142 offset:1024
	ds_read_b128 v[138:141], v142 offset:2048
	ds_read_b128 v[142:145], v142 offset:3072
	ds_read_b128 v[158:161], v200
	ds_read_b128 v[192:195], v200 offset:1024
	ds_read_b128 v[196:199], v200 offset:2048
	ds_read_b128 v[200:203], v200 offset:3072
	s_add_u32 s2, s68, 0x80000
	s_addc_u32 s3, s69, 0
	s_mov_b32 m0, s73
	v_lshl_add_u64 v[242:243], s[2:3], 0, v[152:153]
	global_load_lds_dwordx4 v[242:243], off
	v_lshl_add_u64 v[242:243], s[2:3], 0, v[150:151]
	s_mov_b32 m0, s74
	s_nop 0
	global_load_lds_dwordx4 v[242:243], off
	ds_read_b128 v[210:213], v191 offset:32768
	ds_read_b128 v[214:217], v191 offset:33792
	ds_read_b128 v[218:221], v191 offset:34816
	ds_read_b128 v[222:225], v191 offset:35840
	ds_read_b128 v[226:229], v191 offset:36864
	ds_read_b128 v[230:233], v191 offset:37888
	ds_read_b128 v[234:237], v191 offset:38912
	ds_read_b128 v[238:241], v191 offset:39936
	s_waitcnt vmcnt(8)
	s_waitcnt lgkmcnt(0)
	s_barrier
	s_setprio 1
	s_waitcnt lgkmcnt(0)
	v_mfma_f32_16x16x32_bf16 v[126:129], v[130:133], v[210:213], v[126:129]
	v_mfma_f32_16x16x32_bf16 v[122:125], v[138:141], v[210:213], v[122:125]
	v_mfma_f32_16x16x32_bf16 v[110:113], v[130:133], v[218:221], v[110:113]
	v_mfma_f32_16x16x32_bf16 v[106:109], v[138:141], v[218:221], v[106:109]
	v_mfma_f32_16x16x32_bf16 v[94:97], v[130:133], v[226:229], v[94:97]
	v_mfma_f32_16x16x32_bf16 v[90:93], v[138:141], v[226:229], v[90:93]
	v_mfma_f32_16x16x32_bf16 v[78:81], v[130:133], v[234:237], v[78:81]
	v_mfma_f32_16x16x32_bf16 v[74:77], v[138:141], v[234:237], v[74:77]
	v_mfma_f32_16x16x32_bf16 v[126:129], v[134:137], v[214:217], v[126:129]
	v_mfma_f32_16x16x32_bf16 v[122:125], v[142:145], v[214:217], v[122:125]
	v_mfma_f32_16x16x32_bf16 v[110:113], v[134:137], v[222:225], v[110:113]
	v_mfma_f32_16x16x32_bf16 v[106:109], v[142:145], v[222:225], v[106:109]
	v_mfma_f32_16x16x32_bf16 v[94:97], v[134:137], v[230:233], v[94:97]
	v_mfma_f32_16x16x32_bf16 v[90:93], v[142:145], v[230:233], v[90:93]
	v_mfma_f32_16x16x32_bf16 v[78:81], v[134:137], v[238:241], v[78:81]
	v_mfma_f32_16x16x32_bf16 v[74:77], v[142:145], v[238:241], v[74:77]
	s_setprio 0
	s_setprio 1
	v_mfma_f32_16x16x32_bf16 v[118:121], v[158:161], v[210:213], v[118:121]
	v_mfma_f32_16x16x32_bf16 v[114:117], v[196:199], v[210:213], v[114:117]
	v_mfma_f32_16x16x32_bf16 v[102:105], v[158:161], v[218:221], v[102:105]
	v_mfma_f32_16x16x32_bf16 v[98:101], v[196:199], v[218:221], v[98:101]
	v_mfma_f32_16x16x32_bf16 v[86:89], v[158:161], v[226:229], v[86:89]
	v_mfma_f32_16x16x32_bf16 v[82:85], v[196:199], v[226:229], v[82:85]
	v_mfma_f32_16x16x32_bf16 v[70:73], v[158:161], v[234:237], v[70:73]
	v_mfma_f32_16x16x32_bf16 v[66:69], v[196:199], v[234:237], v[66:69]
	v_mfma_f32_16x16x32_bf16 v[118:121], v[192:195], v[214:217], v[118:121]
	v_mfma_f32_16x16x32_bf16 v[114:117], v[200:203], v[214:217], v[114:117]
	v_mfma_f32_16x16x32_bf16 v[102:105], v[192:195], v[222:225], v[102:105]
	v_mfma_f32_16x16x32_bf16 v[98:101], v[200:203], v[222:225], v[98:101]
	v_mfma_f32_16x16x32_bf16 v[86:89], v[192:195], v[230:233], v[86:89]
	v_mfma_f32_16x16x32_bf16 v[82:85], v[200:203], v[230:233], v[82:85]
	v_mfma_f32_16x16x32_bf16 v[70:73], v[192:195], v[238:241], v[70:73]
	v_mfma_f32_16x16x32_bf16 v[66:69], v[200:203], v[238:241], v[66:69]
	s_setprio 0
	s_barrier
; #define PG8_STAGE(bufoff, gbase, voff) do { _Pragma("unroll") for (int _i = 0; _i < 2; ++_i) \
;         __builtin_amdgcn_global_load_lds((const unsigned*)((const char*)(gbase) + (voff)[_i]), (LAS unsigned*)(lds + (bufoff) + ldsw + _i * 8192), 16, 0, 0); } while (0)
; #define PG8_LDA(dst, b, h) do { _Pragma("unroll") for (int m = 0; m < 4; ++m) _Pragma("unroll") for (int k = 0; k < 2; ++k) dst[m][k] = *(const LAS bf16x8*)(lds + PG8_SA(b, h) + aoff + m * 2048 + k * 1024); } while (0)
; #define PG8_MMA(ai, bj, At, Bt) do { __builtin_amdgcn_s_setprio(1); _Pragma("unroll") for (int m = 0; m < 4; ++m) _Pragma("unroll") for (int n = 0; n < 2; ++n) _Pragma("unroll") for (int k = 0; k < 2; ++k) \
;         acc[ai][bj][m][n] = __builtin_amdgcn_mfma_f32_16x16x32_bf16(Bt[n][k], At[m][k], acc[ai][bj][m][n], 0, 0, 0); __builtin_amdgcn_s_setprio(0); } while (0)
; #define PG8_WAIT_V(n) asm volatile("s_waitcnt vmcnt(" #n ")" ::: "memory")
; #define PG8_WAIT_L(n) asm volatile("s_waitcnt lgkmcnt(" #n ")" ::: "memory")
; #define PG8_BAR __builtin_amdgcn_s_barrier()
; #define PG8_SCHED __builtin_amdgcn_sched_barrier(0)
; template <class Epi>
; __device__ __forceinline__ void gemm_phase(LAS unsigned char* lds, const int tid, const Gemm g, const StaticOrder& S, const Epi& E) {
;     ...
;             PG8_LDA(At, 1, 1); PG8_STAGE(PG8_SB(1, 0), b3, voffB); PG8_STAGE(PG8_SB(1, 1), b3 + hstepB, voffB); PG8_STAGE(PG8_SA(1, 0), a3, voffA);
;             PG8_WAIT_V(8); PG8_WAIT_L(0); PG8_BAR; PG8_MMA(1, 0, At, B0); PG8_MMA(1, 1, At, B1); PG8_BAR; PG8_SCHED;
;         }
;         if (wr == 0) PG8_BAR;
	s_add_i32 s0, s0, s28
	v_lshl_add_u64 v[162:163], v[162:163], 0, s[36:37]
	s_mov_b32 m0, s0
	s_nop 0
	global_load_lds_dwordx4 v[162:163], off
	s_add_i32 m0, s0, 0x2000
	s_add_u32 s2, s30, 0x40080
	v_lshl_add_u64 v[162:163], v[164:165], 0, s[36:37]
	s_addc_u32 s3, s31, 0
	s_add_i32 s0, s1, s28
	global_load_lds_dwordx4 v[162:163], off
	v_lshl_add_u64 v[162:163], s[2:3], 0, v[0:1]
	s_mov_b32 m0, s0
	s_nop 0
	global_load_lds_dwordx4 v[162:163], off
	v_lshl_add_u64 v[162:163], s[2:3], 0, v[148:149]
	s_add_i32 m0, s0, 0x2000
	s_nop 0
	global_load_lds_dwordx4 v[162:163], off
	v_lshl_add_u64 v[162:163], v[170:171], 0, s[36:37]
	s_mov_b32 m0, s75
	s_nop 0
	global_load_lds_dwordx4 v[162:163], off
	v_lshl_add_u64 v[162:163], v[206:207], 0, s[36:37]
	s_mov_b32 m0, s76
	s_nop 0
	global_load_lds_dwordx4 v[162:163], off
	ds_read_b128 v[210:213], v191 offset:49152
	ds_read_b128 v[214:217], v191 offset:50176
	ds_read_b128 v[218:221], v191 offset:51200
	ds_read_b128 v[222:225], v191 offset:52224
	ds_read_b128 v[226:229], v191 offset:53248
	ds_read_b128 v[230:233], v191 offset:54272
	ds_read_b128 v[234:237], v191 offset:55296
	ds_read_b128 v[238:241], v191 offset:56320
	s_waitcnt vmcnt(8)
	s_waitcnt lgkmcnt(0)
	s_barrier
	s_setprio 1
	s_waitcnt lgkmcnt(0)
	v_mfma_f32_16x16x32_bf16 v[62:65], v[130:133], v[210:213], v[62:65]
	v_mfma_f32_16x16x32_bf16 v[58:61], v[138:141], v[210:213], v[58:61]
	v_mfma_f32_16x16x32_bf16 v[46:49], v[130:133], v[218:221], v[46:49]
	v_mfma_f32_16x16x32_bf16 v[42:45], v[138:141], v[218:221], v[42:45]
	v_mfma_f32_16x16x32_bf16 v[30:33], v[130:133], v[226:229], v[30:33]
	v_mfma_f32_16x16x32_bf16 v[26:29], v[138:141], v[226:229], v[26:29]
	v_mfma_f32_16x16x32_bf16 v[14:17], v[130:133], v[234:237], v[14:17]
	v_mfma_f32_16x16x32_bf16 v[10:13], v[138:141], v[234:237], v[10:13]
	v_mfma_f32_16x16x32_bf16 v[62:65], v[134:137], v[214:217], v[62:65]
	v_mfma_f32_16x16x32_bf16 v[58:61], v[142:145], v[214:217], v[58:61]
	v_mfma_f32_16x16x32_bf16 v[46:49], v[134:137], v[222:225], v[46:49]
	v_mfma_f32_16x16x32_bf16 v[42:45], v[142:145], v[222:225], v[42:45]
	v_mfma_f32_16x16x32_bf16 v[30:33], v[134:137], v[230:233], v[30:33]
	v_mfma_f32_16x16x32_bf16 v[26:29], v[142:145], v[230:233], v[26:29]
	v_mfma_f32_16x16x32_bf16 v[14:17], v[134:137], v[238:241], v[14:17]
	v_mfma_f32_16x16x32_bf16 v[10:13], v[142:145], v[238:241], v[10:13]
	s_setprio 0
	s_setprio 1
	v_mfma_f32_16x16x32_bf16 v[54:57], v[158:161], v[210:213], v[54:57]
	v_mfma_f32_16x16x32_bf16 v[50:53], v[196:199], v[210:213], v[50:53]
	v_mfma_f32_16x16x32_bf16 v[38:41], v[158:161], v[218:221], v[38:41]
	v_mfma_f32_16x16x32_bf16 v[34:37], v[196:199], v[218:221], v[34:37]
	v_mfma_f32_16x16x32_bf16 v[22:25], v[158:161], v[226:229], v[22:25]
	v_mfma_f32_16x16x32_bf16 v[18:21], v[196:199], v[226:229], v[18:21]
	v_mfma_f32_16x16x32_bf16 v[6:9], v[158:161], v[234:237], v[6:9]
	v_mfma_f32_16x16x32_bf16 v[2:5], v[196:199], v[234:237], v[2:5]
	v_mfma_f32_16x16x32_bf16 v[54:57], v[192:195], v[214:217], v[54:57]
	v_mfma_f32_16x16x32_bf16 v[50:53], v[200:203], v[214:217], v[50:53]
	v_mfma_f32_16x16x32_bf16 v[38:41], v[192:195], v[222:225], v[38:41]
	v_mfma_f32_16x16x32_bf16 v[34:37], v[200:203], v[222:225], v[34:37]
	v_mfma_f32_16x16x32_bf16 v[22:25], v[192:195], v[230:233], v[22:25]
	v_mfma_f32_16x16x32_bf16 v[18:21], v[200:203], v[230:233], v[18:21]
	v_mfma_f32_16x16x32_bf16 v[6:9], v[192:195], v[238:241], v[6:9]
	v_mfma_f32_16x16x32_bf16 v[2:5], v[200:203], v[238:241], v[2:5]
	s_setprio 0
	s_barrier
	s_add_i32 vcc_lo, vcc_lo, 2
	s_add_u32 s66, s66, 0x100
	s_addc_u32 s67, s67, 0
	s_add_u32 s92, s92, 0x100
	s_addc_u32 s93, s93, 0
	s_cmp_gt_u32 vcc_lo, 13
	s_cbranch_scc0 .LBB0_1333
	s_and_b64 vcc, exec, s[6:7]
	s_cbranch_vccz .LBB0_1336
	s_barrier

; #define PG8_STAGE(bufoff, gbase, voff) do { _Pragma("unroll") for (int _i = 0; _i < 2; ++_i) \
;         __builtin_amdgcn_global_load_lds((const unsigned*)((const char*)(gbase) + (voff)[_i]), (LAS unsigned*)(lds + (bufoff) + ldsw + _i * 8192), 16, 0, 0); } while (0)
; #define PG8_LDA(dst, b, h) do { _Pragma("unroll") for (int m = 0; m < 4; ++m) _Pragma("unroll") for (int k = 0; k < 2; ++k) dst[m][k] = *(const LAS bf16x8*)(lds + PG8_SA(b, h) + aoff + m * 2048 + k * 1024); } while (0)
; #define PG8_LDB(dst, b, h) do { _Pragma("unroll") for (int n = 0; n < 2; ++n) _Pragma("unroll") for (int k = 0; k < 2; ++k) dst[n][k] = *(const LAS bf16x8*)(lds + PG8_SB(b, h) + boff + n * 2048 + k * 1024); } while (0)
; #define PG8_MMA(ai, bj, At, Bt) do { __builtin_amdgcn_s_setprio(1); _Pragma("unroll") for (int m = 0; m < 4; ++m) _Pragma("unroll") for (int n = 0; n < 2; ++n) _Pragma("unroll") for (int k = 0; k < 2; ++k) \
;         acc[ai][bj][m][n] = __builtin_amdgcn_mfma_f32_16x16x32_bf16(Bt[n][k], At[m][k], acc[ai][bj][m][n], 0, 0, 0); __builtin_amdgcn_s_setprio(0); } while (0)
; #define PG8_WAIT_V(n) asm volatile("s_waitcnt vmcnt(" #n ")" ::: "memory")
; #define PG8_WAIT_L(n) asm volatile("s_waitcnt lgkmcnt(" #n ")" ::: "memory")
; #define PG8_BAR __builtin_amdgcn_s_barrier()
; #define PG8_SCHED __builtin_amdgcn_sched_barrier(0)
; template <class Epi>
; __device__ __forceinline__ void gemm_phase(LAS unsigned char* lds, const int tid, const Gemm g, const StaticOrder& S, const Epi& E) {
;     ...
;         for (int t = 0; t < nt; t += 2) {
;             const bool last = (t == nt - 2);
;             const char* a1 = cA + (size_t)(t + 1) * kstep;
;             const char* a2 = last ? nA : cA + (size_t)(t + 2) * kstep; const char* b2 = last ? nB : cB + (size_t)(t + 2) * kstep;
;             const char* a3 = a2 + kstep; const char* b3 = b2 + kstep;
;             PG8_LDB(B0, 0, 0); PG8_LDB(B1, 0, 1); PG8_SCHED; PG8_LDA(At, 0, 0); PG8_STAGE(PG8_SA(1, 1), a1 + hstepA, voffA);
;             PG8_WAIT_V(8); PG8_WAIT_L(0); PG8_BAR; PG8_MMA(0, 0, At, B0); PG8_MMA(0, 1, At, B1); PG8_BAR; PG8_SCHED;
;             PG8_LDA(At, 0, 1); PG8_STAGE(PG8_SB(0, 0), b2, voffB); PG8_STAGE(PG8_SB(0, 1), b2 + hstepB, voffB); PG8_STAGE(PG8_SA(0, 0), a2, voffA);
;             PG8_WAIT_V(8); PG8_WAIT_L(0); PG8_BAR; PG8_MMA(1, 0, At, B0); PG8_MMA(1, 1, At, B1); PG8_BAR; PG8_SCHED;
.LBB0_1487:
	s_add_u32 s27, s68, 0xfffc0080
	s_addc_u32 s30, s69, -1
	s_add_i32 s62, 0, 0x10000
	s_cmp_eq_u32 s26, 12
	s_cselect_b32 vcc_hi, s28, s30
	s_cselect_b32 vcc_lo, s71, s27
	s_cselect_b32 s31, s5, s83
	s_cselect_b32 s30, s73, s75
	s_add_i32 s27, 0, 0x14000
	v_add_u32_e32 v142, s62, v216
	v_add_u32_e32 v158, s27, v216
	ds_read_b128 v[130:133], v142
	ds_read_b128 v[134:137], v142 offset:1024
	ds_read_b128 v[138:141], v142 offset:2048
	ds_read_b128 v[142:145], v142 offset:3072
	ds_read_b128 v[146:149], v158
	ds_read_b128 v[150:153], v158 offset:1024
	ds_read_b128 v[154:157], v158 offset:2048
	ds_read_b128 v[158:161], v158 offset:3072
	v_lshl_add_u64 v[162:163], s[68:69], 0, v[176:177]
	s_add_i32 m0, s1, 0xc000
	s_nop 0
	global_load_lds_dwordx4 v[162:163], off
	v_lshl_add_u64 v[162:163], s[68:69], 0, v[178:179]
	s_add_i32 m0, s1, 0xe000
	s_nop 0
	global_load_lds_dwordx4 v[162:163], off
	ds_read_b128 v[180:183], v218
	ds_read_b128 v[184:187], v218 offset:1024
	ds_read_b128 v[220:223], v218 offset:2048
	ds_read_b128 v[224:227], v218 offset:3072
	ds_read_b128 v[228:231], v218 offset:4096
	ds_read_b128 v[232:235], v218 offset:5120
	ds_read_b128 v[236:239], v218 offset:6144
	ds_read_b128 v[240:243], v218 offset:7168
	s_waitcnt vmcnt(8)
	s_waitcnt lgkmcnt(0)
	s_barrier
	s_setprio 1
	s_waitcnt lgkmcnt(0)
	v_mfma_f32_16x16x32_bf16 v[126:129], v[130:133], v[180:183], v[126:129]
	v_mfma_f32_16x16x32_bf16 v[122:125], v[138:141], v[180:183], v[122:125]
	v_mfma_f32_16x16x32_bf16 v[110:113], v[130:133], v[220:223], v[110:113]
	v_mfma_f32_16x16x32_bf16 v[106:109], v[138:141], v[220:223], v[106:109]
	v_mfma_f32_16x16x32_bf16 v[94:97], v[130:133], v[228:231], v[94:97]
	v_mfma_f32_16x16x32_bf16 v[90:93], v[138:141], v[228:231], v[90:93]
	v_mfma_f32_16x16x32_bf16 v[78:81], v[130:133], v[236:239], v[78:81]
	v_mfma_f32_16x16x32_bf16 v[74:77], v[138:141], v[236:239], v[74:77]
	v_mfma_f32_16x16x32_bf16 v[126:129], v[134:137], v[184:187], v[126:129]
	v_mfma_f32_16x16x32_bf16 v[122:125], v[142:145], v[184:187], v[122:125]
	v_mfma_f32_16x16x32_bf16 v[110:113], v[134:137], v[224:227], v[110:113]
	v_mfma_f32_16x16x32_bf16 v[106:109], v[142:145], v[224:227], v[106:109]
	v_mfma_f32_16x16x32_bf16 v[94:97], v[134:137], v[232:235], v[94:97]
	v_mfma_f32_16x16x32_bf16 v[90:93], v[142:145], v[232:235], v[90:93]
	v_mfma_f32_16x16x32_bf16 v[78:81], v[134:137], v[240:243], v[78:81]
	v_mfma_f32_16x16x32_bf16 v[74:77], v[142:145], v[240:243], v[74:77]
	s_setprio 0
	s_setprio 1
	v_mfma_f32_16x16x32_bf16 v[118:121], v[146:149], v[180:183], v[118:121]
	v_mfma_f32_16x16x32_bf16 v[114:117], v[154:157], v[180:183], v[114:117]
	v_mfma_f32_16x16x32_bf16 v[102:105], v[146:149], v[220:223], v[102:105]
	v_mfma_f32_16x16x32_bf16 v[98:101], v[154:157], v[220:223], v[98:101]
	v_mfma_f32_16x16x32_bf16 v[86:89], v[146:149], v[228:231], v[86:89]
	v_mfma_f32_16x16x32_bf16 v[82:85], v[154:157], v[228:231], v[82:85]
	v_mfma_f32_16x16x32_bf16 v[70:73], v[146:149], v[236:239], v[70:73]
	v_mfma_f32_16x16x32_bf16 v[66:69], v[154:157], v[236:239], v[66:69]
	v_mfma_f32_16x16x32_bf16 v[118:121], v[150:153], v[184:187], v[118:121]
	v_mfma_f32_16x16x32_bf16 v[114:117], v[158:161], v[184:187], v[114:117]
	v_mfma_f32_16x16x32_bf16 v[102:105], v[150:153], v[224:227], v[102:105]
	v_mfma_f32_16x16x32_bf16 v[98:101], v[158:161], v[224:227], v[98:101]
	v_mfma_f32_16x16x32_bf16 v[86:89], v[150:153], v[232:235], v[86:89]
	v_mfma_f32_16x16x32_bf16 v[82:85], v[158:161], v[232:235], v[82:85]
	v_mfma_f32_16x16x32_bf16 v[70:73], v[150:153], v[240:243], v[70:73]
	v_mfma_f32_16x16x32_bf16 v[66:69], v[158:161], v[240:243], v[66:69]
	s_setprio 0
	s_barrier
	s_add_i32 s62, s62, s0
	v_lshl_add_u64 v[162:163], s[30:31], 0, v[0:1]
	s_mov_b32 m0, s62
	s_nop 0
	global_load_lds_dwordx4 v[162:163], off
	s_add_i32 m0, s62, 0x2000
	s_add_u32 s62, s30, 0x40000
	v_lshl_add_u64 v[164:165], s[30:31], 0, v[170:171]
	s_addc_u32 s63, s31, 0
	s_add_i32 s27, s27, s0
	global_load_lds_dwordx4 v[164:165], off
	v_lshl_add_u64 v[206:207], s[62:63], 0, v[0:1]
	s_mov_b32 m0, s27
	v_lshl_add_u64 v[244:245], vcc, 0, v[174:175]
	global_load_lds_dwordx4 v[206:207], off
	v_lshl_add_u64 v[206:207], s[62:63], 0, v[170:171]
	s_add_i32 m0, s27, 0x2000
	s_nop 0
	global_load_lds_dwordx4 v[206:207], off
	v_lshl_add_u64 v[206:207], vcc, 0, v[172:173]
	s_mov_b32 m0, s1
	s_nop 0
	global_load_lds_dwordx4 v[206:207], off
	s_mov_b32 m0, s2
	s_nop 0
	global_load_lds_dwordx4 v[244:245], off
	ds_read_b128 v[180:183], v218 offset:16384
	ds_read_b128 v[184:187], v218 offset:17408
	ds_read_b128 v[220:223], v218 offset:18432
	ds_read_b128 v[224:227], v218 offset:19456
	ds_read_b128 v[228:231], v218 offset:20480
	ds_read_b128 v[232:235], v218 offset:21504
	ds_read_b128 v[236:239], v218 offset:22528
	ds_read_b128 v[240:243], v218 offset:23552
	s_waitcnt vmcnt(8)
	s_waitcnt lgkmcnt(0)
	s_barrier
; #define PG8_STAGE(bufoff, gbase, voff) do { _Pragma("unroll") for (int _i = 0; _i < 2; ++_i) \
;         __builtin_amdgcn_global_load_lds((const unsigned*)((const char*)(gbase) + (voff)[_i]), (LAS unsigned*)(lds + (bufoff) + ldsw + _i * 8192), 16, 0, 0); } while (0)
; #define PG8_LDA(dst, b, h) do { _Pragma("unroll") for (int m = 0; m < 4; ++m) _Pragma("unroll") for (int k = 0; k < 2; ++k) dst[m][k] = *(const LAS bf16x8*)(lds + PG8_SA(b, h) + aoff + m * 2048 + k * 1024); } while (0)
; #define PG8_LDB(dst, b, h) do { _Pragma("unroll") for (int n = 0; n < 2; ++n) _Pragma("unroll") for (int k = 0; k < 2; ++k) dst[n][k] = *(const LAS bf16x8*)(lds + PG8_SB(b, h) + boff + n * 2048 + k * 1024); } while (0)
; #define PG8_MMA(ai, bj, At, Bt) do { __builtin_amdgcn_s_setprio(1); _Pragma("unroll") for (int m = 0; m < 4; ++m) _Pragma("unroll") for (int n = 0; n < 2; ++n) _Pragma("unroll") for (int k = 0; k < 2; ++k) \
;         acc[ai][bj][m][n] = __builtin_amdgcn_mfma_f32_16x16x32_bf16(Bt[n][k], At[m][k], acc[ai][bj][m][n], 0, 0, 0); __builtin_amdgcn_s_setprio(0); } while (0)
; #define PG8_WAIT_V(n) asm volatile("s_waitcnt vmcnt(" #n ")" ::: "memory")
; #define PG8_WAIT_L(n) asm volatile("s_waitcnt lgkmcnt(" #n ")" ::: "memory")
; #define PG8_BAR __builtin_amdgcn_s_barrier()
; #define PG8_SCHED __builtin_amdgcn_sched_barrier(0)
; template <class Epi>
; __device__ __forceinline__ void gemm_phase(LAS unsigned char* lds, const int tid, const Gemm g, const StaticOrder& S, const Epi& E) {
;     ...
;             PG8_WAIT_V(8); PG8_WAIT_L(0); PG8_BAR; PG8_MMA(1, 0, At, B0); PG8_MMA(1, 1, At, B1); PG8_BAR; PG8_SCHED;
;             PG8_LDB(B0, 1, 0); PG8_LDB(B1, 1, 1); PG8_SCHED; PG8_LDA(At, 1, 0); PG8_STAGE(PG8_SA(0, 1), a2 + hstepA, voffA);
;             PG8_WAIT_V(8); PG8_WAIT_L(0); PG8_BAR; PG8_MMA(0, 0, At, B0); PG8_MMA(0, 1, At, B1); PG8_BAR; PG8_SCHED;
;             PG8_LDA(At, 1, 1); PG8_STAGE(PG8_SB(1, 0), b3, voffB); PG8_STAGE(PG8_SB(1, 1), b3 + hstepB, voffB); PG8_STAGE(PG8_SA(1, 0), a3, voffA);
;             PG8_WAIT_V(8); PG8_WAIT_L(0); PG8_BAR; PG8_MMA(1, 0, At, B0); PG8_MMA(1, 1, At, B1); PG8_BAR; PG8_SCHED;
	s_setprio 1
	s_waitcnt lgkmcnt(0)
	v_mfma_f32_16x16x32_bf16 v[62:65], v[130:133], v[180:183], v[62:65]
	v_mfma_f32_16x16x32_bf16 v[58:61], v[138:141], v[180:183], v[58:61]
	v_mfma_f32_16x16x32_bf16 v[46:49], v[130:133], v[220:223], v[46:49]
	v_mfma_f32_16x16x32_bf16 v[42:45], v[138:141], v[220:223], v[42:45]
	v_mfma_f32_16x16x32_bf16 v[30:33], v[130:133], v[228:231], v[30:33]
	v_mfma_f32_16x16x32_bf16 v[26:29], v[138:141], v[228:231], v[26:29]
	v_mfma_f32_16x16x32_bf16 v[14:17], v[130:133], v[236:239], v[14:17]
	v_mfma_f32_16x16x32_bf16 v[10:13], v[138:141], v[236:239], v[10:13]
	v_mfma_f32_16x16x32_bf16 v[62:65], v[134:137], v[184:187], v[62:65]
	v_mfma_f32_16x16x32_bf16 v[58:61], v[142:145], v[184:187], v[58:61]
	v_mfma_f32_16x16x32_bf16 v[46:49], v[134:137], v[224:227], v[46:49]
	v_mfma_f32_16x16x32_bf16 v[42:45], v[142:145], v[224:227], v[42:45]
	v_mfma_f32_16x16x32_bf16 v[30:33], v[134:137], v[232:235], v[30:33]
	v_mfma_f32_16x16x32_bf16 v[26:29], v[142:145], v[232:235], v[26:29]
	v_mfma_f32_16x16x32_bf16 v[14:17], v[134:137], v[240:243], v[14:17]
	v_mfma_f32_16x16x32_bf16 v[10:13], v[142:145], v[240:243], v[10:13]
	s_setprio 0
	s_setprio 1
	v_mfma_f32_16x16x32_bf16 v[54:57], v[146:149], v[180:183], v[54:57]
	v_mfma_f32_16x16x32_bf16 v[50:53], v[154:157], v[180:183], v[50:53]
	v_mfma_f32_16x16x32_bf16 v[38:41], v[146:149], v[220:223], v[38:41]
	v_mfma_f32_16x16x32_bf16 v[34:37], v[154:157], v[220:223], v[34:37]
	v_mfma_f32_16x16x32_bf16 v[22:25], v[146:149], v[228:231], v[22:25]
	v_mfma_f32_16x16x32_bf16 v[18:21], v[154:157], v[228:231], v[18:21]
	v_mfma_f32_16x16x32_bf16 v[6:9], v[146:149], v[236:239], v[6:9]
	v_mfma_f32_16x16x32_bf16 v[2:5], v[154:157], v[236:239], v[2:5]
	v_mfma_f32_16x16x32_bf16 v[54:57], v[150:153], v[184:187], v[54:57]
	v_mfma_f32_16x16x32_bf16 v[50:53], v[158:161], v[184:187], v[50:53]
	v_mfma_f32_16x16x32_bf16 v[38:41], v[150:153], v[224:227], v[38:41]
	v_mfma_f32_16x16x32_bf16 v[34:37], v[158:161], v[224:227], v[34:37]
	v_mfma_f32_16x16x32_bf16 v[22:25], v[150:153], v[232:235], v[22:25]
	v_mfma_f32_16x16x32_bf16 v[18:21], v[158:161], v[232:235], v[18:21]
	v_mfma_f32_16x16x32_bf16 v[6:9], v[150:153], v[240:243], v[6:9]
	v_mfma_f32_16x16x32_bf16 v[2:5], v[158:161], v[240:243], v[2:5]
	s_setprio 0
	s_barrier
	s_add_i32 s27, 0, 0x18000
	s_add_i32 s17, 0, 0x1c000
	v_add_u32_e32 v142, s27, v216
	v_add_u32_e32 v158, s17, v216
	ds_read_b128 v[130:133], v142
	ds_read_b128 v[134:137], v142 offset:1024
	ds_read_b128 v[138:141], v142 offset:2048
	ds_read_b128 v[142:145], v142 offset:3072
	ds_read_b128 v[146:149], v158
	ds_read_b128 v[150:153], v158 offset:1024
	ds_read_b128 v[154:157], v158 offset:2048
	ds_read_b128 v[158:161], v158 offset:3072
	s_add_u32 s62, vcc_lo, 0x40000
	s_addc_u32 s63, vcc_hi, 0
	s_mov_b32 m0, s3
	v_lshl_add_u64 v[246:247], s[62:63], 0, v[172:173]
	global_load_lds_dwordx4 v[246:247], off
	v_lshl_add_u64 v[246:247], s[62:63], 0, v[174:175]
	s_mov_b32 m0, s16
	s_nop 0
	global_load_lds_dwordx4 v[246:247], off
	ds_read_b128 v[180:183], v218 offset:32768
	ds_read_b128 v[184:187], v218 offset:33792
	ds_read_b128 v[220:223], v218 offset:34816
	ds_read_b128 v[224:227], v218 offset:35840
	ds_read_b128 v[228:231], v218 offset:36864
	ds_read_b128 v[232:235], v218 offset:37888
	ds_read_b128 v[236:239], v218 offset:38912
	ds_read_b128 v[240:243], v218 offset:39936
	s_waitcnt vmcnt(8)
	s_waitcnt lgkmcnt(0)
	s_barrier
	s_setprio 1
	s_waitcnt lgkmcnt(0)
	v_mfma_f32_16x16x32_bf16 v[126:129], v[130:133], v[180:183], v[126:129]
	v_mfma_f32_16x16x32_bf16 v[122:125], v[138:141], v[180:183], v[122:125]
	v_mfma_f32_16x16x32_bf16 v[110:113], v[130:133], v[220:223], v[110:113]
	v_mfma_f32_16x16x32_bf16 v[106:109], v[138:141], v[220:223], v[106:109]
	v_mfma_f32_16x16x32_bf16 v[94:97], v[130:133], v[228:231], v[94:97]
	v_mfma_f32_16x16x32_bf16 v[90:93], v[138:141], v[228:231], v[90:93]
	v_mfma_f32_16x16x32_bf16 v[78:81], v[130:133], v[236:239], v[78:81]
	v_mfma_f32_16x16x32_bf16 v[74:77], v[138:141], v[236:239], v[74:77]
	v_mfma_f32_16x16x32_bf16 v[126:129], v[134:137], v[184:187], v[126:129]
	v_mfma_f32_16x16x32_bf16 v[122:125], v[142:145], v[184:187], v[122:125]
	v_mfma_f32_16x16x32_bf16 v[110:113], v[134:137], v[224:227], v[110:113]
	v_mfma_f32_16x16x32_bf16 v[106:109], v[142:145], v[224:227], v[106:109]
	v_mfma_f32_16x16x32_bf16 v[94:97], v[134:137], v[232:235], v[94:97]
	v_mfma_f32_16x16x32_bf16 v[90:93], v[142:145], v[232:235], v[90:93]
	v_mfma_f32_16x16x32_bf16 v[78:81], v[134:137], v[240:243], v[78:81]
	v_mfma_f32_16x16x32_bf16 v[74:77], v[142:145], v[240:243], v[74:77]
	s_setprio 0
	s_setprio 1
	v_mfma_f32_16x16x32_bf16 v[118:121], v[146:149], v[180:183], v[118:121]
	v_mfma_f32_16x16x32_bf16 v[114:117], v[154:157], v[180:183], v[114:117]
	v_mfma_f32_16x16x32_bf16 v[102:105], v[146:149], v[220:223], v[102:105]
	v_mfma_f32_16x16x32_bf16 v[98:101], v[154:157], v[220:223], v[98:101]
	v_mfma_f32_16x16x32_bf16 v[86:89], v[146:149], v[228:231], v[86:89]
	v_mfma_f32_16x16x32_bf16 v[82:85], v[154:157], v[228:231], v[82:85]
	v_mfma_f32_16x16x32_bf16 v[70:73], v[146:149], v[236:239], v[70:73]
	v_mfma_f32_16x16x32_bf16 v[66:69], v[154:157], v[236:239], v[66:69]
	v_mfma_f32_16x16x32_bf16 v[118:121], v[150:153], v[184:187], v[118:121]
	v_mfma_f32_16x16x32_bf16 v[114:117], v[158:161], v[184:187], v[114:117]
	v_mfma_f32_16x16x32_bf16 v[102:105], v[150:153], v[224:227], v[102:105]
	v_mfma_f32_16x16x32_bf16 v[98:101], v[158:161], v[224:227], v[98:101]
	v_mfma_f32_16x16x32_bf16 v[86:89], v[150:153], v[232:235], v[86:89]
	v_mfma_f32_16x16x32_bf16 v[82:85], v[158:161], v[232:235], v[82:85]
	v_mfma_f32_16x16x32_bf16 v[70:73], v[150:153], v[240:243], v[70:73]
	v_mfma_f32_16x16x32_bf16 v[66:69], v[158:161], v[240:243], v[66:69]
	s_setprio 0
	s_barrier
; #define PG8_STAGE(bufoff, gbase, voff) do { _Pragma("unroll") for (int _i = 0; _i < 2; ++_i) \
;         __builtin_amdgcn_global_load_lds((const unsigned*)((const char*)(gbase) + (voff)[_i]), (LAS unsigned*)(lds + (bufoff) + ldsw + _i * 8192), 16, 0, 0); } while (0)
; #define PG8_LDA(dst, b, h) do { _Pragma("unroll") for (int m = 0; m < 4; ++m) _Pragma("unroll") for (int k = 0; k < 2; ++k) dst[m][k] = *(const LAS bf16x8*)(lds + PG8_SA(b, h) + aoff + m * 2048 + k * 1024); } while (0)
; #define PG8_MMA(ai, bj, At, Bt) do { __builtin_amdgcn_s_setprio(1); _Pragma("unroll") for (int m = 0; m < 4; ++m) _Pragma("unroll") for (int n = 0; n < 2; ++n) _Pragma("unroll") for (int k = 0; k < 2; ++k) \
;         acc[ai][bj][m][n] = __builtin_amdgcn_mfma_f32_16x16x32_bf16(Bt[n][k], At[m][k], acc[ai][bj][m][n], 0, 0, 0); __builtin_amdgcn_s_setprio(0); } while (0)
; #define PG8_WAIT_V(n) asm volatile("s_waitcnt vmcnt(" #n ")" ::: "memory")
; #define PG8_WAIT_L(n) asm volatile("s_waitcnt lgkmcnt(" #n ")" ::: "memory")
; #define PG8_BAR __builtin_amdgcn_s_barrier()
; #define PG8_SCHED __builtin_amdgcn_sched_barrier(0)
; template <class Epi>
; __device__ __forceinline__ void gemm_phase(LAS unsigned char* lds, const int tid, const Gemm g, const StaticOrder& S, const Epi& E) {
;     ...
;             PG8_LDA(At, 1, 1); PG8_STAGE(PG8_SB(1, 0), b3, voffB); PG8_STAGE(PG8_SB(1, 1), b3 + hstepB, voffB); PG8_STAGE(PG8_SA(1, 0), a3, voffA);
;             PG8_WAIT_V(8); PG8_WAIT_L(0); PG8_BAR; PG8_MMA(1, 0, At, B0); PG8_MMA(1, 1, At, B1); PG8_BAR; PG8_SCHED;
;         }
;         if (wr == 0) PG8_BAR;
	s_add_i32 s27, s27, s0
	v_lshl_add_u64 v[162:163], v[162:163], 0, s[36:37]
	s_mov_b32 m0, s27
	s_nop 0
	global_load_lds_dwordx4 v[162:163], off
	s_add_i32 m0, s27, 0x2000
	s_add_u32 s30, s30, 0x40080
	v_lshl_add_u64 v[162:163], v[164:165], 0, s[36:37]
	s_addc_u32 s31, s31, 0
	s_add_i32 s17, s17, s0
	global_load_lds_dwordx4 v[162:163], off
	v_lshl_add_u64 v[162:163], s[30:31], 0, v[0:1]
	s_mov_b32 m0, s17
	s_nop 0
	global_load_lds_dwordx4 v[162:163], off
	v_lshl_add_u64 v[162:163], s[30:31], 0, v[170:171]
	s_add_i32 m0, s17, 0x2000
	s_nop 0
	global_load_lds_dwordx4 v[162:163], off
	v_lshl_add_u64 v[162:163], v[206:207], 0, s[36:37]
	s_mov_b32 m0, s10
	s_nop 0
	global_load_lds_dwordx4 v[162:163], off
	v_lshl_add_u64 v[162:163], v[244:245], 0, s[36:37]
	s_mov_b32 m0, s11
	s_nop 0
	global_load_lds_dwordx4 v[162:163], off
	ds_read_b128 v[180:183], v218 offset:49152
	ds_read_b128 v[184:187], v218 offset:50176
	ds_read_b128 v[220:223], v218 offset:51200
	ds_read_b128 v[224:227], v218 offset:52224
	ds_read_b128 v[228:231], v218 offset:53248
	ds_read_b128 v[232:235], v218 offset:54272
	ds_read_b128 v[236:239], v218 offset:55296
	ds_read_b128 v[240:243], v218 offset:56320
	s_waitcnt vmcnt(8)
	s_waitcnt lgkmcnt(0)
	s_barrier
	s_setprio 1
	s_waitcnt lgkmcnt(0)
	v_mfma_f32_16x16x32_bf16 v[62:65], v[130:133], v[180:183], v[62:65]
	v_mfma_f32_16x16x32_bf16 v[58:61], v[138:141], v[180:183], v[58:61]
	v_mfma_f32_16x16x32_bf16 v[46:49], v[130:133], v[220:223], v[46:49]
	v_mfma_f32_16x16x32_bf16 v[42:45], v[138:141], v[220:223], v[42:45]
	v_mfma_f32_16x16x32_bf16 v[30:33], v[130:133], v[228:231], v[30:33]
	v_mfma_f32_16x16x32_bf16 v[26:29], v[138:141], v[228:231], v[26:29]
	v_mfma_f32_16x16x32_bf16 v[14:17], v[130:133], v[236:239], v[14:17]
	v_mfma_f32_16x16x32_bf16 v[10:13], v[138:141], v[236:239], v[10:13]
	v_mfma_f32_16x16x32_bf16 v[62:65], v[134:137], v[184:187], v[62:65]
	v_mfma_f32_16x16x32_bf16 v[58:61], v[142:145], v[184:187], v[58:61]
	v_mfma_f32_16x16x32_bf16 v[46:49], v[134:137], v[224:227], v[46:49]
	v_mfma_f32_16x16x32_bf16 v[42:45], v[142:145], v[224:227], v[42:45]
	v_mfma_f32_16x16x32_bf16 v[30:33], v[134:137], v[232:235], v[30:33]
	v_mfma_f32_16x16x32_bf16 v[26:29], v[142:145], v[232:235], v[26:29]
	v_mfma_f32_16x16x32_bf16 v[14:17], v[134:137], v[240:243], v[14:17]
	v_mfma_f32_16x16x32_bf16 v[10:13], v[142:145], v[240:243], v[10:13]
	s_setprio 0
	s_setprio 1
	v_mfma_f32_16x16x32_bf16 v[54:57], v[146:149], v[180:183], v[54:57]
	v_mfma_f32_16x16x32_bf16 v[50:53], v[154:157], v[180:183], v[50:53]
	v_mfma_f32_16x16x32_bf16 v[38:41], v[146:149], v[220:223], v[38:41]
	v_mfma_f32_16x16x32_bf16 v[34:37], v[154:157], v[220:223], v[34:37]
	v_mfma_f32_16x16x32_bf16 v[22:25], v[146:149], v[228:231], v[22:25]
	v_mfma_f32_16x16x32_bf16 v[18:21], v[154:157], v[228:231], v[18:21]
	v_mfma_f32_16x16x32_bf16 v[6:9], v[146:149], v[236:239], v[6:9]
	v_mfma_f32_16x16x32_bf16 v[2:5], v[154:157], v[236:239], v[2:5]
	v_mfma_f32_16x16x32_bf16 v[54:57], v[150:153], v[184:187], v[54:57]
	v_mfma_f32_16x16x32_bf16 v[50:53], v[158:161], v[184:187], v[50:53]
	v_mfma_f32_16x16x32_bf16 v[38:41], v[150:153], v[224:227], v[38:41]
	v_mfma_f32_16x16x32_bf16 v[34:37], v[158:161], v[224:227], v[34:37]
	v_mfma_f32_16x16x32_bf16 v[22:25], v[150:153], v[232:235], v[22:25]
	v_mfma_f32_16x16x32_bf16 v[18:21], v[158:161], v[232:235], v[18:21]
	v_mfma_f32_16x16x32_bf16 v[6:9], v[150:153], v[240:243], v[6:9]
	v_mfma_f32_16x16x32_bf16 v[2:5], v[158:161], v[240:243], v[2:5]
	s_setprio 0
	s_barrier
	s_add_i32 s26, s26, 2
	s_add_u32 s68, s68, 0x100
	s_addc_u32 s69, s69, 0
	s_add_u32 s75, s75, 0x100
	s_addc_u32 s83, s83, 0
	s_cmp_gt_u32 s26, 13
	s_cbranch_scc0 .LBB0_1487
	v_readlane_b32 s26, v255, 55
	v_readlane_b32 s27, v255, 56
	s_and_b64 vcc, exec, s[26:27]
	s_cbranch_vccz .LBB0_1490
	s_barrier

; #define PG8_STAGE(bufoff, gbase, voff) do { _Pragma("unroll") for (int _i = 0; _i < 2; ++_i) \
;         __builtin_amdgcn_global_load_lds((const unsigned*)((const char*)(gbase) + (voff)[_i]), (LAS unsigned*)(lds + (bufoff) + ldsw + _i * 8192), 16, 0, 0); } while (0)
; #define PG8_LDA(dst, b, h) do { _Pragma("unroll") for (int m = 0; m < 4; ++m) _Pragma("unroll") for (int k = 0; k < 2; ++k) dst[m][k] = *(const LAS bf16x8*)(lds + PG8_SA(b, h) + aoff + m * 2048 + k * 1024); } while (0)
; #define PG8_LDB(dst, b, h) do { _Pragma("unroll") for (int n = 0; n < 2; ++n) _Pragma("unroll") for (int k = 0; k < 2; ++k) dst[n][k] = *(const LAS bf16x8*)(lds + PG8_SB(b, h) + boff + n * 2048 + k * 1024); } while (0)
; #define PG8_MMA(ai, bj, At, Bt) do { __builtin_amdgcn_s_setprio(1); _Pragma("unroll") for (int m = 0; m < 4; ++m) _Pragma("unroll") for (int n = 0; n < 2; ++n) _Pragma("unroll") for (int k = 0; k < 2; ++k) \
;         acc[ai][bj][m][n] = __builtin_amdgcn_mfma_f32_16x16x32_bf16(Bt[n][k], At[m][k], acc[ai][bj][m][n], 0, 0, 0); __builtin_amdgcn_s_setprio(0); } while (0)
; #define PG8_WAIT_V(n) asm volatile("s_waitcnt vmcnt(" #n ")" ::: "memory")
; #define PG8_WAIT_L(n) asm volatile("s_waitcnt lgkmcnt(" #n ")" ::: "memory")
; #define PG8_BAR __builtin_amdgcn_s_barrier()
; #define PG8_SCHED __builtin_amdgcn_sched_barrier(0)
; template <class Epi>
; __device__ __forceinline__ void gemm_phase(LAS unsigned char* lds, const int tid, const Gemm g, const StaticOrder& S, const Epi& E) {
;     ...
;         for (int t = 0; t < nt; t += 2) {
;             const bool last = (t == nt - 2);
;             const char* a1 = cA + (size_t)(t + 1) * kstep;
;             const char* a2 = last ? nA : cA + (size_t)(t + 2) * kstep; const char* b2 = last ? nB : cB + (size_t)(t + 2) * kstep;
;             const char* a3 = a2 + kstep; const char* b3 = b2 + kstep;
;             PG8_LDB(B0, 0, 0); PG8_LDB(B1, 0, 1); PG8_SCHED; PG8_LDA(At, 0, 0); PG8_STAGE(PG8_SA(1, 1), a1 + hstepA, voffA);
;             PG8_WAIT_V(8); PG8_WAIT_L(0); PG8_BAR; PG8_MMA(0, 0, At, B0); PG8_MMA(0, 1, At, B1); PG8_BAR; PG8_SCHED;
;             PG8_LDA(At, 0, 1); PG8_STAGE(PG8_SB(0, 0), b2, voffB); PG8_STAGE(PG8_SB(0, 1), b2 + hstepB, voffB); PG8_STAGE(PG8_SA(0, 0), a2, voffA);
;             PG8_WAIT_V(8); PG8_WAIT_L(0); PG8_BAR; PG8_MMA(1, 0, At, B0); PG8_MMA(1, 1, At, B1); PG8_BAR; PG8_SCHED;
.LBB0_1912:
	s_add_u32 s30, s82, 0xfffc0080
	s_addc_u32 s31, s83, -1
	s_add_i32 s92, 0, 0x10000
	s_cmp_eq_u32 s17, 12
	s_cselect_b32 s89, s7, s31
	s_cselect_b32 s88, s65, s30
	s_cselect_b32 s31, s5, s27
	s_cselect_b32 s30, vcc_lo, vcc_hi
	s_add_i32 s11, 0, 0x14000
	v_add_u32_e32 v110, s92, v158
	v_add_u32_e32 v162, s11, v158
	ds_read_b128 v[98:101], v110
	ds_read_b128 v[102:105], v110 offset:1024
	ds_read_b128 v[106:109], v110 offset:2048
	ds_read_b128 v[110:113], v110 offset:3072
	ds_read_b128 v[174:177], v162
	ds_read_b128 v[178:181], v162 offset:1024
	ds_read_b128 v[182:185], v162 offset:2048
	ds_read_b128 v[186:189], v162 offset:3072
	v_lshl_add_u64 v[162:163], s[82:83], 0, v[152:153]
	s_add_i32 m0, s66, 0xc000
	s_nop 0
	global_load_lds_dwordx4 v[162:163], off
	v_lshl_add_u64 v[162:163], s[82:83], 0, v[154:155]
	s_add_i32 m0, s66, 0xe000
	s_nop 0
	global_load_lds_dwordx4 v[162:163], off
	ds_read_b128 v[190:193], v172
	ds_read_b128 v[194:197], v172 offset:1024
	ds_read_b128 v[198:201], v172 offset:2048
	ds_read_b128 v[210:213], v172 offset:3072
	ds_read_b128 v[214:217], v172 offset:4096
	ds_read_b128 v[218:221], v172 offset:5120
	ds_read_b128 v[222:225], v172 offset:6144
	ds_read_b128 v[226:229], v172 offset:7168
	s_waitcnt vmcnt(8)
	s_waitcnt lgkmcnt(0)
	s_barrier
	s_setprio 1
	s_waitcnt lgkmcnt(0)
	v_mfma_f32_16x16x32_bf16 v[142:145], v[98:101], v[190:193], v[142:145]
	v_mfma_f32_16x16x32_bf16 v[138:141], v[106:109], v[190:193], v[138:141]
	v_mfma_f32_16x16x32_bf16 v[134:137], v[98:101], v[198:201], v[134:137]
	v_mfma_f32_16x16x32_bf16 v[130:133], v[106:109], v[198:201], v[130:133]
	v_mfma_f32_16x16x32_bf16 v[94:97], v[98:101], v[214:217], v[94:97]
	v_mfma_f32_16x16x32_bf16 v[90:93], v[106:109], v[214:217], v[90:93]
	v_mfma_f32_16x16x32_bf16 v[78:81], v[98:101], v[222:225], v[78:81]
	v_mfma_f32_16x16x32_bf16 v[74:77], v[106:109], v[222:225], v[74:77]
	v_mfma_f32_16x16x32_bf16 v[142:145], v[102:105], v[194:197], v[142:145]
	v_mfma_f32_16x16x32_bf16 v[138:141], v[110:113], v[194:197], v[138:141]
	v_mfma_f32_16x16x32_bf16 v[134:137], v[102:105], v[210:213], v[134:137]
	v_mfma_f32_16x16x32_bf16 v[130:133], v[110:113], v[210:213], v[130:133]
	v_mfma_f32_16x16x32_bf16 v[94:97], v[102:105], v[218:221], v[94:97]
	v_mfma_f32_16x16x32_bf16 v[90:93], v[110:113], v[218:221], v[90:93]
	v_mfma_f32_16x16x32_bf16 v[78:81], v[102:105], v[226:229], v[78:81]
	v_mfma_f32_16x16x32_bf16 v[74:77], v[110:113], v[226:229], v[74:77]
	s_setprio 0
	s_setprio 1
	v_mfma_f32_16x16x32_bf16 v[126:129], v[174:177], v[190:193], v[126:129]
	v_mfma_f32_16x16x32_bf16 v[122:125], v[182:185], v[190:193], v[122:125]
	v_mfma_f32_16x16x32_bf16 v[118:121], v[174:177], v[198:201], v[118:121]
	v_mfma_f32_16x16x32_bf16 v[114:117], v[182:185], v[198:201], v[114:117]
	v_mfma_f32_16x16x32_bf16 v[86:89], v[174:177], v[214:217], v[86:89]
	v_mfma_f32_16x16x32_bf16 v[82:85], v[182:185], v[214:217], v[82:85]
	v_mfma_f32_16x16x32_bf16 v[70:73], v[174:177], v[222:225], v[70:73]
	v_mfma_f32_16x16x32_bf16 v[66:69], v[182:185], v[222:225], v[66:69]
	v_mfma_f32_16x16x32_bf16 v[126:129], v[178:181], v[194:197], v[126:129]
	v_mfma_f32_16x16x32_bf16 v[122:125], v[186:189], v[194:197], v[122:125]
	v_mfma_f32_16x16x32_bf16 v[118:121], v[178:181], v[210:213], v[118:121]
	v_mfma_f32_16x16x32_bf16 v[114:117], v[186:189], v[210:213], v[114:117]
	v_mfma_f32_16x16x32_bf16 v[86:89], v[178:181], v[218:221], v[86:89]
	v_mfma_f32_16x16x32_bf16 v[82:85], v[186:189], v[218:221], v[82:85]
	v_mfma_f32_16x16x32_bf16 v[70:73], v[178:181], v[226:229], v[70:73]
	v_mfma_f32_16x16x32_bf16 v[66:69], v[186:189], v[226:229], v[66:69]
	s_setprio 0
	s_barrier
	s_add_i32 s92, s92, s28
	v_lshl_add_u64 v[162:163], s[30:31], 0, v[0:1]
	s_mov_b32 m0, s92
	s_nop 0
	global_load_lds_dwordx4 v[162:163], off
	s_add_i32 m0, s92, 0x2000
	s_add_u32 s92, s30, 0x40000
	v_lshl_add_u64 v[164:165], s[30:31], 0, v[146:147]
	s_addc_u32 s93, s31, 0
	s_add_i32 s11, s11, s28
	global_load_lds_dwordx4 v[164:165], off
	v_lshl_add_u64 v[202:203], s[92:93], 0, v[0:1]
	s_mov_b32 m0, s11
	v_lshl_add_u64 v[206:207], s[88:89], 0, v[148:149]
	global_load_lds_dwordx4 v[202:203], off
	v_lshl_add_u64 v[202:203], s[92:93], 0, v[146:147]
	s_add_i32 m0, s11, 0x2000
	s_nop 0
	global_load_lds_dwordx4 v[202:203], off
	v_lshl_add_u64 v[202:203], s[88:89], 0, v[150:151]
	s_mov_b32 m0, s66
	s_nop 0
	global_load_lds_dwordx4 v[202:203], off
	s_mov_b32 m0, s67
	s_nop 0
	global_load_lds_dwordx4 v[206:207], off
	ds_read_b128 v[190:193], v172 offset:16384
	ds_read_b128 v[194:197], v172 offset:17408
	ds_read_b128 v[198:201], v172 offset:18432
	ds_read_b128 v[210:213], v172 offset:19456
	ds_read_b128 v[214:217], v172 offset:20480
	ds_read_b128 v[218:221], v172 offset:21504
	ds_read_b128 v[222:225], v172 offset:22528
	ds_read_b128 v[226:229], v172 offset:23552
	s_waitcnt vmcnt(8)
	s_waitcnt lgkmcnt(0)
	s_barrier
; #define PG8_STAGE(bufoff, gbase, voff) do { _Pragma("unroll") for (int _i = 0; _i < 2; ++_i) \
;         __builtin_amdgcn_global_load_lds((const unsigned*)((const char*)(gbase) + (voff)[_i]), (LAS unsigned*)(lds + (bufoff) + ldsw + _i * 8192), 16, 0, 0); } while (0)
; #define PG8_LDA(dst, b, h) do { _Pragma("unroll") for (int m = 0; m < 4; ++m) _Pragma("unroll") for (int k = 0; k < 2; ++k) dst[m][k] = *(const LAS bf16x8*)(lds + PG8_SA(b, h) + aoff + m * 2048 + k * 1024); } while (0)
; #define PG8_LDB(dst, b, h) do { _Pragma("unroll") for (int n = 0; n < 2; ++n) _Pragma("unroll") for (int k = 0; k < 2; ++k) dst[n][k] = *(const LAS bf16x8*)(lds + PG8_SB(b, h) + boff + n * 2048 + k * 1024); } while (0)
; #define PG8_MMA(ai, bj, At, Bt) do { __builtin_amdgcn_s_setprio(1); _Pragma("unroll") for (int m = 0; m < 4; ++m) _Pragma("unroll") for (int n = 0; n < 2; ++n) _Pragma("unroll") for (int k = 0; k < 2; ++k) \
;         acc[ai][bj][m][n] = __builtin_amdgcn_mfma_f32_16x16x32_bf16(Bt[n][k], At[m][k], acc[ai][bj][m][n], 0, 0, 0); __builtin_amdgcn_s_setprio(0); } while (0)
; #define PG8_WAIT_V(n) asm volatile("s_waitcnt vmcnt(" #n ")" ::: "memory")
; #define PG8_WAIT_L(n) asm volatile("s_waitcnt lgkmcnt(" #n ")" ::: "memory")
; #define PG8_BAR __builtin_amdgcn_s_barrier()
; #define PG8_SCHED __builtin_amdgcn_sched_barrier(0)
; template <class Epi>
; __device__ __forceinline__ void gemm_phase(LAS unsigned char* lds, const int tid, const Gemm g, const StaticOrder& S, const Epi& E) {
;     ...
;             PG8_WAIT_V(8); PG8_WAIT_L(0); PG8_BAR; PG8_MMA(1, 0, At, B0); PG8_MMA(1, 1, At, B1); PG8_BAR; PG8_SCHED;
;             PG8_LDB(B0, 1, 0); PG8_LDB(B1, 1, 1); PG8_SCHED; PG8_LDA(At, 1, 0); PG8_STAGE(PG8_SA(0, 1), a2 + hstepA, voffA);
;             PG8_WAIT_V(8); PG8_WAIT_L(0); PG8_BAR; PG8_MMA(0, 0, At, B0); PG8_MMA(0, 1, At, B1); PG8_BAR; PG8_SCHED;
;             PG8_LDA(At, 1, 1); PG8_STAGE(PG8_SB(1, 0), b3, voffB); PG8_STAGE(PG8_SB(1, 1), b3 + hstepB, voffB); PG8_STAGE(PG8_SA(1, 0), a3, voffA);
;             PG8_WAIT_V(8); PG8_WAIT_L(0); PG8_BAR; PG8_MMA(1, 0, At, B0); PG8_MMA(1, 1, At, B1); PG8_BAR; PG8_SCHED;
	s_setprio 1
	s_waitcnt lgkmcnt(0)
	v_mfma_f32_16x16x32_bf16 v[62:65], v[98:101], v[190:193], v[62:65]
	v_mfma_f32_16x16x32_bf16 v[58:61], v[106:109], v[190:193], v[58:61]
	v_mfma_f32_16x16x32_bf16 v[54:57], v[98:101], v[198:201], v[54:57]
	v_mfma_f32_16x16x32_bf16 v[46:49], v[106:109], v[198:201], v[46:49]
	v_mfma_f32_16x16x32_bf16 v[30:33], v[98:101], v[214:217], v[30:33]
	v_mfma_f32_16x16x32_bf16 v[26:29], v[106:109], v[214:217], v[26:29]
	v_mfma_f32_16x16x32_bf16 v[22:25], v[98:101], v[222:225], v[22:25]
	v_mfma_f32_16x16x32_bf16 v[14:17], v[106:109], v[222:225], v[14:17]
	v_mfma_f32_16x16x32_bf16 v[62:65], v[102:105], v[194:197], v[62:65]
	v_mfma_f32_16x16x32_bf16 v[58:61], v[110:113], v[194:197], v[58:61]
	v_mfma_f32_16x16x32_bf16 v[54:57], v[102:105], v[210:213], v[54:57]
	v_mfma_f32_16x16x32_bf16 v[46:49], v[110:113], v[210:213], v[46:49]
	v_mfma_f32_16x16x32_bf16 v[30:33], v[102:105], v[218:221], v[30:33]
	v_mfma_f32_16x16x32_bf16 v[26:29], v[110:113], v[218:221], v[26:29]
	v_mfma_f32_16x16x32_bf16 v[22:25], v[102:105], v[226:229], v[22:25]
	v_mfma_f32_16x16x32_bf16 v[14:17], v[110:113], v[226:229], v[14:17]
	s_setprio 0
	s_setprio 1
	v_mfma_f32_16x16x32_bf16 v[50:53], v[174:177], v[190:193], v[50:53]
	v_mfma_f32_16x16x32_bf16 v[42:45], v[182:185], v[190:193], v[42:45]
	v_mfma_f32_16x16x32_bf16 v[38:41], v[174:177], v[198:201], v[38:41]
	v_mfma_f32_16x16x32_bf16 v[34:37], v[182:185], v[198:201], v[34:37]
	v_mfma_f32_16x16x32_bf16 v[18:21], v[174:177], v[214:217], v[18:21]
	v_mfma_f32_16x16x32_bf16 v[10:13], v[182:185], v[214:217], v[10:13]
	v_mfma_f32_16x16x32_bf16 v[6:9], v[174:177], v[222:225], v[6:9]
	v_mfma_f32_16x16x32_bf16 v[2:5], v[182:185], v[222:225], v[2:5]
	v_mfma_f32_16x16x32_bf16 v[50:53], v[178:181], v[194:197], v[50:53]
	v_mfma_f32_16x16x32_bf16 v[42:45], v[186:189], v[194:197], v[42:45]
	v_mfma_f32_16x16x32_bf16 v[38:41], v[178:181], v[210:213], v[38:41]
	v_mfma_f32_16x16x32_bf16 v[34:37], v[186:189], v[210:213], v[34:37]
	v_mfma_f32_16x16x32_bf16 v[18:21], v[178:181], v[218:221], v[18:21]
	v_mfma_f32_16x16x32_bf16 v[10:13], v[186:189], v[218:221], v[10:13]
	v_mfma_f32_16x16x32_bf16 v[6:9], v[178:181], v[226:229], v[6:9]
	v_mfma_f32_16x16x32_bf16 v[2:5], v[186:189], v[226:229], v[2:5]
	s_setprio 0
	s_barrier
	s_add_i32 s11, 0, 0x18000
	s_add_i32 s92, 0, 0x1c000
	v_add_u32_e32 v110, s11, v158
	v_add_u32_e32 v173, s92, v158
	ds_read_b128 v[98:101], v110
	ds_read_b128 v[102:105], v110 offset:1024
	ds_read_b128 v[106:109], v110 offset:2048
	ds_read_b128 v[110:113], v110 offset:3072
	ds_read_b128 v[174:177], v173
	ds_read_b128 v[178:181], v173 offset:1024
	ds_read_b128 v[182:185], v173 offset:2048
	ds_read_b128 v[186:189], v173 offset:3072
	s_add_u32 s88, s88, 0x40000
	s_addc_u32 s89, s89, 0
	s_mov_b32 m0, s70
	v_lshl_add_u64 v[230:231], s[88:89], 0, v[150:151]
	global_load_lds_dwordx4 v[230:231], off
	v_lshl_add_u64 v[230:231], s[88:89], 0, v[148:149]
	s_mov_b32 m0, s71
	s_nop 0
	global_load_lds_dwordx4 v[230:231], off
	ds_read_b128 v[190:193], v172 offset:32768
	ds_read_b128 v[194:197], v172 offset:33792
	ds_read_b128 v[198:201], v172 offset:34816
	ds_read_b128 v[210:213], v172 offset:35840
	ds_read_b128 v[214:217], v172 offset:36864
	ds_read_b128 v[218:221], v172 offset:37888
	ds_read_b128 v[222:225], v172 offset:38912
	ds_read_b128 v[226:229], v172 offset:39936
	s_waitcnt vmcnt(8)
	s_waitcnt lgkmcnt(0)
	s_barrier
	s_setprio 1
	s_waitcnt lgkmcnt(0)
	v_mfma_f32_16x16x32_bf16 v[142:145], v[98:101], v[190:193], v[142:145]
	v_mfma_f32_16x16x32_bf16 v[138:141], v[106:109], v[190:193], v[138:141]
	v_mfma_f32_16x16x32_bf16 v[134:137], v[98:101], v[198:201], v[134:137]
	v_mfma_f32_16x16x32_bf16 v[130:133], v[106:109], v[198:201], v[130:133]
	v_mfma_f32_16x16x32_bf16 v[94:97], v[98:101], v[214:217], v[94:97]
	v_mfma_f32_16x16x32_bf16 v[90:93], v[106:109], v[214:217], v[90:93]
	v_mfma_f32_16x16x32_bf16 v[78:81], v[98:101], v[222:225], v[78:81]
	v_mfma_f32_16x16x32_bf16 v[74:77], v[106:109], v[222:225], v[74:77]
	v_mfma_f32_16x16x32_bf16 v[142:145], v[102:105], v[194:197], v[142:145]
	v_mfma_f32_16x16x32_bf16 v[138:141], v[110:113], v[194:197], v[138:141]
	v_mfma_f32_16x16x32_bf16 v[134:137], v[102:105], v[210:213], v[134:137]
	v_mfma_f32_16x16x32_bf16 v[130:133], v[110:113], v[210:213], v[130:133]
	v_mfma_f32_16x16x32_bf16 v[94:97], v[102:105], v[218:221], v[94:97]
	v_mfma_f32_16x16x32_bf16 v[90:93], v[110:113], v[218:221], v[90:93]
	v_mfma_f32_16x16x32_bf16 v[78:81], v[102:105], v[226:229], v[78:81]
	v_mfma_f32_16x16x32_bf16 v[74:77], v[110:113], v[226:229], v[74:77]
	s_setprio 0
	s_setprio 1
	v_mfma_f32_16x16x32_bf16 v[126:129], v[174:177], v[190:193], v[126:129]
	v_mfma_f32_16x16x32_bf16 v[122:125], v[182:185], v[190:193], v[122:125]
	v_mfma_f32_16x16x32_bf16 v[118:121], v[174:177], v[198:201], v[118:121]
	v_mfma_f32_16x16x32_bf16 v[114:117], v[182:185], v[198:201], v[114:117]
	v_mfma_f32_16x16x32_bf16 v[86:89], v[174:177], v[214:217], v[86:89]
	v_mfma_f32_16x16x32_bf16 v[82:85], v[182:185], v[214:217], v[82:85]
	v_mfma_f32_16x16x32_bf16 v[70:73], v[174:177], v[222:225], v[70:73]
	v_mfma_f32_16x16x32_bf16 v[66:69], v[182:185], v[222:225], v[66:69]
	v_mfma_f32_16x16x32_bf16 v[126:129], v[178:181], v[194:197], v[126:129]
	v_mfma_f32_16x16x32_bf16 v[122:125], v[186:189], v[194:197], v[122:125]
	v_mfma_f32_16x16x32_bf16 v[118:121], v[178:181], v[210:213], v[118:121]
	v_mfma_f32_16x16x32_bf16 v[114:117], v[186:189], v[210:213], v[114:117]
	v_mfma_f32_16x16x32_bf16 v[86:89], v[178:181], v[218:221], v[86:89]
	v_mfma_f32_16x16x32_bf16 v[82:85], v[186:189], v[218:221], v[82:85]
	v_mfma_f32_16x16x32_bf16 v[70:73], v[178:181], v[226:229], v[70:73]
	v_mfma_f32_16x16x32_bf16 v[66:69], v[186:189], v[226:229], v[66:69]
	s_setprio 0
	s_barrier
; #define PG8_STAGE(bufoff, gbase, voff) do { _Pragma("unroll") for (int _i = 0; _i < 2; ++_i) \
;         __builtin_amdgcn_global_load_lds((const unsigned*)((const char*)(gbase) + (voff)[_i]), (LAS unsigned*)(lds + (bufoff) + ldsw + _i * 8192), 16, 0, 0); } while (0)
; #define PG8_LDA(dst, b, h) do { _Pragma("unroll") for (int m = 0; m < 4; ++m) _Pragma("unroll") for (int k = 0; k < 2; ++k) dst[m][k] = *(const LAS bf16x8*)(lds + PG8_SA(b, h) + aoff + m * 2048 + k * 1024); } while (0)
; #define PG8_MMA(ai, bj, At, Bt) do { __builtin_amdgcn_s_setprio(1); _Pragma("unroll") for (int m = 0; m < 4; ++m) _Pragma("unroll") for (int n = 0; n < 2; ++n) _Pragma("unroll") for (int k = 0; k < 2; ++k) \
;         acc[ai][bj][m][n] = __builtin_amdgcn_mfma_f32_16x16x32_bf16(Bt[n][k], At[m][k], acc[ai][bj][m][n], 0, 0, 0); __builtin_amdgcn_s_setprio(0); } while (0)
; #define PG8_WAIT_V(n) asm volatile("s_waitcnt vmcnt(" #n ")" ::: "memory")
; #define PG8_WAIT_L(n) asm volatile("s_waitcnt lgkmcnt(" #n ")" ::: "memory")
; #define PG8_BAR __builtin_amdgcn_s_barrier()
; #define PG8_SCHED __builtin_amdgcn_sched_barrier(0)
; template <class Epi>
; __device__ __forceinline__ void gemm_phase(LAS unsigned char* lds, const int tid, const Gemm g, const StaticOrder& S, const Epi& E) {
;     ...
;             PG8_LDA(At, 1, 1); PG8_STAGE(PG8_SB(1, 0), b3, voffB); PG8_STAGE(PG8_SB(1, 1), b3 + hstepB, voffB); PG8_STAGE(PG8_SA(1, 0), a3, voffA);
;             PG8_WAIT_V(8); PG8_WAIT_L(0); PG8_BAR; PG8_MMA(1, 0, At, B0); PG8_MMA(1, 1, At, B1); PG8_BAR; PG8_SCHED;
;         }
;         if (wr == 0) PG8_BAR;
	s_add_i32 s11, s11, s28
	v_lshl_add_u64 v[162:163], v[162:163], 0, s[36:37]
	s_mov_b32 m0, s11
	s_nop 0
	global_load_lds_dwordx4 v[162:163], off
	s_add_i32 m0, s11, 0x2000
	s_add_u32 s30, s30, 0x40080
	v_lshl_add_u64 v[162:163], v[164:165], 0, s[36:37]
	s_addc_u32 s31, s31, 0
	s_add_i32 s11, s92, s28
	global_load_lds_dwordx4 v[162:163], off
	v_lshl_add_u64 v[162:163], s[30:31], 0, v[0:1]
	s_mov_b32 m0, s11
	s_nop 0
	global_load_lds_dwordx4 v[162:163], off
	v_lshl_add_u64 v[162:163], s[30:31], 0, v[146:147]
	s_add_i32 m0, s11, 0x2000
	s_nop 0
	global_load_lds_dwordx4 v[162:163], off
	v_lshl_add_u64 v[162:163], v[202:203], 0, s[36:37]
	s_mov_b32 m0, s72
	s_nop 0
	global_load_lds_dwordx4 v[162:163], off
	v_lshl_add_u64 v[162:163], v[206:207], 0, s[36:37]
	s_mov_b32 m0, s73
	s_nop 0
	global_load_lds_dwordx4 v[162:163], off
	ds_read_b128 v[190:193], v172 offset:49152
	ds_read_b128 v[194:197], v172 offset:50176
	ds_read_b128 v[198:201], v172 offset:51200
	ds_read_b128 v[210:213], v172 offset:52224
	ds_read_b128 v[214:217], v172 offset:53248
	ds_read_b128 v[218:221], v172 offset:54272
	ds_read_b128 v[222:225], v172 offset:55296
	ds_read_b128 v[226:229], v172 offset:56320
	s_waitcnt vmcnt(8)
	s_waitcnt lgkmcnt(0)
	s_barrier
	s_setprio 1
	s_waitcnt lgkmcnt(0)
	v_mfma_f32_16x16x32_bf16 v[62:65], v[98:101], v[190:193], v[62:65]
	v_mfma_f32_16x16x32_bf16 v[58:61], v[106:109], v[190:193], v[58:61]
	v_mfma_f32_16x16x32_bf16 v[54:57], v[98:101], v[198:201], v[54:57]
	v_mfma_f32_16x16x32_bf16 v[46:49], v[106:109], v[198:201], v[46:49]
	v_mfma_f32_16x16x32_bf16 v[30:33], v[98:101], v[214:217], v[30:33]
	v_mfma_f32_16x16x32_bf16 v[26:29], v[106:109], v[214:217], v[26:29]
	v_mfma_f32_16x16x32_bf16 v[22:25], v[98:101], v[222:225], v[22:25]
	v_mfma_f32_16x16x32_bf16 v[14:17], v[106:109], v[222:225], v[14:17]
	v_mfma_f32_16x16x32_bf16 v[62:65], v[102:105], v[194:197], v[62:65]
	v_mfma_f32_16x16x32_bf16 v[58:61], v[110:113], v[194:197], v[58:61]
	v_mfma_f32_16x16x32_bf16 v[54:57], v[102:105], v[210:213], v[54:57]
	v_mfma_f32_16x16x32_bf16 v[46:49], v[110:113], v[210:213], v[46:49]
	v_mfma_f32_16x16x32_bf16 v[30:33], v[102:105], v[218:221], v[30:33]
	v_mfma_f32_16x16x32_bf16 v[26:29], v[110:113], v[218:221], v[26:29]
	v_mfma_f32_16x16x32_bf16 v[22:25], v[102:105], v[226:229], v[22:25]
	v_mfma_f32_16x16x32_bf16 v[14:17], v[110:113], v[226:229], v[14:17]
	s_setprio 0
	s_setprio 1
	v_mfma_f32_16x16x32_bf16 v[50:53], v[174:177], v[190:193], v[50:53]
	v_mfma_f32_16x16x32_bf16 v[42:45], v[182:185], v[190:193], v[42:45]
	v_mfma_f32_16x16x32_bf16 v[38:41], v[174:177], v[198:201], v[38:41]
	v_mfma_f32_16x16x32_bf16 v[34:37], v[182:185], v[198:201], v[34:37]
	v_mfma_f32_16x16x32_bf16 v[18:21], v[174:177], v[214:217], v[18:21]
	v_mfma_f32_16x16x32_bf16 v[10:13], v[182:185], v[214:217], v[10:13]
	v_mfma_f32_16x16x32_bf16 v[6:9], v[174:177], v[222:225], v[6:9]
	v_mfma_f32_16x16x32_bf16 v[2:5], v[182:185], v[222:225], v[2:5]
	v_mfma_f32_16x16x32_bf16 v[50:53], v[178:181], v[194:197], v[50:53]
	v_mfma_f32_16x16x32_bf16 v[42:45], v[186:189], v[194:197], v[42:45]
	v_mfma_f32_16x16x32_bf16 v[38:41], v[178:181], v[210:213], v[38:41]
	v_mfma_f32_16x16x32_bf16 v[34:37], v[186:189], v[210:213], v[34:37]
	v_mfma_f32_16x16x32_bf16 v[18:21], v[178:181], v[218:221], v[18:21]
	v_mfma_f32_16x16x32_bf16 v[10:13], v[186:189], v[218:221], v[10:13]
	v_mfma_f32_16x16x32_bf16 v[6:9], v[178:181], v[226:229], v[6:9]
	v_mfma_f32_16x16x32_bf16 v[2:5], v[186:189], v[226:229], v[2:5]
	s_setprio 0
	s_barrier
	s_add_i32 s17, s17, 2
	s_add_u32 s82, s82, 0x100
	s_addc_u32 s83, s83, 0
	s_add_u32 vcc_hi, vcc_hi, 0x100
	s_addc_u32 s27, s27, 0
	s_cmp_gt_u32 s17, 13
	s_cbranch_scc0 .LBB0_1912
	s_and_b64 vcc, exec, s[2:3]
	s_cbranch_vccz .LBB0_1915
	s_barrier

; #define PG8_STAGE(bufoff, gbase, voff) do { _Pragma("unroll") for (int _i = 0; _i < 2; ++_i) \
;         __builtin_amdgcn_global_load_lds((const unsigned*)((const char*)(gbase) + (voff)[_i]), (LAS unsigned*)(lds + (bufoff) + ldsw + _i * 8192), 16, 0, 0); } while (0)
; #define PG8_LDA(dst, b, h) do { _Pragma("unroll") for (int m = 0; m < 4; ++m) _Pragma("unroll") for (int k = 0; k < 2; ++k) dst[m][k] = *(const LAS bf16x8*)(lds + PG8_SA(b, h) + aoff + m * 2048 + k * 1024); } while (0)
; #define PG8_LDB(dst, b, h) do { _Pragma("unroll") for (int n = 0; n < 2; ++n) _Pragma("unroll") for (int k = 0; k < 2; ++k) dst[n][k] = *(const LAS bf16x8*)(lds + PG8_SB(b, h) + boff + n * 2048 + k * 1024); } while (0)
; #define PG8_MMA(ai, bj, At, Bt) do { __builtin_amdgcn_s_setprio(1); _Pragma("unroll") for (int m = 0; m < 4; ++m) _Pragma("unroll") for (int n = 0; n < 2; ++n) _Pragma("unroll") for (int k = 0; k < 2; ++k) \
;         acc[ai][bj][m][n] = __builtin_amdgcn_mfma_f32_16x16x32_bf16(Bt[n][k], At[m][k], acc[ai][bj][m][n], 0, 0, 0); __builtin_amdgcn_s_setprio(0); } while (0)
; #define PG8_WAIT_V(n) asm volatile("s_waitcnt vmcnt(" #n ")" ::: "memory")
; #define PG8_WAIT_L(n) asm volatile("s_waitcnt lgkmcnt(" #n ")" ::: "memory")
; #define PG8_BAR __builtin_amdgcn_s_barrier()
; #define PG8_SCHED __builtin_amdgcn_sched_barrier(0)
; template <class Epi>
; __device__ __forceinline__ void gemm_phase(LAS unsigned char* lds, const int tid, const Gemm g, const StaticOrder& S, const Epi& E) {
;     ...
;         for (int t = 0; t < nt; t += 2) {
;             const bool last = (t == nt - 2);
;             const char* a1 = cA + (size_t)(t + 1) * kstep;
;             const char* a2 = last ? nA : cA + (size_t)(t + 2) * kstep; const char* b2 = last ? nB : cB + (size_t)(t + 2) * kstep;
;             const char* a3 = a2 + kstep; const char* b3 = b2 + kstep;
;             PG8_LDB(B0, 0, 0); PG8_LDB(B1, 0, 1); PG8_SCHED; PG8_LDA(At, 0, 0); PG8_STAGE(PG8_SA(1, 1), a1 + hstepA, voffA);
;             PG8_WAIT_V(8); PG8_WAIT_L(0); PG8_BAR; PG8_MMA(0, 0, At, B0); PG8_MMA(0, 1, At, B1); PG8_BAR; PG8_SCHED;
;             PG8_LDA(At, 0, 1); PG8_STAGE(PG8_SB(0, 0), b2, voffB); PG8_STAGE(PG8_SB(0, 1), b2 + hstepB, voffB); PG8_STAGE(PG8_SA(0, 0), a2, voffA);
;             PG8_WAIT_V(8); PG8_WAIT_L(0); PG8_BAR; PG8_MMA(1, 0, At, B0); PG8_MMA(1, 1, At, B1); PG8_BAR; PG8_SCHED;
.LBB0_2193:
	s_add_u32 s70, s30, 0x100
	s_addc_u32 s71, s31, 0
	s_add_i32 s76, 0, 0x10000
	s_cmp_eq_u32 vcc_hi, 40
	s_cselect_b32 s75, s1, s71
	s_cselect_b32 s74, s0, s70
	s_cselect_b32 s73, s69, vcc_lo
	s_cselect_b32 s72, s68, s28
	s_add_i32 s2, 0, 0x14000
	v_add_u32_e32 v154, s76, v179
	v_add_u32_e32 v162, s2, v179
	ds_read_b128 v[130:133], v154
	ds_read_b128 v[134:137], v154 offset:1024
	ds_read_b128 v[138:141], v154 offset:2048
	ds_read_b128 v[154:157], v154 offset:3072
	ds_read_b128 v[158:161], v162
	ds_read_b128 v[170:173], v162 offset:1024
	ds_read_b128 v[174:177], v162 offset:2048
	ds_read_b128 v[184:187], v162 offset:3072
	v_lshl_add_u64 v[162:163], s[30:31], 0, v[150:151]
	s_add_i32 m0, s5, 0xc000
	s_nop 0
	global_load_lds_dwordx4 v[162:163], off
	v_lshl_add_u64 v[162:163], s[30:31], 0, v[152:153]
	s_add_i32 m0, s5, 0xe000
	s_nop 0
	global_load_lds_dwordx4 v[162:163], off
	ds_read_b128 v[188:191], v181
	ds_read_b128 v[192:195], v181 offset:1024
	ds_read_b128 v[196:199], v181 offset:2048
	ds_read_b128 v[200:203], v181 offset:3072
	ds_read_b128 v[212:215], v181 offset:4096
	ds_read_b128 v[216:219], v181 offset:5120
	ds_read_b128 v[220:223], v181 offset:6144
	ds_read_b128 v[224:227], v181 offset:7168
	s_waitcnt vmcnt(8)
	s_waitcnt lgkmcnt(0)
	s_barrier
	s_setprio 1
	s_waitcnt lgkmcnt(0)
	v_mfma_f32_16x16x32_bf16 v[126:129], v[130:133], v[188:191], v[126:129]
	v_mfma_f32_16x16x32_bf16 v[122:125], v[138:141], v[188:191], v[122:125]
	v_mfma_f32_16x16x32_bf16 v[110:113], v[130:133], v[196:199], v[110:113]
	v_mfma_f32_16x16x32_bf16 v[106:109], v[138:141], v[196:199], v[106:109]
	v_mfma_f32_16x16x32_bf16 v[94:97], v[130:133], v[212:215], v[94:97]
	v_mfma_f32_16x16x32_bf16 v[90:93], v[138:141], v[212:215], v[90:93]
	v_mfma_f32_16x16x32_bf16 v[78:81], v[130:133], v[220:223], v[78:81]
	v_mfma_f32_16x16x32_bf16 v[74:77], v[138:141], v[220:223], v[74:77]
	v_mfma_f32_16x16x32_bf16 v[126:129], v[134:137], v[192:195], v[126:129]
	v_mfma_f32_16x16x32_bf16 v[122:125], v[154:157], v[192:195], v[122:125]
	v_mfma_f32_16x16x32_bf16 v[110:113], v[134:137], v[200:203], v[110:113]
	v_mfma_f32_16x16x32_bf16 v[106:109], v[154:157], v[200:203], v[106:109]
	v_mfma_f32_16x16x32_bf16 v[94:97], v[134:137], v[216:219], v[94:97]
	v_mfma_f32_16x16x32_bf16 v[90:93], v[154:157], v[216:219], v[90:93]
	v_mfma_f32_16x16x32_bf16 v[78:81], v[134:137], v[224:227], v[78:81]
	v_mfma_f32_16x16x32_bf16 v[74:77], v[154:157], v[224:227], v[74:77]
	s_setprio 0
	s_setprio 1
	v_mfma_f32_16x16x32_bf16 v[118:121], v[158:161], v[188:191], v[118:121]
	v_mfma_f32_16x16x32_bf16 v[114:117], v[174:177], v[188:191], v[114:117]
	v_mfma_f32_16x16x32_bf16 v[102:105], v[158:161], v[196:199], v[102:105]
	v_mfma_f32_16x16x32_bf16 v[98:101], v[174:177], v[196:199], v[98:101]
	v_mfma_f32_16x16x32_bf16 v[86:89], v[158:161], v[212:215], v[86:89]
	v_mfma_f32_16x16x32_bf16 v[82:85], v[174:177], v[212:215], v[82:85]
	v_mfma_f32_16x16x32_bf16 v[70:73], v[158:161], v[220:223], v[70:73]
	v_mfma_f32_16x16x32_bf16 v[66:69], v[174:177], v[220:223], v[66:69]
	v_mfma_f32_16x16x32_bf16 v[118:121], v[170:173], v[192:195], v[118:121]
	v_mfma_f32_16x16x32_bf16 v[114:117], v[184:187], v[192:195], v[114:117]
	v_mfma_f32_16x16x32_bf16 v[102:105], v[170:173], v[200:203], v[102:105]
	v_mfma_f32_16x16x32_bf16 v[98:101], v[184:187], v[200:203], v[98:101]
	v_mfma_f32_16x16x32_bf16 v[86:89], v[170:173], v[216:219], v[86:89]
	v_mfma_f32_16x16x32_bf16 v[82:85], v[184:187], v[216:219], v[82:85]
	v_mfma_f32_16x16x32_bf16 v[70:73], v[170:173], v[224:227], v[70:73]
	v_mfma_f32_16x16x32_bf16 v[66:69], v[184:187], v[224:227], v[66:69]
	s_setprio 0
	s_barrier
	s_add_i32 s3, s76, s4
	v_lshl_add_u64 v[162:163], s[72:73], 0, v[0:1]
	s_mov_b32 m0, s3
	s_nop 0
	global_load_lds_dwordx4 v[162:163], off
	s_add_i32 m0, s3, 0x2000
	s_add_u32 s30, s72, 0xb0000
	v_lshl_add_u64 v[164:165], s[72:73], 0, v[148:149]
	s_addc_u32 s31, s73, 0
	s_add_i32 s2, s2, s4
	global_load_lds_dwordx4 v[164:165], off
	v_lshl_add_u64 v[206:207], s[30:31], 0, v[0:1]
	s_mov_b32 m0, s2
	v_lshl_add_u64 v[228:229], s[74:75], 0, v[144:145]
	global_load_lds_dwordx4 v[206:207], off
	v_lshl_add_u64 v[206:207], s[30:31], 0, v[148:149]
	s_add_i32 m0, s2, 0x2000
	s_nop 0
	global_load_lds_dwordx4 v[206:207], off
	v_lshl_add_u64 v[206:207], s[74:75], 0, v[142:143]
	s_mov_b32 m0, s5
	s_nop 0
	global_load_lds_dwordx4 v[206:207], off
	s_mov_b32 m0, s6
	s_nop 0
	global_load_lds_dwordx4 v[228:229], off
	ds_read_b128 v[188:191], v181 offset:16384
	ds_read_b128 v[192:195], v181 offset:17408
	ds_read_b128 v[196:199], v181 offset:18432
	ds_read_b128 v[200:203], v181 offset:19456
	ds_read_b128 v[212:215], v181 offset:20480
	ds_read_b128 v[216:219], v181 offset:21504
	ds_read_b128 v[220:223], v181 offset:22528
	ds_read_b128 v[224:227], v181 offset:23552
	s_waitcnt vmcnt(8)
	s_waitcnt lgkmcnt(0)
	s_barrier
; #define PG8_STAGE(bufoff, gbase, voff) do { _Pragma("unroll") for (int _i = 0; _i < 2; ++_i) \
;         __builtin_amdgcn_global_load_lds((const unsigned*)((const char*)(gbase) + (voff)[_i]), (LAS unsigned*)(lds + (bufoff) + ldsw + _i * 8192), 16, 0, 0); } while (0)
; #define PG8_LDA(dst, b, h) do { _Pragma("unroll") for (int m = 0; m < 4; ++m) _Pragma("unroll") for (int k = 0; k < 2; ++k) dst[m][k] = *(const LAS bf16x8*)(lds + PG8_SA(b, h) + aoff + m * 2048 + k * 1024); } while (0)
; #define PG8_LDB(dst, b, h) do { _Pragma("unroll") for (int n = 0; n < 2; ++n) _Pragma("unroll") for (int k = 0; k < 2; ++k) dst[n][k] = *(const LAS bf16x8*)(lds + PG8_SB(b, h) + boff + n * 2048 + k * 1024); } while (0)
; #define PG8_MMA(ai, bj, At, Bt) do { __builtin_amdgcn_s_setprio(1); _Pragma("unroll") for (int m = 0; m < 4; ++m) _Pragma("unroll") for (int n = 0; n < 2; ++n) _Pragma("unroll") for (int k = 0; k < 2; ++k) \
;         acc[ai][bj][m][n] = __builtin_amdgcn_mfma_f32_16x16x32_bf16(Bt[n][k], At[m][k], acc[ai][bj][m][n], 0, 0, 0); __builtin_amdgcn_s_setprio(0); } while (0)
; #define PG8_WAIT_V(n) asm volatile("s_waitcnt vmcnt(" #n ")" ::: "memory")
; #define PG8_WAIT_L(n) asm volatile("s_waitcnt lgkmcnt(" #n ")" ::: "memory")
; #define PG8_BAR __builtin_amdgcn_s_barrier()
; #define PG8_SCHED __builtin_amdgcn_sched_barrier(0)
; template <class Epi>
; __device__ __forceinline__ void gemm_phase(LAS unsigned char* lds, const int tid, const Gemm g, const StaticOrder& S, const Epi& E) {
;     ...
;             PG8_WAIT_V(8); PG8_WAIT_L(0); PG8_BAR; PG8_MMA(1, 0, At, B0); PG8_MMA(1, 1, At, B1); PG8_BAR; PG8_SCHED;
;             PG8_LDB(B0, 1, 0); PG8_LDB(B1, 1, 1); PG8_SCHED; PG8_LDA(At, 1, 0); PG8_STAGE(PG8_SA(0, 1), a2 + hstepA, voffA);
;             PG8_WAIT_V(8); PG8_WAIT_L(0); PG8_BAR; PG8_MMA(0, 0, At, B0); PG8_MMA(0, 1, At, B1); PG8_BAR; PG8_SCHED;
;             PG8_LDA(At, 1, 1); PG8_STAGE(PG8_SB(1, 0), b3, voffB); PG8_STAGE(PG8_SB(1, 1), b3 + hstepB, voffB); PG8_STAGE(PG8_SA(1, 0), a3, voffA);
;             PG8_WAIT_V(8); PG8_WAIT_L(0); PG8_BAR; PG8_MMA(1, 0, At, B0); PG8_MMA(1, 1, At, B1); PG8_BAR; PG8_SCHED;
	s_setprio 1
	s_waitcnt lgkmcnt(0)
	v_mfma_f32_16x16x32_bf16 v[62:65], v[130:133], v[188:191], v[62:65]
	v_mfma_f32_16x16x32_bf16 v[58:61], v[138:141], v[188:191], v[58:61]
	v_mfma_f32_16x16x32_bf16 v[46:49], v[130:133], v[196:199], v[46:49]
	v_mfma_f32_16x16x32_bf16 v[42:45], v[138:141], v[196:199], v[42:45]
	v_mfma_f32_16x16x32_bf16 v[30:33], v[130:133], v[212:215], v[30:33]
	v_mfma_f32_16x16x32_bf16 v[26:29], v[138:141], v[212:215], v[26:29]
	v_mfma_f32_16x16x32_bf16 v[14:17], v[130:133], v[220:223], v[14:17]
	v_mfma_f32_16x16x32_bf16 v[10:13], v[138:141], v[220:223], v[10:13]
	v_mfma_f32_16x16x32_bf16 v[62:65], v[134:137], v[192:195], v[62:65]
	v_mfma_f32_16x16x32_bf16 v[58:61], v[154:157], v[192:195], v[58:61]
	v_mfma_f32_16x16x32_bf16 v[46:49], v[134:137], v[200:203], v[46:49]
	v_mfma_f32_16x16x32_bf16 v[42:45], v[154:157], v[200:203], v[42:45]
	v_mfma_f32_16x16x32_bf16 v[30:33], v[134:137], v[216:219], v[30:33]
	v_mfma_f32_16x16x32_bf16 v[26:29], v[154:157], v[216:219], v[26:29]
	v_mfma_f32_16x16x32_bf16 v[14:17], v[134:137], v[224:227], v[14:17]
	v_mfma_f32_16x16x32_bf16 v[10:13], v[154:157], v[224:227], v[10:13]
	s_setprio 0
	s_setprio 1
	v_mfma_f32_16x16x32_bf16 v[54:57], v[158:161], v[188:191], v[54:57]
	v_mfma_f32_16x16x32_bf16 v[50:53], v[174:177], v[188:191], v[50:53]
	v_mfma_f32_16x16x32_bf16 v[38:41], v[158:161], v[196:199], v[38:41]
	v_mfma_f32_16x16x32_bf16 v[34:37], v[174:177], v[196:199], v[34:37]
	v_mfma_f32_16x16x32_bf16 v[22:25], v[158:161], v[212:215], v[22:25]
	v_mfma_f32_16x16x32_bf16 v[18:21], v[174:177], v[212:215], v[18:21]
	v_mfma_f32_16x16x32_bf16 v[6:9], v[158:161], v[220:223], v[6:9]
	v_mfma_f32_16x16x32_bf16 v[2:5], v[174:177], v[220:223], v[2:5]
	v_mfma_f32_16x16x32_bf16 v[54:57], v[170:173], v[192:195], v[54:57]
	v_mfma_f32_16x16x32_bf16 v[50:53], v[184:187], v[192:195], v[50:53]
	v_mfma_f32_16x16x32_bf16 v[38:41], v[170:173], v[200:203], v[38:41]
	v_mfma_f32_16x16x32_bf16 v[34:37], v[184:187], v[200:203], v[34:37]
	v_mfma_f32_16x16x32_bf16 v[22:25], v[170:173], v[216:219], v[22:25]
	v_mfma_f32_16x16x32_bf16 v[18:21], v[184:187], v[216:219], v[18:21]
	v_mfma_f32_16x16x32_bf16 v[6:9], v[170:173], v[224:227], v[6:9]
	v_mfma_f32_16x16x32_bf16 v[2:5], v[184:187], v[224:227], v[2:5]
	s_setprio 0
	s_barrier
	s_add_i32 s2, 0, 0x18000
	s_add_i32 s3, 0, 0x1c000
	v_add_u32_e32 v154, s2, v179
	v_add_u32_e32 v183, s3, v179
	ds_read_b128 v[130:133], v154
	ds_read_b128 v[134:137], v154 offset:1024
	ds_read_b128 v[138:141], v154 offset:2048
	ds_read_b128 v[154:157], v154 offset:3072
	ds_read_b128 v[158:161], v183
	ds_read_b128 v[170:173], v183 offset:1024
	ds_read_b128 v[174:177], v183 offset:2048
	ds_read_b128 v[184:187], v183 offset:3072
	s_add_u32 s30, s74, 0x160000
	s_addc_u32 s31, s75, 0
	s_mov_b32 m0, s7
	v_lshl_add_u64 v[230:231], s[30:31], 0, v[142:143]
	global_load_lds_dwordx4 v[230:231], off
	v_lshl_add_u64 v[230:231], s[30:31], 0, v[144:145]
	s_mov_b32 m0, s77
	s_nop 0
	global_load_lds_dwordx4 v[230:231], off
	ds_read_b128 v[188:191], v181 offset:32768
	ds_read_b128 v[192:195], v181 offset:33792
	ds_read_b128 v[196:199], v181 offset:34816
	ds_read_b128 v[200:203], v181 offset:35840
	ds_read_b128 v[212:215], v181 offset:36864
	ds_read_b128 v[216:219], v181 offset:37888
	ds_read_b128 v[220:223], v181 offset:38912
	ds_read_b128 v[224:227], v181 offset:39936
	s_waitcnt vmcnt(8)
	s_waitcnt lgkmcnt(0)
	s_barrier
	s_setprio 1
	s_waitcnt lgkmcnt(0)
	v_mfma_f32_16x16x32_bf16 v[126:129], v[130:133], v[188:191], v[126:129]
	v_mfma_f32_16x16x32_bf16 v[122:125], v[138:141], v[188:191], v[122:125]
	v_mfma_f32_16x16x32_bf16 v[110:113], v[130:133], v[196:199], v[110:113]
	v_mfma_f32_16x16x32_bf16 v[106:109], v[138:141], v[196:199], v[106:109]
	v_mfma_f32_16x16x32_bf16 v[94:97], v[130:133], v[212:215], v[94:97]
	v_mfma_f32_16x16x32_bf16 v[90:93], v[138:141], v[212:215], v[90:93]
	v_mfma_f32_16x16x32_bf16 v[78:81], v[130:133], v[220:223], v[78:81]
	v_mfma_f32_16x16x32_bf16 v[74:77], v[138:141], v[220:223], v[74:77]
	v_mfma_f32_16x16x32_bf16 v[126:129], v[134:137], v[192:195], v[126:129]
	v_mfma_f32_16x16x32_bf16 v[122:125], v[154:157], v[192:195], v[122:125]
	v_mfma_f32_16x16x32_bf16 v[110:113], v[134:137], v[200:203], v[110:113]
	v_mfma_f32_16x16x32_bf16 v[106:109], v[154:157], v[200:203], v[106:109]
	v_mfma_f32_16x16x32_bf16 v[94:97], v[134:137], v[216:219], v[94:97]
	v_mfma_f32_16x16x32_bf16 v[90:93], v[154:157], v[216:219], v[90:93]
	v_mfma_f32_16x16x32_bf16 v[78:81], v[134:137], v[224:227], v[78:81]
	v_mfma_f32_16x16x32_bf16 v[74:77], v[154:157], v[224:227], v[74:77]
	s_setprio 0
	s_setprio 1
	v_mfma_f32_16x16x32_bf16 v[118:121], v[158:161], v[188:191], v[118:121]
	v_mfma_f32_16x16x32_bf16 v[114:117], v[174:177], v[188:191], v[114:117]
	v_mfma_f32_16x16x32_bf16 v[102:105], v[158:161], v[196:199], v[102:105]
	v_mfma_f32_16x16x32_bf16 v[98:101], v[174:177], v[196:199], v[98:101]
	v_mfma_f32_16x16x32_bf16 v[86:89], v[158:161], v[212:215], v[86:89]
	v_mfma_f32_16x16x32_bf16 v[82:85], v[174:177], v[212:215], v[82:85]
	v_mfma_f32_16x16x32_bf16 v[70:73], v[158:161], v[220:223], v[70:73]
	v_mfma_f32_16x16x32_bf16 v[66:69], v[174:177], v[220:223], v[66:69]
	v_mfma_f32_16x16x32_bf16 v[118:121], v[170:173], v[192:195], v[118:121]
	v_mfma_f32_16x16x32_bf16 v[114:117], v[184:187], v[192:195], v[114:117]
	v_mfma_f32_16x16x32_bf16 v[102:105], v[170:173], v[200:203], v[102:105]
	v_mfma_f32_16x16x32_bf16 v[98:101], v[184:187], v[200:203], v[98:101]
	v_mfma_f32_16x16x32_bf16 v[86:89], v[170:173], v[216:219], v[86:89]
	v_mfma_f32_16x16x32_bf16 v[82:85], v[184:187], v[216:219], v[82:85]
	v_mfma_f32_16x16x32_bf16 v[70:73], v[170:173], v[224:227], v[70:73]
	v_mfma_f32_16x16x32_bf16 v[66:69], v[184:187], v[224:227], v[66:69]
	s_setprio 0
	s_barrier
; #define PG8_STAGE(bufoff, gbase, voff) do { _Pragma("unroll") for (int _i = 0; _i < 2; ++_i) \
;         __builtin_amdgcn_global_load_lds((const unsigned*)((const char*)(gbase) + (voff)[_i]), (LAS unsigned*)(lds + (bufoff) + ldsw + _i * 8192), 16, 0, 0); } while (0)
; #define PG8_LDA(dst, b, h) do { _Pragma("unroll") for (int m = 0; m < 4; ++m) _Pragma("unroll") for (int k = 0; k < 2; ++k) dst[m][k] = *(const LAS bf16x8*)(lds + PG8_SA(b, h) + aoff + m * 2048 + k * 1024); } while (0)
; #define PG8_MMA(ai, bj, At, Bt) do { __builtin_amdgcn_s_setprio(1); _Pragma("unroll") for (int m = 0; m < 4; ++m) _Pragma("unroll") for (int n = 0; n < 2; ++n) _Pragma("unroll") for (int k = 0; k < 2; ++k) \
;         acc[ai][bj][m][n] = __builtin_amdgcn_mfma_f32_16x16x32_bf16(Bt[n][k], At[m][k], acc[ai][bj][m][n], 0, 0, 0); __builtin_amdgcn_s_setprio(0); } while (0)
; #define PG8_WAIT_V(n) asm volatile("s_waitcnt vmcnt(" #n ")" ::: "memory")
; #define PG8_WAIT_L(n) asm volatile("s_waitcnt lgkmcnt(" #n ")" ::: "memory")
; #define PG8_BAR __builtin_amdgcn_s_barrier()
; #define PG8_SCHED __builtin_amdgcn_sched_barrier(0)
; template <class Epi>
; __device__ __forceinline__ void gemm_phase(LAS unsigned char* lds, const int tid, const Gemm g, const StaticOrder& S, const Epi& E) {
;     ...
;             PG8_LDA(At, 1, 1); PG8_STAGE(PG8_SB(1, 0), b3, voffB); PG8_STAGE(PG8_SB(1, 1), b3 + hstepB, voffB); PG8_STAGE(PG8_SA(1, 0), a3, voffA);
;             PG8_WAIT_V(8); PG8_WAIT_L(0); PG8_BAR; PG8_MMA(1, 0, At, B0); PG8_MMA(1, 1, At, B1); PG8_BAR; PG8_SCHED;
;         }
;         if (wr == 0) PG8_BAR;
	s_add_i32 s2, s2, s4
	v_lshl_add_u64 v[162:163], v[162:163], 0, s[36:37]
	s_mov_b32 m0, s2
	s_nop 0
	global_load_lds_dwordx4 v[162:163], off
	s_add_i32 m0, s2, 0x2000
	s_add_u32 s30, s72, 0xb0080
	v_lshl_add_u64 v[162:163], v[164:165], 0, s[36:37]
	s_addc_u32 s31, s73, 0
	s_add_i32 s2, s3, s4
	global_load_lds_dwordx4 v[162:163], off
	v_lshl_add_u64 v[162:163], s[30:31], 0, v[0:1]
	s_mov_b32 m0, s2
	s_nop 0
	global_load_lds_dwordx4 v[162:163], off
	v_lshl_add_u64 v[162:163], s[30:31], 0, v[148:149]
	s_add_i32 m0, s2, 0x2000
	s_nop 0
	global_load_lds_dwordx4 v[162:163], off
	v_lshl_add_u64 v[162:163], v[206:207], 0, s[36:37]
	s_mov_b32 m0, s83
	s_nop 0
	global_load_lds_dwordx4 v[162:163], off
	v_lshl_add_u64 v[162:163], v[228:229], 0, s[36:37]
	s_mov_b32 m0, s88
	s_nop 0
	global_load_lds_dwordx4 v[162:163], off
	ds_read_b128 v[188:191], v181 offset:49152
	ds_read_b128 v[192:195], v181 offset:50176
	ds_read_b128 v[196:199], v181 offset:51200
	ds_read_b128 v[200:203], v181 offset:52224
	ds_read_b128 v[212:215], v181 offset:53248
	ds_read_b128 v[216:219], v181 offset:54272
	ds_read_b128 v[220:223], v181 offset:55296
	ds_read_b128 v[224:227], v181 offset:56320
	s_waitcnt vmcnt(8)
	s_waitcnt lgkmcnt(0)
	s_barrier
	s_setprio 1
	s_waitcnt lgkmcnt(0)
	v_mfma_f32_16x16x32_bf16 v[62:65], v[130:133], v[188:191], v[62:65]
	v_mfma_f32_16x16x32_bf16 v[58:61], v[138:141], v[188:191], v[58:61]
	v_mfma_f32_16x16x32_bf16 v[46:49], v[130:133], v[196:199], v[46:49]
	v_mfma_f32_16x16x32_bf16 v[42:45], v[138:141], v[196:199], v[42:45]
	v_mfma_f32_16x16x32_bf16 v[30:33], v[130:133], v[212:215], v[30:33]
	v_mfma_f32_16x16x32_bf16 v[26:29], v[138:141], v[212:215], v[26:29]
	v_mfma_f32_16x16x32_bf16 v[14:17], v[130:133], v[220:223], v[14:17]
	v_mfma_f32_16x16x32_bf16 v[10:13], v[138:141], v[220:223], v[10:13]
	v_mfma_f32_16x16x32_bf16 v[62:65], v[134:137], v[192:195], v[62:65]
	v_mfma_f32_16x16x32_bf16 v[58:61], v[154:157], v[192:195], v[58:61]
	v_mfma_f32_16x16x32_bf16 v[46:49], v[134:137], v[200:203], v[46:49]
	v_mfma_f32_16x16x32_bf16 v[42:45], v[154:157], v[200:203], v[42:45]
	v_mfma_f32_16x16x32_bf16 v[30:33], v[134:137], v[216:219], v[30:33]
	v_mfma_f32_16x16x32_bf16 v[26:29], v[154:157], v[216:219], v[26:29]
	v_mfma_f32_16x16x32_bf16 v[14:17], v[134:137], v[224:227], v[14:17]
	v_mfma_f32_16x16x32_bf16 v[10:13], v[154:157], v[224:227], v[10:13]
	s_setprio 0
	s_setprio 1
	v_mfma_f32_16x16x32_bf16 v[54:57], v[158:161], v[188:191], v[54:57]
	v_mfma_f32_16x16x32_bf16 v[50:53], v[174:177], v[188:191], v[50:53]
	v_mfma_f32_16x16x32_bf16 v[38:41], v[158:161], v[196:199], v[38:41]
	v_mfma_f32_16x16x32_bf16 v[34:37], v[174:177], v[196:199], v[34:37]
	v_mfma_f32_16x16x32_bf16 v[22:25], v[158:161], v[212:215], v[22:25]
	v_mfma_f32_16x16x32_bf16 v[18:21], v[174:177], v[212:215], v[18:21]
	v_mfma_f32_16x16x32_bf16 v[6:9], v[158:161], v[220:223], v[6:9]
	v_mfma_f32_16x16x32_bf16 v[2:5], v[174:177], v[220:223], v[2:5]
	v_mfma_f32_16x16x32_bf16 v[54:57], v[170:173], v[192:195], v[54:57]
	v_mfma_f32_16x16x32_bf16 v[50:53], v[184:187], v[192:195], v[50:53]
	v_mfma_f32_16x16x32_bf16 v[38:41], v[170:173], v[200:203], v[38:41]
	v_mfma_f32_16x16x32_bf16 v[34:37], v[184:187], v[200:203], v[34:37]
	v_mfma_f32_16x16x32_bf16 v[22:25], v[170:173], v[216:219], v[22:25]
	v_mfma_f32_16x16x32_bf16 v[18:21], v[184:187], v[216:219], v[18:21]
	v_mfma_f32_16x16x32_bf16 v[6:9], v[170:173], v[224:227], v[6:9]
	v_mfma_f32_16x16x32_bf16 v[2:5], v[184:187], v[224:227], v[2:5]
	s_setprio 0
	s_barrier
	s_add_i32 vcc_hi, vcc_hi, 2
	s_add_u32 s28, s28, 0x100
	s_addc_u32 vcc_lo, vcc_lo, 0
	s_cmp_gt_u32 vcc_hi, 41
	s_mov_b64 s[30:31], s[70:71]
	s_cbranch_scc0 .LBB0_2193
	s_and_b64 vcc, exec, s[26:27]
	s_cbranch_vccz .LBB0_2196
	s_barrier

; #define PG8_STAGE(bufoff, gbase, voff) do { _Pragma("unroll") for (int _i = 0; _i < 2; ++_i) \
;         __builtin_amdgcn_global_load_lds((const unsigned*)((const char*)(gbase) + (voff)[_i]), (LAS unsigned*)(lds + (bufoff) + ldsw + _i * 8192), 16, 0, 0); } while (0)
; #define PG8_LDA(dst, b, h) do { _Pragma("unroll") for (int m = 0; m < 4; ++m) _Pragma("unroll") for (int k = 0; k < 2; ++k) dst[m][k] = *(const LAS bf16x8*)(lds + PG8_SA(b, h) + aoff + m * 2048 + k * 1024); } while (0)
; #define PG8_LDB(dst, b, h) do { _Pragma("unroll") for (int n = 0; n < 2; ++n) _Pragma("unroll") for (int k = 0; k < 2; ++k) dst[n][k] = *(const LAS bf16x8*)(lds + PG8_SB(b, h) + boff + n * 2048 + k * 1024); } while (0)
; #define PG8_MMA(ai, bj, At, Bt) do { __builtin_amdgcn_s_setprio(1); _Pragma("unroll") for (int m = 0; m < 4; ++m) _Pragma("unroll") for (int n = 0; n < 2; ++n) _Pragma("unroll") for (int k = 0; k < 2; ++k) \
;         acc[ai][bj][m][n] = __builtin_amdgcn_mfma_f32_16x16x32_bf16(Bt[n][k], At[m][k], acc[ai][bj][m][n], 0, 0, 0); __builtin_amdgcn_s_setprio(0); } while (0)
; #define PG8_WAIT_V(n) asm volatile("s_waitcnt vmcnt(" #n ")" ::: "memory")
; #define PG8_WAIT_L(n) asm volatile("s_waitcnt lgkmcnt(" #n ")" ::: "memory")
; #define PG8_BAR __builtin_amdgcn_s_barrier()
; #define PG8_SCHED __builtin_amdgcn_sched_barrier(0)
; template <class Epi>
; __device__ __forceinline__ void gemm_phase(LAS unsigned char* lds, const int tid, const Gemm g, const StaticOrder& S, const Epi& E) {
;     ...
;         for (int t = 0; t < nt; t += 2) {
;             const bool last = (t == nt - 2);
;             const char* a1 = cA + (size_t)(t + 1) * kstep;
;             const char* a2 = last ? nA : cA + (size_t)(t + 2) * kstep; const char* b2 = last ? nB : cB + (size_t)(t + 2) * kstep;
;             const char* a3 = a2 + kstep; const char* b3 = b2 + kstep;
;             PG8_LDB(B0, 0, 0); PG8_LDB(B1, 0, 1); PG8_SCHED; PG8_LDA(At, 0, 0); PG8_STAGE(PG8_SA(1, 1), a1 + hstepA, voffA);
;             PG8_WAIT_V(8); PG8_WAIT_L(0); PG8_BAR; PG8_MMA(0, 0, At, B0); PG8_MMA(0, 1, At, B1); PG8_BAR; PG8_SCHED;
;             PG8_LDA(At, 0, 1); PG8_STAGE(PG8_SB(0, 0), b2, voffB); PG8_STAGE(PG8_SB(0, 1), b2 + hstepB, voffB); PG8_STAGE(PG8_SA(0, 0), a2, voffA);
;             PG8_WAIT_V(8); PG8_WAIT_L(0); PG8_BAR; PG8_MMA(1, 0, At, B0); PG8_MMA(1, 1, At, B1); PG8_BAR; PG8_SCHED;
.LBB0_2303:
	s_add_u32 s68, s66, 0x100
	s_addc_u32 s69, s67, 0
	s_add_i32 s76, 0, 0x10000
	s_cmp_eq_u32 s93, 40
	s_cselect_b32 s73, s1, s69
	s_cselect_b32 s72, s0, s68
	s_cselect_b32 s71, s31, s28
	s_cselect_b32 s70, s30, s11
	s_add_i32 vcc_lo, 0, 0x14000
	v_add_u32_e32 v70, s76, v212
	v_add_u32_e32 v162, vcc_lo, v212
	ds_read_b128 v[42:45], v70
	ds_read_b128 v[46:49], v70 offset:1024
	ds_read_b128 v[66:69], v70 offset:2048
	ds_read_b128 v[70:73], v70 offset:3072
	ds_read_b128 v[158:161], v162
	ds_read_b128 v[170:173], v162 offset:1024
	ds_read_b128 v[174:177], v162 offset:2048
	ds_read_b128 v[178:181], v162 offset:3072
	v_lshl_add_u64 v[162:163], s[66:67], 0, v[154:155]
	s_add_i32 m0, s5, 0xc000
	s_nop 0
	global_load_lds_dwordx4 v[162:163], off
	v_lshl_add_u64 v[162:163], s[66:67], 0, v[156:157]
	s_add_i32 m0, s5, 0xe000
	s_nop 0
	global_load_lds_dwordx4 v[162:163], off
	ds_read_b128 v[182:185], v214
	ds_read_b128 v[186:189], v214 offset:1024
	ds_read_b128 v[190:193], v214 offset:2048
	ds_read_b128 v[194:197], v214 offset:3072
	ds_read_b128 v[198:201], v214 offset:4096
	ds_read_b128 v[216:219], v214 offset:5120
	ds_read_b128 v[220:223], v214 offset:6144
	ds_read_b128 v[224:227], v214 offset:7168
	s_waitcnt vmcnt(8)
	s_waitcnt lgkmcnt(0)
	s_barrier
	s_setprio 1
	s_waitcnt lgkmcnt(0)
	v_mfma_f32_16x16x32_bf16 v[142:145], v[42:45], v[182:185], v[142:145]
	v_mfma_f32_16x16x32_bf16 v[138:141], v[66:69], v[182:185], v[138:141]
	v_mfma_f32_16x16x32_bf16 v[126:129], v[42:45], v[190:193], v[126:129]
	v_mfma_f32_16x16x32_bf16 v[122:125], v[66:69], v[190:193], v[122:125]
	v_mfma_f32_16x16x32_bf16 v[110:113], v[42:45], v[198:201], v[110:113]
	v_mfma_f32_16x16x32_bf16 v[106:109], v[66:69], v[198:201], v[106:109]
	v_mfma_f32_16x16x32_bf16 v[94:97], v[42:45], v[220:223], v[94:97]
	v_mfma_f32_16x16x32_bf16 v[90:93], v[66:69], v[220:223], v[90:93]
	v_mfma_f32_16x16x32_bf16 v[142:145], v[46:49], v[186:189], v[142:145]
	v_mfma_f32_16x16x32_bf16 v[138:141], v[70:73], v[186:189], v[138:141]
	v_mfma_f32_16x16x32_bf16 v[126:129], v[46:49], v[194:197], v[126:129]
	v_mfma_f32_16x16x32_bf16 v[122:125], v[70:73], v[194:197], v[122:125]
	v_mfma_f32_16x16x32_bf16 v[110:113], v[46:49], v[216:219], v[110:113]
	v_mfma_f32_16x16x32_bf16 v[106:109], v[70:73], v[216:219], v[106:109]
	v_mfma_f32_16x16x32_bf16 v[94:97], v[46:49], v[224:227], v[94:97]
	v_mfma_f32_16x16x32_bf16 v[90:93], v[70:73], v[224:227], v[90:93]
	s_setprio 0
	s_setprio 1
	v_mfma_f32_16x16x32_bf16 v[134:137], v[158:161], v[182:185], v[134:137]
	v_mfma_f32_16x16x32_bf16 v[130:133], v[174:177], v[182:185], v[130:133]
	v_mfma_f32_16x16x32_bf16 v[118:121], v[158:161], v[190:193], v[118:121]
	v_mfma_f32_16x16x32_bf16 v[114:117], v[174:177], v[190:193], v[114:117]
	v_mfma_f32_16x16x32_bf16 v[102:105], v[158:161], v[198:201], v[102:105]
	v_mfma_f32_16x16x32_bf16 v[98:101], v[174:177], v[198:201], v[98:101]
	v_mfma_f32_16x16x32_bf16 v[86:89], v[158:161], v[220:223], v[86:89]
	v_mfma_f32_16x16x32_bf16 v[82:85], v[174:177], v[220:223], v[82:85]
	v_mfma_f32_16x16x32_bf16 v[134:137], v[170:173], v[186:189], v[134:137]
	v_mfma_f32_16x16x32_bf16 v[130:133], v[178:181], v[186:189], v[130:133]
	v_mfma_f32_16x16x32_bf16 v[118:121], v[170:173], v[194:197], v[118:121]
	v_mfma_f32_16x16x32_bf16 v[114:117], v[178:181], v[194:197], v[114:117]
	v_mfma_f32_16x16x32_bf16 v[102:105], v[170:173], v[216:219], v[102:105]
	v_mfma_f32_16x16x32_bf16 v[98:101], v[178:181], v[216:219], v[98:101]
	v_mfma_f32_16x16x32_bf16 v[86:89], v[170:173], v[224:227], v[86:89]
	v_mfma_f32_16x16x32_bf16 v[82:85], v[178:181], v[224:227], v[82:85]
	s_setprio 0
	s_barrier
	s_add_i32 s66, s76, s4
	v_lshl_add_u64 v[162:163], s[70:71], 0, v[0:1]
	s_mov_b32 m0, s66
	s_nop 0
	global_load_lds_dwordx4 v[162:163], off
	s_add_i32 m0, s66, 0x2000
	s_add_u32 s66, s70, 0xb0000
	v_lshl_add_u64 v[164:165], s[70:71], 0, v[152:153]
	s_addc_u32 s67, s71, 0
	s_add_i32 s76, vcc_lo, s4
	global_load_lds_dwordx4 v[164:165], off
	v_lshl_add_u64 v[202:203], s[66:67], 0, v[0:1]
	s_mov_b32 m0, s76
	v_lshl_add_u64 v[206:207], s[72:73], 0, v[150:151]
	global_load_lds_dwordx4 v[202:203], off
	v_lshl_add_u64 v[202:203], s[66:67], 0, v[152:153]
	s_add_i32 m0, s76, 0x2000
	s_nop 0
	global_load_lds_dwordx4 v[202:203], off
	v_lshl_add_u64 v[202:203], s[72:73], 0, v[148:149]
	s_mov_b32 m0, s5
	s_nop 0
	global_load_lds_dwordx4 v[202:203], off
	s_mov_b32 m0, s6
	s_nop 0
	global_load_lds_dwordx4 v[206:207], off
	ds_read_b128 v[182:185], v214 offset:16384
	ds_read_b128 v[186:189], v214 offset:17408
	ds_read_b128 v[190:193], v214 offset:18432
	ds_read_b128 v[194:197], v214 offset:19456
	ds_read_b128 v[198:201], v214 offset:20480
	ds_read_b128 v[216:219], v214 offset:21504
	ds_read_b128 v[220:223], v214 offset:22528
	ds_read_b128 v[224:227], v214 offset:23552
	s_waitcnt vmcnt(8)
	s_waitcnt lgkmcnt(0)
	s_barrier
; #define PG8_STAGE(bufoff, gbase, voff) do { _Pragma("unroll") for (int _i = 0; _i < 2; ++_i) \
;         __builtin_amdgcn_global_load_lds((const unsigned*)((const char*)(gbase) + (voff)[_i]), (LAS unsigned*)(lds + (bufoff) + ldsw + _i * 8192), 16, 0, 0); } while (0)
; #define PG8_LDA(dst, b, h) do { _Pragma("unroll") for (int m = 0; m < 4; ++m) _Pragma("unroll") for (int k = 0; k < 2; ++k) dst[m][k] = *(const LAS bf16x8*)(lds + PG8_SA(b, h) + aoff + m * 2048 + k * 1024); } while (0)
; #define PG8_LDB(dst, b, h) do { _Pragma("unroll") for (int n = 0; n < 2; ++n) _Pragma("unroll") for (int k = 0; k < 2; ++k) dst[n][k] = *(const LAS bf16x8*)(lds + PG8_SB(b, h) + boff + n * 2048 + k * 1024); } while (0)
; #define PG8_MMA(ai, bj, At, Bt) do { __builtin_amdgcn_s_setprio(1); _Pragma("unroll") for (int m = 0; m < 4; ++m) _Pragma("unroll") for (int n = 0; n < 2; ++n) _Pragma("unroll") for (int k = 0; k < 2; ++k) \
;         acc[ai][bj][m][n] = __builtin_amdgcn_mfma_f32_16x16x32_bf16(Bt[n][k], At[m][k], acc[ai][bj][m][n], 0, 0, 0); __builtin_amdgcn_s_setprio(0); } while (0)
; #define PG8_WAIT_V(n) asm volatile("s_waitcnt vmcnt(" #n ")" ::: "memory")
; #define PG8_WAIT_L(n) asm volatile("s_waitcnt lgkmcnt(" #n ")" ::: "memory")
; #define PG8_BAR __builtin_amdgcn_s_barrier()
; #define PG8_SCHED __builtin_amdgcn_sched_barrier(0)
; template <class Epi>
; __device__ __forceinline__ void gemm_phase(LAS unsigned char* lds, const int tid, const Gemm g, const StaticOrder& S, const Epi& E) {
;     ...
;             PG8_WAIT_V(8); PG8_WAIT_L(0); PG8_BAR; PG8_MMA(1, 0, At, B0); PG8_MMA(1, 1, At, B1); PG8_BAR; PG8_SCHED;
;             PG8_LDB(B0, 1, 0); PG8_LDB(B1, 1, 1); PG8_SCHED; PG8_LDA(At, 1, 0); PG8_STAGE(PG8_SA(0, 1), a2 + hstepA, voffA);
;             PG8_WAIT_V(8); PG8_WAIT_L(0); PG8_BAR; PG8_MMA(0, 0, At, B0); PG8_MMA(0, 1, At, B1); PG8_BAR; PG8_SCHED;
;             PG8_LDA(At, 1, 1); PG8_STAGE(PG8_SB(1, 0), b3, voffB); PG8_STAGE(PG8_SB(1, 1), b3 + hstepB, voffB); PG8_STAGE(PG8_SA(1, 0), a3, voffA);
;             PG8_WAIT_V(8); PG8_WAIT_L(0); PG8_BAR; PG8_MMA(1, 0, At, B0); PG8_MMA(1, 1, At, B1); PG8_BAR; PG8_SCHED;
	s_setprio 1
	s_waitcnt lgkmcnt(0)
	v_mfma_f32_16x16x32_bf16 v[78:81], v[42:45], v[182:185], v[78:81]
	v_mfma_f32_16x16x32_bf16 v[74:77], v[66:69], v[182:185], v[74:77]
	v_mfma_f32_16x16x32_bf16 v[54:57], v[42:45], v[190:193], v[54:57]
	v_mfma_f32_16x16x32_bf16 v[50:53], v[66:69], v[190:193], v[50:53]
	v_mfma_f32_16x16x32_bf16 v[30:33], v[42:45], v[198:201], v[30:33]
	v_mfma_f32_16x16x32_bf16 v[26:29], v[66:69], v[198:201], v[26:29]
	v_mfma_f32_16x16x32_bf16 v[14:17], v[42:45], v[220:223], v[14:17]
	v_mfma_f32_16x16x32_bf16 v[10:13], v[66:69], v[220:223], v[10:13]
	v_mfma_f32_16x16x32_bf16 v[78:81], v[46:49], v[186:189], v[78:81]
	v_mfma_f32_16x16x32_bf16 v[74:77], v[70:73], v[186:189], v[74:77]
	v_mfma_f32_16x16x32_bf16 v[54:57], v[46:49], v[194:197], v[54:57]
	v_mfma_f32_16x16x32_bf16 v[50:53], v[70:73], v[194:197], v[50:53]
	v_mfma_f32_16x16x32_bf16 v[30:33], v[46:49], v[216:219], v[30:33]
	v_mfma_f32_16x16x32_bf16 v[26:29], v[70:73], v[216:219], v[26:29]
	v_mfma_f32_16x16x32_bf16 v[14:17], v[46:49], v[224:227], v[14:17]
	v_mfma_f32_16x16x32_bf16 v[10:13], v[70:73], v[224:227], v[10:13]
	s_setprio 0
	s_setprio 1
	v_mfma_f32_16x16x32_bf16 v[38:41], v[158:161], v[190:193], v[38:41]
	v_mfma_f32_16x16x32_bf16 v[34:37], v[174:177], v[190:193], v[34:37]
	v_mfma_f32_16x16x32_bf16 v[22:25], v[158:161], v[198:201], v[22:25]
	v_mfma_f32_16x16x32_bf16 v[18:21], v[174:177], v[198:201], v[18:21]
	v_mfma_f32_16x16x32_bf16 v[6:9], v[158:161], v[220:223], v[6:9]
	v_mfma_f32_16x16x32_bf16 v[2:5], v[174:177], v[220:223], v[2:5]
	v_mfma_f32_16x16x32_bf16 v[42:45], v[158:161], v[182:185], v[62:65]
	v_mfma_f32_16x16x32_bf16 v[46:49], v[174:177], v[182:185], v[58:61]
	v_mfma_f32_16x16x32_bf16 v[38:41], v[170:173], v[194:197], v[38:41]
	v_mfma_f32_16x16x32_bf16 v[34:37], v[178:181], v[194:197], v[34:37]
	v_mfma_f32_16x16x32_bf16 v[22:25], v[170:173], v[216:219], v[22:25]
	v_mfma_f32_16x16x32_bf16 v[18:21], v[178:181], v[216:219], v[18:21]
	v_mfma_f32_16x16x32_bf16 v[6:9], v[170:173], v[224:227], v[6:9]
	v_mfma_f32_16x16x32_bf16 v[2:5], v[178:181], v[224:227], v[2:5]
	v_mfma_f32_16x16x32_bf16 v[42:45], v[170:173], v[186:189], v[42:45]
	v_mfma_f32_16x16x32_bf16 v[46:49], v[178:181], v[186:189], v[46:49]
	s_setprio 0
	s_barrier
	s_add_i32 s76, 0, 0x18000
	s_add_i32 vcc_lo, 0, 0x1c000
	v_add_u32_e32 v70, s76, v212
	v_add_u32_e32 v178, vcc_lo, v212
	ds_read_b128 v[58:61], v70
	ds_read_b128 v[62:65], v70 offset:1024
	ds_read_b128 v[66:69], v70 offset:2048
	ds_read_b128 v[70:73], v70 offset:3072
	ds_read_b128 v[158:161], v178
	ds_read_b128 v[170:173], v178 offset:1024
	ds_read_b128 v[174:177], v178 offset:2048
	ds_read_b128 v[178:181], v178 offset:3072
	s_add_u32 s66, s72, 0x160000
	s_addc_u32 s67, s73, 0
	s_mov_b32 m0, s7
	v_lshl_add_u64 v[228:229], s[66:67], 0, v[148:149]
	global_load_lds_dwordx4 v[228:229], off
	v_lshl_add_u64 v[228:229], s[66:67], 0, v[150:151]
	s_mov_b32 m0, s74
	s_nop 0
	global_load_lds_dwordx4 v[228:229], off
	ds_read_b128 v[182:185], v214 offset:32768
	ds_read_b128 v[186:189], v214 offset:33792
	ds_read_b128 v[190:193], v214 offset:34816
	ds_read_b128 v[194:197], v214 offset:35840
	ds_read_b128 v[198:201], v214 offset:36864
	ds_read_b128 v[216:219], v214 offset:37888
	ds_read_b128 v[220:223], v214 offset:38912
	ds_read_b128 v[224:227], v214 offset:39936
	s_waitcnt vmcnt(8)
	s_waitcnt lgkmcnt(0)
	s_barrier
	s_setprio 1
	s_waitcnt lgkmcnt(0)
	v_mfma_f32_16x16x32_bf16 v[142:145], v[58:61], v[182:185], v[142:145]
	v_mfma_f32_16x16x32_bf16 v[138:141], v[66:69], v[182:185], v[138:141]
	v_mfma_f32_16x16x32_bf16 v[126:129], v[58:61], v[190:193], v[126:129]
	v_mfma_f32_16x16x32_bf16 v[122:125], v[66:69], v[190:193], v[122:125]
	v_mfma_f32_16x16x32_bf16 v[110:113], v[58:61], v[198:201], v[110:113]
	v_mfma_f32_16x16x32_bf16 v[106:109], v[66:69], v[198:201], v[106:109]
	v_mfma_f32_16x16x32_bf16 v[94:97], v[58:61], v[220:223], v[94:97]
	v_mfma_f32_16x16x32_bf16 v[90:93], v[66:69], v[220:223], v[90:93]
	v_mfma_f32_16x16x32_bf16 v[142:145], v[62:65], v[186:189], v[142:145]
	v_mfma_f32_16x16x32_bf16 v[138:141], v[70:73], v[186:189], v[138:141]
	v_mfma_f32_16x16x32_bf16 v[126:129], v[62:65], v[194:197], v[126:129]
	v_mfma_f32_16x16x32_bf16 v[122:125], v[70:73], v[194:197], v[122:125]
	v_mfma_f32_16x16x32_bf16 v[110:113], v[62:65], v[216:219], v[110:113]
	v_mfma_f32_16x16x32_bf16 v[106:109], v[70:73], v[216:219], v[106:109]
	v_mfma_f32_16x16x32_bf16 v[94:97], v[62:65], v[224:227], v[94:97]
	v_mfma_f32_16x16x32_bf16 v[90:93], v[70:73], v[224:227], v[90:93]
	s_setprio 0
	s_setprio 1
	v_mfma_f32_16x16x32_bf16 v[134:137], v[158:161], v[182:185], v[134:137]
	v_mfma_f32_16x16x32_bf16 v[130:133], v[174:177], v[182:185], v[130:133]
	v_mfma_f32_16x16x32_bf16 v[118:121], v[158:161], v[190:193], v[118:121]
	v_mfma_f32_16x16x32_bf16 v[114:117], v[174:177], v[190:193], v[114:117]
	v_mfma_f32_16x16x32_bf16 v[102:105], v[158:161], v[198:201], v[102:105]
	v_mfma_f32_16x16x32_bf16 v[98:101], v[174:177], v[198:201], v[98:101]
	v_mfma_f32_16x16x32_bf16 v[86:89], v[158:161], v[220:223], v[86:89]
	v_mfma_f32_16x16x32_bf16 v[82:85], v[174:177], v[220:223], v[82:85]
	v_mfma_f32_16x16x32_bf16 v[134:137], v[170:173], v[186:189], v[134:137]
	v_mfma_f32_16x16x32_bf16 v[130:133], v[178:181], v[186:189], v[130:133]
	v_mfma_f32_16x16x32_bf16 v[118:121], v[170:173], v[194:197], v[118:121]
	v_mfma_f32_16x16x32_bf16 v[114:117], v[178:181], v[194:197], v[114:117]
	v_mfma_f32_16x16x32_bf16 v[102:105], v[170:173], v[216:219], v[102:105]
	v_mfma_f32_16x16x32_bf16 v[98:101], v[178:181], v[216:219], v[98:101]
	v_mfma_f32_16x16x32_bf16 v[86:89], v[170:173], v[224:227], v[86:89]
	v_mfma_f32_16x16x32_bf16 v[82:85], v[178:181], v[224:227], v[82:85]
	s_setprio 0
	s_barrier
; #define PG8_STAGE(bufoff, gbase, voff) do { _Pragma("unroll") for (int _i = 0; _i < 2; ++_i) \
;         __builtin_amdgcn_global_load_lds((const unsigned*)((const char*)(gbase) + (voff)[_i]), (LAS unsigned*)(lds + (bufoff) + ldsw + _i * 8192), 16, 0, 0); } while (0)
; #define PG8_LDA(dst, b, h) do { _Pragma("unroll") for (int m = 0; m < 4; ++m) _Pragma("unroll") for (int k = 0; k < 2; ++k) dst[m][k] = *(const LAS bf16x8*)(lds + PG8_SA(b, h) + aoff + m * 2048 + k * 1024); } while (0)
; #define PG8_MMA(ai, bj, At, Bt) do { __builtin_amdgcn_s_setprio(1); _Pragma("unroll") for (int m = 0; m < 4; ++m) _Pragma("unroll") for (int n = 0; n < 2; ++n) _Pragma("unroll") for (int k = 0; k < 2; ++k) \
;         acc[ai][bj][m][n] = __builtin_amdgcn_mfma_f32_16x16x32_bf16(Bt[n][k], At[m][k], acc[ai][bj][m][n], 0, 0, 0); __builtin_amdgcn_s_setprio(0); } while (0)
; #define PG8_WAIT_V(n) asm volatile("s_waitcnt vmcnt(" #n ")" ::: "memory")
; #define PG8_WAIT_L(n) asm volatile("s_waitcnt lgkmcnt(" #n ")" ::: "memory")
; #define PG8_BAR __builtin_amdgcn_s_barrier()
; #define PG8_SCHED __builtin_amdgcn_sched_barrier(0)
; template <class Epi>
; __device__ __forceinline__ void gemm_phase(LAS unsigned char* lds, const int tid, const Gemm g, const StaticOrder& S, const Epi& E) {
;     ...
;             PG8_LDA(At, 1, 1); PG8_STAGE(PG8_SB(1, 0), b3, voffB); PG8_STAGE(PG8_SB(1, 1), b3 + hstepB, voffB); PG8_STAGE(PG8_SA(1, 0), a3, voffA);
;             PG8_WAIT_V(8); PG8_WAIT_L(0); PG8_BAR; PG8_MMA(1, 0, At, B0); PG8_MMA(1, 1, At, B1); PG8_BAR; PG8_SCHED;
;         }
;         if (wr == 0) PG8_BAR;
	s_add_i32 s66, s76, s4
	v_lshl_add_u64 v[162:163], v[162:163], 0, s[36:37]
	s_mov_b32 m0, s66
	s_nop 0
	global_load_lds_dwordx4 v[162:163], off
	s_add_i32 m0, s66, 0x2000
	s_add_u32 s66, s70, 0xb0080
	v_lshl_add_u64 v[162:163], v[164:165], 0, s[36:37]
	s_addc_u32 s67, s71, 0
	s_add_i32 s70, vcc_lo, s4
	global_load_lds_dwordx4 v[162:163], off
	v_lshl_add_u64 v[162:163], s[66:67], 0, v[0:1]
	s_mov_b32 m0, s70
	s_nop 0
	global_load_lds_dwordx4 v[162:163], off
	v_lshl_add_u64 v[162:163], s[66:67], 0, v[152:153]
	s_add_i32 m0, s70, 0x2000
	s_nop 0
	global_load_lds_dwordx4 v[162:163], off
	v_lshl_add_u64 v[162:163], v[202:203], 0, s[36:37]
	s_mov_b32 m0, s77
	s_nop 0
	global_load_lds_dwordx4 v[162:163], off
	v_lshl_add_u64 v[162:163], v[206:207], 0, s[36:37]
	s_mov_b32 m0, s79
	s_nop 0
	global_load_lds_dwordx4 v[162:163], off
	ds_read_b128 v[182:185], v214 offset:49152
	ds_read_b128 v[186:189], v214 offset:50176
	ds_read_b128 v[190:193], v214 offset:51200
	ds_read_b128 v[194:197], v214 offset:52224
	ds_read_b128 v[198:201], v214 offset:53248
	ds_read_b128 v[216:219], v214 offset:54272
	ds_read_b128 v[220:223], v214 offset:55296
	ds_read_b128 v[224:227], v214 offset:56320
	s_waitcnt vmcnt(8)
	s_waitcnt lgkmcnt(0)
	s_barrier
	s_setprio 1
	s_waitcnt lgkmcnt(0)
	v_mfma_f32_16x16x32_bf16 v[78:81], v[58:61], v[182:185], v[78:81]
	v_mfma_f32_16x16x32_bf16 v[74:77], v[66:69], v[182:185], v[74:77]
	v_mfma_f32_16x16x32_bf16 v[54:57], v[58:61], v[190:193], v[54:57]
	v_mfma_f32_16x16x32_bf16 v[50:53], v[66:69], v[190:193], v[50:53]
	v_mfma_f32_16x16x32_bf16 v[30:33], v[58:61], v[198:201], v[30:33]
	v_mfma_f32_16x16x32_bf16 v[26:29], v[66:69], v[198:201], v[26:29]
	v_mfma_f32_16x16x32_bf16 v[14:17], v[58:61], v[220:223], v[14:17]
	v_mfma_f32_16x16x32_bf16 v[10:13], v[66:69], v[220:223], v[10:13]
	v_mfma_f32_16x16x32_bf16 v[78:81], v[62:65], v[186:189], v[78:81]
	v_mfma_f32_16x16x32_bf16 v[74:77], v[70:73], v[186:189], v[74:77]
	v_mfma_f32_16x16x32_bf16 v[54:57], v[62:65], v[194:197], v[54:57]
	v_mfma_f32_16x16x32_bf16 v[50:53], v[70:73], v[194:197], v[50:53]
	v_mfma_f32_16x16x32_bf16 v[30:33], v[62:65], v[216:219], v[30:33]
	v_mfma_f32_16x16x32_bf16 v[26:29], v[70:73], v[216:219], v[26:29]
	v_mfma_f32_16x16x32_bf16 v[14:17], v[62:65], v[224:227], v[14:17]
	v_mfma_f32_16x16x32_bf16 v[10:13], v[70:73], v[224:227], v[10:13]
	s_setprio 0
	s_setprio 1
	v_mfma_f32_16x16x32_bf16 v[42:45], v[158:161], v[182:185], v[42:45]
	v_mfma_f32_16x16x32_bf16 v[62:65], v[170:173], v[186:189], v[42:45]
	v_mfma_f32_16x16x32_bf16 v[42:45], v[174:177], v[182:185], v[46:49]
	v_mfma_f32_16x16x32_bf16 v[38:41], v[158:161], v[190:193], v[38:41]
	v_mfma_f32_16x16x32_bf16 v[34:37], v[174:177], v[190:193], v[34:37]
	v_mfma_f32_16x16x32_bf16 v[22:25], v[158:161], v[198:201], v[22:25]
	v_mfma_f32_16x16x32_bf16 v[18:21], v[174:177], v[198:201], v[18:21]
	v_mfma_f32_16x16x32_bf16 v[6:9], v[158:161], v[220:223], v[6:9]
	v_mfma_f32_16x16x32_bf16 v[2:5], v[174:177], v[220:223], v[2:5]
	v_mfma_f32_16x16x32_bf16 v[58:61], v[178:181], v[186:189], v[42:45]
	v_mfma_f32_16x16x32_bf16 v[38:41], v[170:173], v[194:197], v[38:41]
	v_mfma_f32_16x16x32_bf16 v[34:37], v[178:181], v[194:197], v[34:37]
	v_mfma_f32_16x16x32_bf16 v[22:25], v[170:173], v[216:219], v[22:25]
	v_mfma_f32_16x16x32_bf16 v[18:21], v[178:181], v[216:219], v[18:21]
	v_mfma_f32_16x16x32_bf16 v[6:9], v[170:173], v[224:227], v[6:9]
	v_mfma_f32_16x16x32_bf16 v[2:5], v[178:181], v[224:227], v[2:5]
	s_setprio 0
	s_barrier
	s_add_i32 s93, s93, 2
	s_add_u32 s11, s11, 0x100
	s_addc_u32 s28, s28, 0
	s_cmp_gt_u32 s93, 41
	s_mov_b64 s[66:67], s[68:69]
	s_cbranch_scc0 .LBB0_2303
	s_and_b64 vcc, exec, s[26:27]
	s_cbranch_vccz .LBB0_2306
	s_barrier

; #define PG8_STAGE(bufoff, gbase, voff) do { _Pragma("unroll") for (int _i = 0; _i < 2; ++_i) \
;         __builtin_amdgcn_global_load_lds((const unsigned*)((const char*)(gbase) + (voff)[_i]), (LAS unsigned*)(lds + (bufoff) + ldsw + _i * 8192), 16, 0, 0); } while (0)
; #define PG8_LDA(dst, b, h) do { _Pragma("unroll") for (int m = 0; m < 4; ++m) _Pragma("unroll") for (int k = 0; k < 2; ++k) dst[m][k] = *(const LAS bf16x8*)(lds + PG8_SA(b, h) + aoff + m * 2048 + k * 1024); } while (0)
; #define PG8_LDB(dst, b, h) do { _Pragma("unroll") for (int n = 0; n < 2; ++n) _Pragma("unroll") for (int k = 0; k < 2; ++k) dst[n][k] = *(const LAS bf16x8*)(lds + PG8_SB(b, h) + boff + n * 2048 + k * 1024); } while (0)
; #define PG8_MMA(ai, bj, At, Bt) do { __builtin_amdgcn_s_setprio(1); _Pragma("unroll") for (int m = 0; m < 4; ++m) _Pragma("unroll") for (int n = 0; n < 2; ++n) _Pragma("unroll") for (int k = 0; k < 2; ++k) \
;         acc[ai][bj][m][n] = __builtin_amdgcn_mfma_f32_16x16x32_bf16(Bt[n][k], At[m][k], acc[ai][bj][m][n], 0, 0, 0); __builtin_amdgcn_s_setprio(0); } while (0)
; #define PG8_WAIT_V(n) asm volatile("s_waitcnt vmcnt(" #n ")" ::: "memory")
; #define PG8_WAIT_L(n) asm volatile("s_waitcnt lgkmcnt(" #n ")" ::: "memory")
; #define PG8_BAR __builtin_amdgcn_s_barrier()
; #define PG8_SCHED __builtin_amdgcn_sched_barrier(0)
; template <class Epi>
; __device__ __forceinline__ void gemm_phase(LAS unsigned char* lds, const int tid, const Gemm g, const StaticOrder& S, const Epi& E) {
;     ...
;         for (int t = 0; t < nt; t += 2) {
;             const bool last = (t == nt - 2);
;             const char* a1 = cA + (size_t)(t + 1) * kstep;
;             const char* a2 = last ? nA : cA + (size_t)(t + 2) * kstep; const char* b2 = last ? nB : cB + (size_t)(t + 2) * kstep;
;             const char* a3 = a2 + kstep; const char* b3 = b2 + kstep;
;             PG8_LDB(B0, 0, 0); PG8_LDB(B1, 0, 1); PG8_SCHED; PG8_LDA(At, 0, 0); PG8_STAGE(PG8_SA(1, 1), a1 + hstepA, voffA);
;             PG8_WAIT_V(8); PG8_WAIT_L(0); PG8_BAR; PG8_MMA(0, 0, At, B0); PG8_MMA(0, 1, At, B1); PG8_BAR; PG8_SCHED;
;             PG8_LDA(At, 0, 1); PG8_STAGE(PG8_SB(0, 0), b2, voffB); PG8_STAGE(PG8_SB(0, 1), b2 + hstepB, voffB); PG8_STAGE(PG8_SA(0, 0), a2, voffA);
;             PG8_WAIT_V(8); PG8_WAIT_L(0); PG8_BAR; PG8_MMA(1, 0, At, B0); PG8_MMA(1, 1, At, B1); PG8_BAR; PG8_SCHED;
.LBB0_2353:
	s_add_u32 s70, s68, 0x100
	s_addc_u32 s71, s69, 0
	s_add_i32 s76, 0, 0x10000
	s_cmp_eq_u32 vcc_hi, 40
	s_cselect_b32 s75, s1, s71
	s_cselect_b32 s74, s0, s70
	s_cselect_b32 s73, s31, vcc_lo
	s_cselect_b32 s72, s30, s11
	s_add_i32 s2, 0, 0x14000
	v_add_u32_e32 v154, s76, v199
	v_add_u32_e32 v162, s2, v199
	ds_read_b128 v[130:133], v154
	ds_read_b128 v[134:137], v154 offset:1024
	ds_read_b128 v[138:141], v154 offset:2048
	ds_read_b128 v[154:157], v154 offset:3072
	ds_read_b128 v[158:161], v162
	ds_read_b128 v[170:173], v162 offset:1024
	ds_read_b128 v[174:177], v162 offset:2048
	ds_read_b128 v[212:215], v162 offset:3072
	v_lshl_add_u64 v[162:163], s[68:69], 0, v[150:151]
	s_add_i32 m0, s83, 0xc000
	s_nop 0
	global_load_lds_dwordx4 v[162:163], off
	v_lshl_add_u64 v[162:163], s[68:69], 0, v[152:153]
	s_add_i32 m0, s83, 0xe000
	s_nop 0
	global_load_lds_dwordx4 v[162:163], off
	ds_read_b128 v[216:219], v201
	ds_read_b128 v[220:223], v201 offset:1024
	ds_read_b128 v[224:227], v201 offset:2048
	ds_read_b128 v[228:231], v201 offset:3072
	ds_read_b128 v[232:235], v201 offset:4096
	ds_read_b128 v[236:239], v201 offset:5120
	ds_read_b128 v[240:243], v201 offset:6144
	ds_read_b128 v[244:247], v201 offset:7168
	s_waitcnt vmcnt(8)
	s_waitcnt lgkmcnt(0)
	s_barrier
	s_setprio 1
	s_waitcnt lgkmcnt(0)
	v_mfma_f32_16x16x32_bf16 v[126:129], v[130:133], v[216:219], v[126:129]
	v_mfma_f32_16x16x32_bf16 v[122:125], v[138:141], v[216:219], v[122:125]
	v_mfma_f32_16x16x32_bf16 v[110:113], v[130:133], v[224:227], v[110:113]
	v_mfma_f32_16x16x32_bf16 v[106:109], v[138:141], v[224:227], v[106:109]
	v_mfma_f32_16x16x32_bf16 v[94:97], v[130:133], v[232:235], v[94:97]
	v_mfma_f32_16x16x32_bf16 v[90:93], v[138:141], v[232:235], v[90:93]
	v_mfma_f32_16x16x32_bf16 v[78:81], v[130:133], v[240:243], v[78:81]
	v_mfma_f32_16x16x32_bf16 v[74:77], v[138:141], v[240:243], v[74:77]
	v_mfma_f32_16x16x32_bf16 v[126:129], v[134:137], v[220:223], v[126:129]
	v_mfma_f32_16x16x32_bf16 v[122:125], v[154:157], v[220:223], v[122:125]
	v_mfma_f32_16x16x32_bf16 v[110:113], v[134:137], v[228:231], v[110:113]
	v_mfma_f32_16x16x32_bf16 v[106:109], v[154:157], v[228:231], v[106:109]
	v_mfma_f32_16x16x32_bf16 v[94:97], v[134:137], v[236:239], v[94:97]
	v_mfma_f32_16x16x32_bf16 v[90:93], v[154:157], v[236:239], v[90:93]
	v_mfma_f32_16x16x32_bf16 v[78:81], v[134:137], v[244:247], v[78:81]
	v_mfma_f32_16x16x32_bf16 v[74:77], v[154:157], v[244:247], v[74:77]
	s_setprio 0
	s_setprio 1
	v_mfma_f32_16x16x32_bf16 v[118:121], v[158:161], v[216:219], v[118:121]
	v_mfma_f32_16x16x32_bf16 v[114:117], v[174:177], v[216:219], v[114:117]
	v_mfma_f32_16x16x32_bf16 v[102:105], v[158:161], v[224:227], v[102:105]
	v_mfma_f32_16x16x32_bf16 v[98:101], v[174:177], v[224:227], v[98:101]
	v_mfma_f32_16x16x32_bf16 v[86:89], v[158:161], v[232:235], v[86:89]
	v_mfma_f32_16x16x32_bf16 v[82:85], v[174:177], v[232:235], v[82:85]
	v_mfma_f32_16x16x32_bf16 v[70:73], v[158:161], v[240:243], v[70:73]
	v_mfma_f32_16x16x32_bf16 v[66:69], v[174:177], v[240:243], v[66:69]
	v_mfma_f32_16x16x32_bf16 v[118:121], v[170:173], v[220:223], v[118:121]
	v_mfma_f32_16x16x32_bf16 v[114:117], v[212:215], v[220:223], v[114:117]
	v_mfma_f32_16x16x32_bf16 v[102:105], v[170:173], v[228:231], v[102:105]
	v_mfma_f32_16x16x32_bf16 v[98:101], v[212:215], v[228:231], v[98:101]
	v_mfma_f32_16x16x32_bf16 v[86:89], v[170:173], v[236:239], v[86:89]
	v_mfma_f32_16x16x32_bf16 v[82:85], v[212:215], v[236:239], v[82:85]
	v_mfma_f32_16x16x32_bf16 v[70:73], v[170:173], v[244:247], v[70:73]
	v_mfma_f32_16x16x32_bf16 v[66:69], v[212:215], v[244:247], v[66:69]
	s_setprio 0
	s_barrier
	s_add_i32 s3, s76, s82
	v_lshl_add_u64 v[162:163], s[72:73], 0, v[0:1]
	s_mov_b32 m0, s3
	s_nop 0
	global_load_lds_dwordx4 v[162:163], off
	s_add_i32 m0, s3, 0x2000
	s_add_u32 s68, s72, 0xb0000
	v_lshl_add_u64 v[164:165], s[72:73], 0, v[142:143]
	s_addc_u32 s69, s73, 0
	s_add_i32 s2, s2, s82
	global_load_lds_dwordx4 v[164:165], off
	v_lshl_add_u64 v[178:179], s[68:69], 0, v[0:1]
	s_mov_b32 m0, s2
	v_lshl_add_u64 v[206:207], s[74:75], 0, v[148:149]
	global_load_lds_dwordx4 v[178:179], off
	v_lshl_add_u64 v[178:179], s[68:69], 0, v[142:143]
	s_add_i32 m0, s2, 0x2000
	s_nop 0
	global_load_lds_dwordx4 v[178:179], off
	v_lshl_add_u64 v[178:179], s[74:75], 0, v[144:145]
	s_mov_b32 m0, s83
	s_nop 0
	global_load_lds_dwordx4 v[178:179], off
	s_mov_b32 m0, s88
	s_nop 0
	global_load_lds_dwordx4 v[206:207], off
	ds_read_b128 v[216:219], v201 offset:16384
	ds_read_b128 v[220:223], v201 offset:17408
	ds_read_b128 v[224:227], v201 offset:18432
	ds_read_b128 v[228:231], v201 offset:19456
	ds_read_b128 v[232:235], v201 offset:20480
	ds_read_b128 v[236:239], v201 offset:21504
	ds_read_b128 v[240:243], v201 offset:22528
	ds_read_b128 v[244:247], v201 offset:23552
	s_waitcnt vmcnt(8)
	s_waitcnt lgkmcnt(0)
	s_barrier
; #define PG8_STAGE(bufoff, gbase, voff) do { _Pragma("unroll") for (int _i = 0; _i < 2; ++_i) \
;         __builtin_amdgcn_global_load_lds((const unsigned*)((const char*)(gbase) + (voff)[_i]), (LAS unsigned*)(lds + (bufoff) + ldsw + _i * 8192), 16, 0, 0); } while (0)
; #define PG8_LDA(dst, b, h) do { _Pragma("unroll") for (int m = 0; m < 4; ++m) _Pragma("unroll") for (int k = 0; k < 2; ++k) dst[m][k] = *(const LAS bf16x8*)(lds + PG8_SA(b, h) + aoff + m * 2048 + k * 1024); } while (0)
; #define PG8_LDB(dst, b, h) do { _Pragma("unroll") for (int n = 0; n < 2; ++n) _Pragma("unroll") for (int k = 0; k < 2; ++k) dst[n][k] = *(const LAS bf16x8*)(lds + PG8_SB(b, h) + boff + n * 2048 + k * 1024); } while (0)
; #define PG8_MMA(ai, bj, At, Bt) do { __builtin_amdgcn_s_setprio(1); _Pragma("unroll") for (int m = 0; m < 4; ++m) _Pragma("unroll") for (int n = 0; n < 2; ++n) _Pragma("unroll") for (int k = 0; k < 2; ++k) \
;         acc[ai][bj][m][n] = __builtin_amdgcn_mfma_f32_16x16x32_bf16(Bt[n][k], At[m][k], acc[ai][bj][m][n], 0, 0, 0); __builtin_amdgcn_s_setprio(0); } while (0)
; #define PG8_WAIT_V(n) asm volatile("s_waitcnt vmcnt(" #n ")" ::: "memory")
; #define PG8_WAIT_L(n) asm volatile("s_waitcnt lgkmcnt(" #n ")" ::: "memory")
; #define PG8_BAR __builtin_amdgcn_s_barrier()
; #define PG8_SCHED __builtin_amdgcn_sched_barrier(0)
; template <class Epi>
; __device__ __forceinline__ void gemm_phase(LAS unsigned char* lds, const int tid, const Gemm g, const StaticOrder& S, const Epi& E) {
;     ...
;             PG8_WAIT_V(8); PG8_WAIT_L(0); PG8_BAR; PG8_MMA(1, 0, At, B0); PG8_MMA(1, 1, At, B1); PG8_BAR; PG8_SCHED;
;             PG8_LDB(B0, 1, 0); PG8_LDB(B1, 1, 1); PG8_SCHED; PG8_LDA(At, 1, 0); PG8_STAGE(PG8_SA(0, 1), a2 + hstepA, voffA);
;             PG8_WAIT_V(8); PG8_WAIT_L(0); PG8_BAR; PG8_MMA(0, 0, At, B0); PG8_MMA(0, 1, At, B1); PG8_BAR; PG8_SCHED;
;             PG8_LDA(At, 1, 1); PG8_STAGE(PG8_SB(1, 0), b3, voffB); PG8_STAGE(PG8_SB(1, 1), b3 + hstepB, voffB); PG8_STAGE(PG8_SA(1, 0), a3, voffA);
;             PG8_WAIT_V(8); PG8_WAIT_L(0); PG8_BAR; PG8_MMA(1, 0, At, B0); PG8_MMA(1, 1, At, B1); PG8_BAR; PG8_SCHED;
	s_setprio 1
	s_waitcnt lgkmcnt(0)
	v_mfma_f32_16x16x32_bf16 v[62:65], v[130:133], v[216:219], v[62:65]
	v_mfma_f32_16x16x32_bf16 v[58:61], v[138:141], v[216:219], v[58:61]
	v_mfma_f32_16x16x32_bf16 v[46:49], v[130:133], v[224:227], v[46:49]
	v_mfma_f32_16x16x32_bf16 v[42:45], v[138:141], v[224:227], v[42:45]
	v_mfma_f32_16x16x32_bf16 v[30:33], v[130:133], v[232:235], v[30:33]
	v_mfma_f32_16x16x32_bf16 v[26:29], v[138:141], v[232:235], v[26:29]
	v_mfma_f32_16x16x32_bf16 v[14:17], v[130:133], v[240:243], v[14:17]
	v_mfma_f32_16x16x32_bf16 v[10:13], v[138:141], v[240:243], v[10:13]
	v_mfma_f32_16x16x32_bf16 v[62:65], v[134:137], v[220:223], v[62:65]
	v_mfma_f32_16x16x32_bf16 v[58:61], v[154:157], v[220:223], v[58:61]
	v_mfma_f32_16x16x32_bf16 v[46:49], v[134:137], v[228:231], v[46:49]
	v_mfma_f32_16x16x32_bf16 v[42:45], v[154:157], v[228:231], v[42:45]
	v_mfma_f32_16x16x32_bf16 v[30:33], v[134:137], v[236:239], v[30:33]
	v_mfma_f32_16x16x32_bf16 v[26:29], v[154:157], v[236:239], v[26:29]
	v_mfma_f32_16x16x32_bf16 v[14:17], v[134:137], v[244:247], v[14:17]
	v_mfma_f32_16x16x32_bf16 v[10:13], v[154:157], v[244:247], v[10:13]
	s_setprio 0
	s_setprio 1
	v_mfma_f32_16x16x32_bf16 v[54:57], v[158:161], v[216:219], v[54:57]
	v_mfma_f32_16x16x32_bf16 v[50:53], v[174:177], v[216:219], v[50:53]
	v_mfma_f32_16x16x32_bf16 v[38:41], v[158:161], v[224:227], v[38:41]
	v_mfma_f32_16x16x32_bf16 v[34:37], v[174:177], v[224:227], v[34:37]
	v_mfma_f32_16x16x32_bf16 v[22:25], v[158:161], v[232:235], v[22:25]
	v_mfma_f32_16x16x32_bf16 v[18:21], v[174:177], v[232:235], v[18:21]
	v_mfma_f32_16x16x32_bf16 v[6:9], v[158:161], v[240:243], v[6:9]
	v_mfma_f32_16x16x32_bf16 v[2:5], v[174:177], v[240:243], v[2:5]
	v_mfma_f32_16x16x32_bf16 v[54:57], v[170:173], v[220:223], v[54:57]
	v_mfma_f32_16x16x32_bf16 v[50:53], v[212:215], v[220:223], v[50:53]
	v_mfma_f32_16x16x32_bf16 v[38:41], v[170:173], v[228:231], v[38:41]
	v_mfma_f32_16x16x32_bf16 v[34:37], v[212:215], v[228:231], v[34:37]
	v_mfma_f32_16x16x32_bf16 v[22:25], v[170:173], v[236:239], v[22:25]
	v_mfma_f32_16x16x32_bf16 v[18:21], v[212:215], v[236:239], v[18:21]
	v_mfma_f32_16x16x32_bf16 v[6:9], v[170:173], v[244:247], v[6:9]
	v_mfma_f32_16x16x32_bf16 v[2:5], v[212:215], v[244:247], v[2:5]
	s_setprio 0
	s_barrier
	s_add_i32 s2, 0, 0x18000
	s_add_i32 s3, 0, 0x1c000
	v_add_u32_e32 v154, s2, v199
	v_add_u32_e32 v192, s3, v199
	ds_read_b128 v[130:133], v154
	ds_read_b128 v[134:137], v154 offset:1024
	ds_read_b128 v[138:141], v154 offset:2048
	ds_read_b128 v[154:157], v154 offset:3072
	ds_read_b128 v[158:161], v192
	ds_read_b128 v[170:173], v192 offset:1024
	ds_read_b128 v[174:177], v192 offset:2048
	ds_read_b128 v[212:215], v192 offset:3072
	s_add_u32 s68, s74, 0x160000
	s_addc_u32 s69, s75, 0
	s_mov_b32 m0, s89
	v_lshl_add_u64 v[192:193], s[68:69], 0, v[144:145]
	global_load_lds_dwordx4 v[192:193], off
	v_lshl_add_u64 v[192:193], s[68:69], 0, v[148:149]
	s_mov_b32 m0, s92
	s_nop 0
	global_load_lds_dwordx4 v[192:193], off
	ds_read_b128 v[216:219], v201 offset:32768
	ds_read_b128 v[220:223], v201 offset:33792
	ds_read_b128 v[224:227], v201 offset:34816
	ds_read_b128 v[228:231], v201 offset:35840
	ds_read_b128 v[232:235], v201 offset:36864
	ds_read_b128 v[236:239], v201 offset:37888
	ds_read_b128 v[240:243], v201 offset:38912
	ds_read_b128 v[244:247], v201 offset:39936
	s_waitcnt vmcnt(8)
	s_waitcnt lgkmcnt(0)
	s_barrier
	s_setprio 1
	s_waitcnt lgkmcnt(0)
	v_mfma_f32_16x16x32_bf16 v[126:129], v[130:133], v[216:219], v[126:129]
	v_mfma_f32_16x16x32_bf16 v[122:125], v[138:141], v[216:219], v[122:125]
	v_mfma_f32_16x16x32_bf16 v[110:113], v[130:133], v[224:227], v[110:113]
	v_mfma_f32_16x16x32_bf16 v[106:109], v[138:141], v[224:227], v[106:109]
	v_mfma_f32_16x16x32_bf16 v[94:97], v[130:133], v[232:235], v[94:97]
	v_mfma_f32_16x16x32_bf16 v[90:93], v[138:141], v[232:235], v[90:93]
	v_mfma_f32_16x16x32_bf16 v[78:81], v[130:133], v[240:243], v[78:81]
	v_mfma_f32_16x16x32_bf16 v[74:77], v[138:141], v[240:243], v[74:77]
	v_mfma_f32_16x16x32_bf16 v[126:129], v[134:137], v[220:223], v[126:129]
	v_mfma_f32_16x16x32_bf16 v[122:125], v[154:157], v[220:223], v[122:125]
	v_mfma_f32_16x16x32_bf16 v[110:113], v[134:137], v[228:231], v[110:113]
	v_mfma_f32_16x16x32_bf16 v[106:109], v[154:157], v[228:231], v[106:109]
	v_mfma_f32_16x16x32_bf16 v[94:97], v[134:137], v[236:239], v[94:97]
	v_mfma_f32_16x16x32_bf16 v[90:93], v[154:157], v[236:239], v[90:93]
	v_mfma_f32_16x16x32_bf16 v[78:81], v[134:137], v[244:247], v[78:81]
	v_mfma_f32_16x16x32_bf16 v[74:77], v[154:157], v[244:247], v[74:77]
	s_setprio 0
	s_setprio 1
	v_mfma_f32_16x16x32_bf16 v[118:121], v[158:161], v[216:219], v[118:121]
	v_mfma_f32_16x16x32_bf16 v[114:117], v[174:177], v[216:219], v[114:117]
	v_mfma_f32_16x16x32_bf16 v[102:105], v[158:161], v[224:227], v[102:105]
	v_mfma_f32_16x16x32_bf16 v[98:101], v[174:177], v[224:227], v[98:101]
	v_mfma_f32_16x16x32_bf16 v[86:89], v[158:161], v[232:235], v[86:89]
	v_mfma_f32_16x16x32_bf16 v[82:85], v[174:177], v[232:235], v[82:85]
	v_mfma_f32_16x16x32_bf16 v[70:73], v[158:161], v[240:243], v[70:73]
	v_mfma_f32_16x16x32_bf16 v[66:69], v[174:177], v[240:243], v[66:69]
	v_mfma_f32_16x16x32_bf16 v[118:121], v[170:173], v[220:223], v[118:121]
	v_mfma_f32_16x16x32_bf16 v[114:117], v[212:215], v[220:223], v[114:117]
	v_mfma_f32_16x16x32_bf16 v[102:105], v[170:173], v[228:231], v[102:105]
	v_mfma_f32_16x16x32_bf16 v[98:101], v[212:215], v[228:231], v[98:101]
	v_mfma_f32_16x16x32_bf16 v[86:89], v[170:173], v[236:239], v[86:89]
	v_mfma_f32_16x16x32_bf16 v[82:85], v[212:215], v[236:239], v[82:85]
	v_mfma_f32_16x16x32_bf16 v[70:73], v[170:173], v[244:247], v[70:73]
	v_mfma_f32_16x16x32_bf16 v[66:69], v[212:215], v[244:247], v[66:69]
	s_setprio 0
	s_barrier
; #define PG8_STAGE(bufoff, gbase, voff) do { _Pragma("unroll") for (int _i = 0; _i < 2; ++_i) \
;         __builtin_amdgcn_global_load_lds((const unsigned*)((const char*)(gbase) + (voff)[_i]), (LAS unsigned*)(lds + (bufoff) + ldsw + _i * 8192), 16, 0, 0); } while (0)
; #define PG8_LDA(dst, b, h) do { _Pragma("unroll") for (int m = 0; m < 4; ++m) _Pragma("unroll") for (int k = 0; k < 2; ++k) dst[m][k] = *(const LAS bf16x8*)(lds + PG8_SA(b, h) + aoff + m * 2048 + k * 1024); } while (0)
; #define PG8_MMA(ai, bj, At, Bt) do { __builtin_amdgcn_s_setprio(1); _Pragma("unroll") for (int m = 0; m < 4; ++m) _Pragma("unroll") for (int n = 0; n < 2; ++n) _Pragma("unroll") for (int k = 0; k < 2; ++k) \
;         acc[ai][bj][m][n] = __builtin_amdgcn_mfma_f32_16x16x32_bf16(Bt[n][k], At[m][k], acc[ai][bj][m][n], 0, 0, 0); __builtin_amdgcn_s_setprio(0); } while (0)
; #define PG8_WAIT_V(n) asm volatile("s_waitcnt vmcnt(" #n ")" ::: "memory")
; #define PG8_WAIT_L(n) asm volatile("s_waitcnt lgkmcnt(" #n ")" ::: "memory")
; #define PG8_BAR __builtin_amdgcn_s_barrier()
; #define PG8_SCHED __builtin_amdgcn_sched_barrier(0)
; template <class Epi>
; __device__ __forceinline__ void gemm_phase(LAS unsigned char* lds, const int tid, const Gemm g, const StaticOrder& S, const Epi& E) {
;     ...
;             PG8_LDA(At, 1, 1); PG8_STAGE(PG8_SB(1, 0), b3, voffB); PG8_STAGE(PG8_SB(1, 1), b3 + hstepB, voffB); PG8_STAGE(PG8_SA(1, 0), a3, voffA);
;             PG8_WAIT_V(8); PG8_WAIT_L(0); PG8_BAR; PG8_MMA(1, 0, At, B0); PG8_MMA(1, 1, At, B1); PG8_BAR; PG8_SCHED;
;         }
;         if (wr == 0) PG8_BAR;
	s_add_i32 s2, s2, s82
	v_lshl_add_u64 v[162:163], v[162:163], 0, s[36:37]
	s_mov_b32 m0, s2
	s_nop 0
	global_load_lds_dwordx4 v[162:163], off
	s_add_i32 m0, s2, 0x2000
	s_add_u32 s68, s72, 0xb0080
	v_lshl_add_u64 v[162:163], v[164:165], 0, s[36:37]
	s_addc_u32 s69, s73, 0
	s_add_i32 s2, s3, s82
	global_load_lds_dwordx4 v[162:163], off
	v_lshl_add_u64 v[162:163], s[68:69], 0, v[0:1]
	s_mov_b32 m0, s2
	s_nop 0
	global_load_lds_dwordx4 v[162:163], off
	v_lshl_add_u64 v[162:163], s[68:69], 0, v[142:143]
	s_add_i32 m0, s2, 0x2000
	s_nop 0
	global_load_lds_dwordx4 v[162:163], off
	v_lshl_add_u64 v[162:163], v[178:179], 0, s[36:37]
	s_mov_b32 m0, s4
	s_nop 0
	global_load_lds_dwordx4 v[162:163], off
	v_lshl_add_u64 v[162:163], v[206:207], 0, s[36:37]
	s_mov_b32 m0, s5
	s_nop 0
	global_load_lds_dwordx4 v[162:163], off
	ds_read_b128 v[216:219], v201 offset:49152
	ds_read_b128 v[220:223], v201 offset:50176
	ds_read_b128 v[224:227], v201 offset:51200
	ds_read_b128 v[228:231], v201 offset:52224
	ds_read_b128 v[232:235], v201 offset:53248
	ds_read_b128 v[236:239], v201 offset:54272
	ds_read_b128 v[240:243], v201 offset:55296
	ds_read_b128 v[244:247], v201 offset:56320
	s_waitcnt vmcnt(8)
	s_waitcnt lgkmcnt(0)
	s_barrier
	s_setprio 1
	s_waitcnt lgkmcnt(0)
	v_mfma_f32_16x16x32_bf16 v[62:65], v[130:133], v[216:219], v[62:65]
	v_mfma_f32_16x16x32_bf16 v[58:61], v[138:141], v[216:219], v[58:61]
	v_mfma_f32_16x16x32_bf16 v[46:49], v[130:133], v[224:227], v[46:49]
	v_mfma_f32_16x16x32_bf16 v[42:45], v[138:141], v[224:227], v[42:45]
	v_mfma_f32_16x16x32_bf16 v[30:33], v[130:133], v[232:235], v[30:33]
	v_mfma_f32_16x16x32_bf16 v[26:29], v[138:141], v[232:235], v[26:29]
	v_mfma_f32_16x16x32_bf16 v[14:17], v[130:133], v[240:243], v[14:17]
	v_mfma_f32_16x16x32_bf16 v[10:13], v[138:141], v[240:243], v[10:13]
	v_mfma_f32_16x16x32_bf16 v[62:65], v[134:137], v[220:223], v[62:65]
	v_mfma_f32_16x16x32_bf16 v[58:61], v[154:157], v[220:223], v[58:61]
	v_mfma_f32_16x16x32_bf16 v[46:49], v[134:137], v[228:231], v[46:49]
	v_mfma_f32_16x16x32_bf16 v[42:45], v[154:157], v[228:231], v[42:45]
	v_mfma_f32_16x16x32_bf16 v[30:33], v[134:137], v[236:239], v[30:33]
	v_mfma_f32_16x16x32_bf16 v[26:29], v[154:157], v[236:239], v[26:29]
	v_mfma_f32_16x16x32_bf16 v[14:17], v[134:137], v[244:247], v[14:17]
	v_mfma_f32_16x16x32_bf16 v[10:13], v[154:157], v[244:247], v[10:13]
	s_setprio 0
	s_setprio 1
	v_mfma_f32_16x16x32_bf16 v[54:57], v[158:161], v[216:219], v[54:57]
	v_mfma_f32_16x16x32_bf16 v[50:53], v[174:177], v[216:219], v[50:53]
	v_mfma_f32_16x16x32_bf16 v[38:41], v[158:161], v[224:227], v[38:41]
	v_mfma_f32_16x16x32_bf16 v[34:37], v[174:177], v[224:227], v[34:37]
	v_mfma_f32_16x16x32_bf16 v[22:25], v[158:161], v[232:235], v[22:25]
	v_mfma_f32_16x16x32_bf16 v[18:21], v[174:177], v[232:235], v[18:21]
	v_mfma_f32_16x16x32_bf16 v[6:9], v[158:161], v[240:243], v[6:9]
	v_mfma_f32_16x16x32_bf16 v[2:5], v[174:177], v[240:243], v[2:5]
	v_mfma_f32_16x16x32_bf16 v[54:57], v[170:173], v[220:223], v[54:57]
	v_mfma_f32_16x16x32_bf16 v[50:53], v[212:215], v[220:223], v[50:53]
	v_mfma_f32_16x16x32_bf16 v[38:41], v[170:173], v[228:231], v[38:41]
	v_mfma_f32_16x16x32_bf16 v[34:37], v[212:215], v[228:231], v[34:37]
	v_mfma_f32_16x16x32_bf16 v[22:25], v[170:173], v[236:239], v[22:25]
	v_mfma_f32_16x16x32_bf16 v[18:21], v[212:215], v[236:239], v[18:21]
	v_mfma_f32_16x16x32_bf16 v[6:9], v[170:173], v[244:247], v[6:9]
	v_mfma_f32_16x16x32_bf16 v[2:5], v[212:215], v[244:247], v[2:5]
	s_setprio 0
	s_barrier
	s_add_i32 vcc_hi, vcc_hi, 2
	s_add_u32 s11, s11, 0x100
	s_addc_u32 vcc_lo, vcc_lo, 0
	s_cmp_gt_u32 vcc_hi, 41
	s_mov_b64 s[68:69], s[70:71]
	s_cbranch_scc0 .LBB0_2353
	s_and_b64 vcc, exec, s[26:27]
	s_cbranch_vccz .LBB0_2356
	s_barrier
